# v15 + mid-block setprio 0/1 pair removed in GEMM MFMA blocks
# baseline (speedup 1.0000x reference)
.LBB0_422:
	ds_read_b128 v[146:149], v154
	ds_read_b128 v[158:161], v154 offset:1024
	ds_read_b128 v[162:165], v154 offset:2048
	ds_read_b128 v[166:169], v154 offset:3072
	ds_read_b128 v[170:173], v155
	ds_read_b128 v[178:181], v155 offset:1024
	ds_read_b128 v[182:185], v155 offset:2048
	ds_read_b128 v[186:189], v155 offset:3072
	s_add_u32 s30, s28, 0xfc000
	s_addc_u32 s31, s29, 0
	s_cmp_eq_u32 s53, 60
	s_cselect_b32 s36, s21, s30
	s_cselect_b32 s37, s9, s31
	s_cselect_b32 s34, s50, s51
	s_cselect_b32 s35, s19, s52
	s_add_u32 s30, s36, 0x100000
	s_addc_u32 s31, s37, 0
	s_add_i32 m0, s1, 0xc000
	ds_read_b128 v[190:193], v156
	ds_read_b128 v[194:197], v156 offset:1024
	ds_read_b128 v[198:201], v156 offset:2048
	ds_read_b128 v[202:205], v156 offset:3072
	ds_read_b128 v[206:209], v156 offset:4096
	ds_read_b128 v[210:213], v156 offset:5120
	ds_read_b128 v[214:217], v156 offset:6144
	ds_read_b128 v[218:221], v156 offset:7168
	global_load_lds_dwordx4 v138, s[28:29]
	s_add_i32 m0, s1, 0xe000
	s_nop 0
	global_load_lds_dwordx4 v140, s[28:29]
	s_waitcnt vmcnt(8)
	s_waitcnt lgkmcnt(0)
	s_setprio 1
	s_barrier
	v_mfma_f32_16x16x32_bf16 v[126:129], v[146:149], v[190:193], v[126:129]
	v_mfma_f32_16x16x32_bf16 v[122:125], v[162:165], v[190:193], v[122:125]
	v_mfma_f32_16x16x32_bf16 v[110:113], v[146:149], v[198:201], v[110:113]
	v_mfma_f32_16x16x32_bf16 v[106:109], v[162:165], v[198:201], v[106:109]
	v_mfma_f32_16x16x32_bf16 v[94:97], v[146:149], v[206:209], v[94:97]
	v_mfma_f32_16x16x32_bf16 v[90:93], v[162:165], v[206:209], v[90:93]
	v_mfma_f32_16x16x32_bf16 v[78:81], v[146:149], v[214:217], v[78:81]
	v_mfma_f32_16x16x32_bf16 v[74:77], v[162:165], v[214:217], v[74:77]
	v_mfma_f32_16x16x32_bf16 v[126:129], v[158:161], v[194:197], v[126:129]
	v_mfma_f32_16x16x32_bf16 v[122:125], v[166:169], v[194:197], v[122:125]
	v_mfma_f32_16x16x32_bf16 v[110:113], v[158:161], v[202:205], v[110:113]
	v_mfma_f32_16x16x32_bf16 v[106:109], v[166:169], v[202:205], v[106:109]
	v_mfma_f32_16x16x32_bf16 v[94:97], v[158:161], v[210:213], v[94:97]
	v_mfma_f32_16x16x32_bf16 v[90:93], v[166:169], v[210:213], v[90:93]
	v_mfma_f32_16x16x32_bf16 v[78:81], v[158:161], v[218:221], v[78:81]
	v_mfma_f32_16x16x32_bf16 v[74:77], v[166:169], v[218:221], v[74:77]
	v_mfma_f32_16x16x32_bf16 v[118:121], v[170:173], v[190:193], v[118:121]
	v_mfma_f32_16x16x32_bf16 v[114:117], v[182:185], v[190:193], v[114:117]
	v_mfma_f32_16x16x32_bf16 v[102:105], v[170:173], v[198:201], v[102:105]
	v_mfma_f32_16x16x32_bf16 v[98:101], v[182:185], v[198:201], v[98:101]
	v_mfma_f32_16x16x32_bf16 v[86:89], v[170:173], v[206:209], v[86:89]
	v_mfma_f32_16x16x32_bf16 v[82:85], v[182:185], v[206:209], v[82:85]
	v_mfma_f32_16x16x32_bf16 v[70:73], v[170:173], v[214:217], v[70:73]
	v_mfma_f32_16x16x32_bf16 v[66:69], v[182:185], v[214:217], v[66:69]
	v_mfma_f32_16x16x32_bf16 v[118:121], v[178:181], v[194:197], v[118:121]
	v_mfma_f32_16x16x32_bf16 v[114:117], v[186:189], v[194:197], v[114:117]
	v_mfma_f32_16x16x32_bf16 v[102:105], v[178:181], v[202:205], v[102:105]
	v_mfma_f32_16x16x32_bf16 v[98:101], v[186:189], v[202:205], v[98:101]
	v_mfma_f32_16x16x32_bf16 v[86:89], v[178:181], v[210:213], v[86:89]
	v_mfma_f32_16x16x32_bf16 v[82:85], v[186:189], v[210:213], v[82:85]
	v_mfma_f32_16x16x32_bf16 v[70:73], v[178:181], v[218:221], v[70:73]
	v_mfma_f32_16x16x32_bf16 v[66:69], v[186:189], v[218:221], v[66:69]
	s_barrier
	s_setprio 0
	s_add_i32 s54, s48, s0
	s_mov_b32 m0, s54
	ds_read_b128 v[190:193], v156 offset:16384
	ds_read_b128 v[194:197], v156 offset:17408
	ds_read_b128 v[198:201], v156 offset:18432
	ds_read_b128 v[202:205], v156 offset:19456
	ds_read_b128 v[206:209], v156 offset:20480
	ds_read_b128 v[210:213], v156 offset:21504
	ds_read_b128 v[214:217], v156 offset:22528
	ds_read_b128 v[218:221], v156 offset:23552
	global_load_lds_dwordx4 v132, s[34:35]
	s_add_i32 m0, s54, 0x2000
	s_add_u32 s54, s34, 0x4000
	s_addc_u32 s55, s35, 0
	s_add_i32 s56, s49, s0
	global_load_lds_dwordx4 v136, s[34:35]
	s_mov_b32 m0, s56
	s_nop 0
	global_load_lds_dwordx4 v132, s[54:55]
	s_add_i32 m0, s56, 0x2000
	s_nop 0
	global_load_lds_dwordx4 v136, s[54:55]
	s_mov_b32 m0, s1
	s_nop 0
	global_load_lds_dwordx4 v130, s[36:37]
	s_mov_b32 m0, s27
	s_nop 0
	global_load_lds_dwordx4 v134, s[36:37]
	s_waitcnt vmcnt(8)
	s_waitcnt lgkmcnt(0)
	s_setprio 1
	s_barrier
	v_mfma_f32_16x16x32_bf16 v[62:65], v[146:149], v[190:193], v[62:65]
	v_mfma_f32_16x16x32_bf16 v[58:61], v[162:165], v[190:193], v[58:61]
	v_mfma_f32_16x16x32_bf16 v[46:49], v[146:149], v[198:201], v[46:49]
	v_mfma_f32_16x16x32_bf16 v[42:45], v[162:165], v[198:201], v[42:45]
	v_mfma_f32_16x16x32_bf16 v[30:33], v[146:149], v[206:209], v[30:33]
	v_mfma_f32_16x16x32_bf16 v[26:29], v[162:165], v[206:209], v[26:29]
	v_mfma_f32_16x16x32_bf16 v[14:17], v[146:149], v[214:217], v[14:17]
	v_mfma_f32_16x16x32_bf16 v[10:13], v[162:165], v[214:217], v[10:13]
	v_mfma_f32_16x16x32_bf16 v[62:65], v[158:161], v[194:197], v[62:65]
	v_mfma_f32_16x16x32_bf16 v[58:61], v[166:169], v[194:197], v[58:61]
	v_mfma_f32_16x16x32_bf16 v[46:49], v[158:161], v[202:205], v[46:49]
	v_mfma_f32_16x16x32_bf16 v[42:45], v[166:169], v[202:205], v[42:45]
	v_mfma_f32_16x16x32_bf16 v[30:33], v[158:161], v[210:213], v[30:33]
	v_mfma_f32_16x16x32_bf16 v[26:29], v[166:169], v[210:213], v[26:29]
	v_mfma_f32_16x16x32_bf16 v[14:17], v[158:161], v[218:221], v[14:17]
	v_mfma_f32_16x16x32_bf16 v[10:13], v[166:169], v[218:221], v[10:13]
	v_mfma_f32_16x16x32_bf16 v[54:57], v[170:173], v[190:193], v[54:57]
	v_mfma_f32_16x16x32_bf16 v[50:53], v[182:185], v[190:193], v[50:53]
	v_mfma_f32_16x16x32_bf16 v[38:41], v[170:173], v[198:201], v[38:41]
	v_mfma_f32_16x16x32_bf16 v[34:37], v[182:185], v[198:201], v[34:37]
	v_mfma_f32_16x16x32_bf16 v[22:25], v[170:173], v[206:209], v[22:25]
	v_mfma_f32_16x16x32_bf16 v[18:21], v[182:185], v[206:209], v[18:21]
	v_mfma_f32_16x16x32_bf16 v[6:9], v[170:173], v[214:217], v[6:9]
	v_mfma_f32_16x16x32_bf16 v[2:5], v[182:185], v[214:217], v[2:5]
	v_mfma_f32_16x16x32_bf16 v[54:57], v[178:181], v[194:197], v[54:57]
	v_mfma_f32_16x16x32_bf16 v[50:53], v[186:189], v[194:197], v[50:53]
	v_mfma_f32_16x16x32_bf16 v[38:41], v[178:181], v[202:205], v[38:41]
	v_mfma_f32_16x16x32_bf16 v[34:37], v[186:189], v[202:205], v[34:37]
	v_mfma_f32_16x16x32_bf16 v[22:25], v[178:181], v[210:213], v[22:25]
	v_mfma_f32_16x16x32_bf16 v[18:21], v[186:189], v[210:213], v[18:21]
	v_mfma_f32_16x16x32_bf16 v[6:9], v[178:181], v[218:221], v[6:9]
	v_mfma_f32_16x16x32_bf16 v[2:5], v[186:189], v[218:221], v[2:5]
	s_barrier
	s_setprio 0
	s_add_i32 s54, 0, 0x18000
	v_add_u32_e32 v150, s54, v153
	s_add_i32 s55, 0, 0x1c000
	ds_read_b128 v[146:149], v150
	ds_read_b128 v[158:161], v150 offset:1024
	ds_read_b128 v[162:165], v150 offset:2048
	ds_read_b128 v[166:169], v150 offset:3072
	v_add_u32_e32 v150, s55, v153
	ds_read_b128 v[170:173], v150
	ds_read_b128 v[178:181], v150 offset:1024
	ds_read_b128 v[182:185], v150 offset:2048
	ds_read_b128 v[186:189], v150 offset:3072
	s_add_u32 s36, s36, 0x4000
	s_addc_u32 s37, s37, 0
	s_mov_b32 m0, s33
	ds_read_b128 v[190:193], v156 offset:32768
	ds_read_b128 v[194:197], v156 offset:33792
	ds_read_b128 v[198:201], v156 offset:34816
	ds_read_b128 v[202:205], v156 offset:35840
	ds_read_b128 v[206:209], v156 offset:36864
	ds_read_b128 v[210:213], v156 offset:37888
	ds_read_b128 v[214:217], v156 offset:38912
	ds_read_b128 v[218:221], v156 offset:39936
	global_load_lds_dwordx4 v130, s[36:37]
	s_mov_b32 m0, s38
	s_nop 0
	global_load_lds_dwordx4 v134, s[36:37]
	s_waitcnt vmcnt(8)
	s_waitcnt lgkmcnt(0)
	s_setprio 1
	s_barrier
	v_mfma_f32_16x16x32_bf16 v[126:129], v[146:149], v[190:193], v[126:129]
	v_mfma_f32_16x16x32_bf16 v[122:125], v[162:165], v[190:193], v[122:125]
	v_mfma_f32_16x16x32_bf16 v[110:113], v[146:149], v[198:201], v[110:113]
	v_mfma_f32_16x16x32_bf16 v[106:109], v[162:165], v[198:201], v[106:109]
	v_mfma_f32_16x16x32_bf16 v[94:97], v[146:149], v[206:209], v[94:97]
	v_mfma_f32_16x16x32_bf16 v[90:93], v[162:165], v[206:209], v[90:93]
	v_mfma_f32_16x16x32_bf16 v[78:81], v[146:149], v[214:217], v[78:81]
	v_mfma_f32_16x16x32_bf16 v[74:77], v[162:165], v[214:217], v[74:77]
	v_mfma_f32_16x16x32_bf16 v[126:129], v[158:161], v[194:197], v[126:129]
	v_mfma_f32_16x16x32_bf16 v[122:125], v[166:169], v[194:197], v[122:125]
	v_mfma_f32_16x16x32_bf16 v[110:113], v[158:161], v[202:205], v[110:113]
	v_mfma_f32_16x16x32_bf16 v[106:109], v[166:169], v[202:205], v[106:109]
	v_mfma_f32_16x16x32_bf16 v[94:97], v[158:161], v[210:213], v[94:97]
	v_mfma_f32_16x16x32_bf16 v[90:93], v[166:169], v[210:213], v[90:93]
	v_mfma_f32_16x16x32_bf16 v[78:81], v[158:161], v[218:221], v[78:81]
	v_mfma_f32_16x16x32_bf16 v[74:77], v[166:169], v[218:221], v[74:77]
	v_mfma_f32_16x16x32_bf16 v[118:121], v[170:173], v[190:193], v[118:121]
	v_mfma_f32_16x16x32_bf16 v[114:117], v[182:185], v[190:193], v[114:117]
	v_mfma_f32_16x16x32_bf16 v[102:105], v[170:173], v[198:201], v[102:105]
	v_mfma_f32_16x16x32_bf16 v[98:101], v[182:185], v[198:201], v[98:101]
	v_mfma_f32_16x16x32_bf16 v[86:89], v[170:173], v[206:209], v[86:89]
	v_mfma_f32_16x16x32_bf16 v[82:85], v[182:185], v[206:209], v[82:85]
	v_mfma_f32_16x16x32_bf16 v[70:73], v[170:173], v[214:217], v[70:73]
	v_mfma_f32_16x16x32_bf16 v[66:69], v[182:185], v[214:217], v[66:69]
	v_mfma_f32_16x16x32_bf16 v[118:121], v[178:181], v[194:197], v[118:121]
	v_mfma_f32_16x16x32_bf16 v[114:117], v[186:189], v[194:197], v[114:117]
	v_mfma_f32_16x16x32_bf16 v[102:105], v[178:181], v[202:205], v[102:105]
	v_mfma_f32_16x16x32_bf16 v[98:101], v[186:189], v[202:205], v[98:101]
	v_mfma_f32_16x16x32_bf16 v[86:89], v[178:181], v[210:213], v[86:89]
	v_mfma_f32_16x16x32_bf16 v[82:85], v[186:189], v[210:213], v[82:85]
	v_mfma_f32_16x16x32_bf16 v[70:73], v[178:181], v[218:221], v[70:73]
	v_mfma_f32_16x16x32_bf16 v[66:69], v[186:189], v[218:221], v[66:69]
	s_barrier
	s_setprio 0
	s_add_u32 s36, s34, 0x380000
	s_addc_u32 s37, s35, 0
	s_add_i32 s54, s54, s0
	s_mov_b32 m0, s54
	ds_read_b128 v[190:193], v156 offset:49152
	ds_read_b128 v[194:197], v156 offset:50176
	ds_read_b128 v[198:201], v156 offset:51200
	ds_read_b128 v[202:205], v156 offset:52224
	ds_read_b128 v[206:209], v156 offset:53248
	ds_read_b128 v[210:213], v156 offset:54272
	ds_read_b128 v[214:217], v156 offset:55296
	ds_read_b128 v[218:221], v156 offset:56320
	global_load_lds_dwordx4 v132, s[36:37]
	s_add_i32 m0, s54, 0x2000
	s_add_u32 s34, s34, 0x384000
	s_addc_u32 s35, s35, 0
	global_load_lds_dwordx4 v136, s[36:37]
	s_add_i32 s36, s55, s0
	s_mov_b32 m0, s36
	s_nop 0
	global_load_lds_dwordx4 v132, s[34:35]
	s_add_i32 m0, s36, 0x2000
	s_nop 0
	global_load_lds_dwordx4 v136, s[34:35]
	s_mov_b32 m0, s44
	s_nop 0
	global_load_lds_dwordx4 v130, s[30:31]
	s_mov_b32 m0, s45
	s_nop 0
	global_load_lds_dwordx4 v134, s[30:31]
	s_waitcnt vmcnt(8)
	s_waitcnt lgkmcnt(0)
	s_setprio 1
	s_barrier
	v_mfma_f32_16x16x32_bf16 v[62:65], v[146:149], v[190:193], v[62:65]
	v_mfma_f32_16x16x32_bf16 v[58:61], v[162:165], v[190:193], v[58:61]
	v_mfma_f32_16x16x32_bf16 v[46:49], v[146:149], v[198:201], v[46:49]
	v_mfma_f32_16x16x32_bf16 v[42:45], v[162:165], v[198:201], v[42:45]
	v_mfma_f32_16x16x32_bf16 v[30:33], v[146:149], v[206:209], v[30:33]
	v_mfma_f32_16x16x32_bf16 v[26:29], v[162:165], v[206:209], v[26:29]
	v_mfma_f32_16x16x32_bf16 v[14:17], v[146:149], v[214:217], v[14:17]
	v_mfma_f32_16x16x32_bf16 v[10:13], v[162:165], v[214:217], v[10:13]
	v_mfma_f32_16x16x32_bf16 v[62:65], v[158:161], v[194:197], v[62:65]
	v_mfma_f32_16x16x32_bf16 v[58:61], v[166:169], v[194:197], v[58:61]
	v_mfma_f32_16x16x32_bf16 v[46:49], v[158:161], v[202:205], v[46:49]
	v_mfma_f32_16x16x32_bf16 v[42:45], v[166:169], v[202:205], v[42:45]
	v_mfma_f32_16x16x32_bf16 v[30:33], v[158:161], v[210:213], v[30:33]
	v_mfma_f32_16x16x32_bf16 v[26:29], v[166:169], v[210:213], v[26:29]
	v_mfma_f32_16x16x32_bf16 v[14:17], v[158:161], v[218:221], v[14:17]
	v_mfma_f32_16x16x32_bf16 v[10:13], v[166:169], v[218:221], v[10:13]
	v_mfma_f32_16x16x32_bf16 v[54:57], v[170:173], v[190:193], v[54:57]
	v_mfma_f32_16x16x32_bf16 v[50:53], v[182:185], v[190:193], v[50:53]
	v_mfma_f32_16x16x32_bf16 v[38:41], v[170:173], v[198:201], v[38:41]
	v_mfma_f32_16x16x32_bf16 v[34:37], v[182:185], v[198:201], v[34:37]
	v_mfma_f32_16x16x32_bf16 v[22:25], v[170:173], v[206:209], v[22:25]
	v_mfma_f32_16x16x32_bf16 v[18:21], v[182:185], v[206:209], v[18:21]
	v_mfma_f32_16x16x32_bf16 v[6:9], v[170:173], v[214:217], v[6:9]
	v_mfma_f32_16x16x32_bf16 v[2:5], v[182:185], v[214:217], v[2:5]
	v_mfma_f32_16x16x32_bf16 v[54:57], v[178:181], v[194:197], v[54:57]
	v_mfma_f32_16x16x32_bf16 v[50:53], v[186:189], v[194:197], v[50:53]
	v_mfma_f32_16x16x32_bf16 v[38:41], v[178:181], v[202:205], v[38:41]
	v_mfma_f32_16x16x32_bf16 v[34:37], v[186:189], v[202:205], v[34:37]
	v_mfma_f32_16x16x32_bf16 v[22:25], v[178:181], v[210:213], v[22:25]
	v_mfma_f32_16x16x32_bf16 v[18:21], v[186:189], v[210:213], v[18:21]
	v_mfma_f32_16x16x32_bf16 v[6:9], v[178:181], v[218:221], v[6:9]
	v_mfma_f32_16x16x32_bf16 v[2:5], v[186:189], v[218:221], v[2:5]
	s_barrier
	s_setprio 0
	s_add_i32 s53, s53, 2
	s_add_u32 s51, s51, 0x700000
	s_addc_u32 s52, s52, 0
	s_add_u32 s28, s28, 0x200000
	s_addc_u32 s29, s29, 0
	s_cmp_gt_u32 s53, 61
	s_cbranch_scc0 .LBB0_422
	s_and_b64 vcc, exec, s[16:17]
	s_cbranch_vccz .LBB0_425
	s_barrier

.LBB0_501:
	ds_read_b128 v[146:149], v152
	ds_read_b128 v[156:159], v152 offset:1024
	ds_read_b128 v[160:163], v152 offset:2048
	ds_read_b128 v[164:167], v152 offset:3072
	ds_read_b128 v[168:171], v153
	ds_read_b128 v[172:175], v153 offset:1024
	ds_read_b128 v[178:181], v153 offset:2048
	ds_read_b128 v[182:185], v153 offset:3072
	s_add_u32 s26, s10, 0xfc000
	s_addc_u32 s27, s11, 0
	s_cmpk_eq_i32 s47, 0xdc
	s_cselect_b32 s30, s21, s26
	s_cselect_b32 s31, s5, s27
	s_cselect_b32 s28, s44, s45
	s_cselect_b32 s29, s19, s46
	s_add_u32 s26, s30, 0x100000
	s_addc_u32 s27, s31, 0
	s_add_i32 m0, s1, 0xc000
	ds_read_b128 v[186:189], v154
	ds_read_b128 v[190:193], v154 offset:1024
	ds_read_b128 v[194:197], v154 offset:2048
	ds_read_b128 v[198:201], v154 offset:3072
	ds_read_b128 v[202:205], v154 offset:4096
	ds_read_b128 v[206:209], v154 offset:5120
	ds_read_b128 v[210:213], v154 offset:6144
	ds_read_b128 v[214:217], v154 offset:7168
	global_load_lds_dwordx4 v138, s[10:11]
	s_add_i32 m0, s1, 0xe000
	s_nop 0
	global_load_lds_dwordx4 v140, s[10:11]
	s_waitcnt vmcnt(8)
	s_waitcnt lgkmcnt(0)
	s_setprio 1
	s_barrier
	v_mfma_f32_16x16x32_bf16 v[126:129], v[146:149], v[186:189], v[126:129]
	v_mfma_f32_16x16x32_bf16 v[122:125], v[160:163], v[186:189], v[122:125]
	v_mfma_f32_16x16x32_bf16 v[110:113], v[146:149], v[194:197], v[110:113]
	v_mfma_f32_16x16x32_bf16 v[106:109], v[160:163], v[194:197], v[106:109]
	v_mfma_f32_16x16x32_bf16 v[94:97], v[146:149], v[202:205], v[94:97]
	v_mfma_f32_16x16x32_bf16 v[90:93], v[160:163], v[202:205], v[90:93]
	v_mfma_f32_16x16x32_bf16 v[78:81], v[146:149], v[210:213], v[78:81]
	v_mfma_f32_16x16x32_bf16 v[74:77], v[160:163], v[210:213], v[74:77]
	v_mfma_f32_16x16x32_bf16 v[126:129], v[156:159], v[190:193], v[126:129]
	v_mfma_f32_16x16x32_bf16 v[122:125], v[164:167], v[190:193], v[122:125]
	v_mfma_f32_16x16x32_bf16 v[110:113], v[156:159], v[198:201], v[110:113]
	v_mfma_f32_16x16x32_bf16 v[106:109], v[164:167], v[198:201], v[106:109]
	v_mfma_f32_16x16x32_bf16 v[94:97], v[156:159], v[206:209], v[94:97]
	v_mfma_f32_16x16x32_bf16 v[90:93], v[164:167], v[206:209], v[90:93]
	v_mfma_f32_16x16x32_bf16 v[78:81], v[156:159], v[214:217], v[78:81]
	v_mfma_f32_16x16x32_bf16 v[74:77], v[164:167], v[214:217], v[74:77]
	v_mfma_f32_16x16x32_bf16 v[118:121], v[168:171], v[186:189], v[118:121]
	v_mfma_f32_16x16x32_bf16 v[114:117], v[178:181], v[186:189], v[114:117]
	v_mfma_f32_16x16x32_bf16 v[102:105], v[168:171], v[194:197], v[102:105]
	v_mfma_f32_16x16x32_bf16 v[98:101], v[178:181], v[194:197], v[98:101]
	v_mfma_f32_16x16x32_bf16 v[86:89], v[168:171], v[202:205], v[86:89]
	v_mfma_f32_16x16x32_bf16 v[82:85], v[178:181], v[202:205], v[82:85]
	v_mfma_f32_16x16x32_bf16 v[70:73], v[168:171], v[210:213], v[70:73]
	v_mfma_f32_16x16x32_bf16 v[66:69], v[178:181], v[210:213], v[66:69]
	v_mfma_f32_16x16x32_bf16 v[118:121], v[172:175], v[190:193], v[118:121]
	v_mfma_f32_16x16x32_bf16 v[114:117], v[182:185], v[190:193], v[114:117]
	v_mfma_f32_16x16x32_bf16 v[102:105], v[172:175], v[198:201], v[102:105]
	v_mfma_f32_16x16x32_bf16 v[98:101], v[182:185], v[198:201], v[98:101]
	v_mfma_f32_16x16x32_bf16 v[86:89], v[172:175], v[206:209], v[86:89]
	v_mfma_f32_16x16x32_bf16 v[82:85], v[182:185], v[206:209], v[82:85]
	v_mfma_f32_16x16x32_bf16 v[70:73], v[172:175], v[214:217], v[70:73]
	v_mfma_f32_16x16x32_bf16 v[66:69], v[182:185], v[214:217], v[66:69]
	s_barrier
	s_setprio 0
	s_add_i32 s48, s41, s0
	s_mov_b32 m0, s48
	ds_read_b128 v[186:189], v154 offset:16384
	ds_read_b128 v[190:193], v154 offset:17408
	ds_read_b128 v[194:197], v154 offset:18432
	ds_read_b128 v[198:201], v154 offset:19456
	ds_read_b128 v[202:205], v154 offset:20480
	ds_read_b128 v[206:209], v154 offset:21504
	ds_read_b128 v[210:213], v154 offset:22528
	ds_read_b128 v[214:217], v154 offset:23552
	global_load_lds_dwordx4 v132, s[28:29]
	s_add_i32 m0, s48, 0x2000
	s_add_u32 s48, s28, 0x4000
	s_addc_u32 s49, s29, 0
	s_add_i32 s50, s42, s0
	global_load_lds_dwordx4 v136, s[28:29]
	s_mov_b32 m0, s50
	s_nop 0
	global_load_lds_dwordx4 v132, s[48:49]
	s_add_i32 m0, s50, 0x2000
	s_nop 0
	global_load_lds_dwordx4 v136, s[48:49]
	s_mov_b32 m0, s1
	s_nop 0
	global_load_lds_dwordx4 v130, s[30:31]
	s_mov_b32 m0, s33
	s_nop 0
	global_load_lds_dwordx4 v134, s[30:31]
	s_waitcnt vmcnt(8)
	s_waitcnt lgkmcnt(0)
	s_setprio 1
	s_barrier
	v_mfma_f32_16x16x32_bf16 v[62:65], v[146:149], v[186:189], v[62:65]
	v_mfma_f32_16x16x32_bf16 v[58:61], v[160:163], v[186:189], v[58:61]
	v_mfma_f32_16x16x32_bf16 v[46:49], v[146:149], v[194:197], v[46:49]
	v_mfma_f32_16x16x32_bf16 v[42:45], v[160:163], v[194:197], v[42:45]
	v_mfma_f32_16x16x32_bf16 v[30:33], v[146:149], v[202:205], v[30:33]
	v_mfma_f32_16x16x32_bf16 v[26:29], v[160:163], v[202:205], v[26:29]
	v_mfma_f32_16x16x32_bf16 v[14:17], v[146:149], v[210:213], v[14:17]
	v_mfma_f32_16x16x32_bf16 v[10:13], v[160:163], v[210:213], v[10:13]
	v_mfma_f32_16x16x32_bf16 v[62:65], v[156:159], v[190:193], v[62:65]
	v_mfma_f32_16x16x32_bf16 v[58:61], v[164:167], v[190:193], v[58:61]
	v_mfma_f32_16x16x32_bf16 v[46:49], v[156:159], v[198:201], v[46:49]
	v_mfma_f32_16x16x32_bf16 v[42:45], v[164:167], v[198:201], v[42:45]
	v_mfma_f32_16x16x32_bf16 v[30:33], v[156:159], v[206:209], v[30:33]
	v_mfma_f32_16x16x32_bf16 v[26:29], v[164:167], v[206:209], v[26:29]
	v_mfma_f32_16x16x32_bf16 v[14:17], v[156:159], v[214:217], v[14:17]
	v_mfma_f32_16x16x32_bf16 v[10:13], v[164:167], v[214:217], v[10:13]
	v_mfma_f32_16x16x32_bf16 v[54:57], v[168:171], v[186:189], v[54:57]
	v_mfma_f32_16x16x32_bf16 v[50:53], v[178:181], v[186:189], v[50:53]
	v_mfma_f32_16x16x32_bf16 v[38:41], v[168:171], v[194:197], v[38:41]
	v_mfma_f32_16x16x32_bf16 v[34:37], v[178:181], v[194:197], v[34:37]
	v_mfma_f32_16x16x32_bf16 v[22:25], v[168:171], v[202:205], v[22:25]
	v_mfma_f32_16x16x32_bf16 v[18:21], v[178:181], v[202:205], v[18:21]
	v_mfma_f32_16x16x32_bf16 v[6:9], v[168:171], v[210:213], v[6:9]
	v_mfma_f32_16x16x32_bf16 v[2:5], v[178:181], v[210:213], v[2:5]
	v_mfma_f32_16x16x32_bf16 v[54:57], v[172:175], v[190:193], v[54:57]
	v_mfma_f32_16x16x32_bf16 v[50:53], v[182:185], v[190:193], v[50:53]
	v_mfma_f32_16x16x32_bf16 v[38:41], v[172:175], v[198:201], v[38:41]
	v_mfma_f32_16x16x32_bf16 v[34:37], v[182:185], v[198:201], v[34:37]
	v_mfma_f32_16x16x32_bf16 v[22:25], v[172:175], v[206:209], v[22:25]
	v_mfma_f32_16x16x32_bf16 v[18:21], v[182:185], v[206:209], v[18:21]
	v_mfma_f32_16x16x32_bf16 v[6:9], v[172:175], v[214:217], v[6:9]
	v_mfma_f32_16x16x32_bf16 v[2:5], v[182:185], v[214:217], v[2:5]
	s_barrier
	s_setprio 0
	s_add_i32 s48, 0, 0x18000
	s_add_i32 s49, 0, 0x1c000
	v_add_u32_e32 v164, s48, v151
	v_add_u32_e32 v176, s49, v151
	ds_read_b128 v[146:149], v164
	ds_read_b128 v[156:159], v164 offset:1024
	ds_read_b128 v[160:163], v164 offset:2048
	ds_read_b128 v[164:167], v164 offset:3072
	ds_read_b128 v[168:171], v176
	ds_read_b128 v[172:175], v176 offset:1024
	ds_read_b128 v[178:181], v176 offset:2048
	ds_read_b128 v[182:185], v176 offset:3072
	s_add_u32 s30, s30, 0x4000
	s_addc_u32 s31, s31, 0
	s_mov_b32 m0, s34
	ds_read_b128 v[186:189], v154 offset:32768
	ds_read_b128 v[190:193], v154 offset:33792
	ds_read_b128 v[194:197], v154 offset:34816
	ds_read_b128 v[198:201], v154 offset:35840
	ds_read_b128 v[202:205], v154 offset:36864
	ds_read_b128 v[206:209], v154 offset:37888
	ds_read_b128 v[210:213], v154 offset:38912
	ds_read_b128 v[214:217], v154 offset:39936
	global_load_lds_dwordx4 v130, s[30:31]
	s_mov_b32 m0, s35
	s_nop 0
	global_load_lds_dwordx4 v134, s[30:31]
	s_waitcnt vmcnt(8)
	s_waitcnt lgkmcnt(0)
	s_setprio 1
	s_barrier
	v_mfma_f32_16x16x32_bf16 v[126:129], v[146:149], v[186:189], v[126:129]
	v_mfma_f32_16x16x32_bf16 v[122:125], v[160:163], v[186:189], v[122:125]
	v_mfma_f32_16x16x32_bf16 v[110:113], v[146:149], v[194:197], v[110:113]
	v_mfma_f32_16x16x32_bf16 v[106:109], v[160:163], v[194:197], v[106:109]
	v_mfma_f32_16x16x32_bf16 v[94:97], v[146:149], v[202:205], v[94:97]
	v_mfma_f32_16x16x32_bf16 v[90:93], v[160:163], v[202:205], v[90:93]
	v_mfma_f32_16x16x32_bf16 v[78:81], v[146:149], v[210:213], v[78:81]
	v_mfma_f32_16x16x32_bf16 v[74:77], v[160:163], v[210:213], v[74:77]
	v_mfma_f32_16x16x32_bf16 v[126:129], v[156:159], v[190:193], v[126:129]
	v_mfma_f32_16x16x32_bf16 v[122:125], v[164:167], v[190:193], v[122:125]
	v_mfma_f32_16x16x32_bf16 v[110:113], v[156:159], v[198:201], v[110:113]
	v_mfma_f32_16x16x32_bf16 v[106:109], v[164:167], v[198:201], v[106:109]
	v_mfma_f32_16x16x32_bf16 v[94:97], v[156:159], v[206:209], v[94:97]
	v_mfma_f32_16x16x32_bf16 v[90:93], v[164:167], v[206:209], v[90:93]
	v_mfma_f32_16x16x32_bf16 v[78:81], v[156:159], v[214:217], v[78:81]
	v_mfma_f32_16x16x32_bf16 v[74:77], v[164:167], v[214:217], v[74:77]
	v_mfma_f32_16x16x32_bf16 v[118:121], v[168:171], v[186:189], v[118:121]
	v_mfma_f32_16x16x32_bf16 v[114:117], v[178:181], v[186:189], v[114:117]
	v_mfma_f32_16x16x32_bf16 v[102:105], v[168:171], v[194:197], v[102:105]
	v_mfma_f32_16x16x32_bf16 v[98:101], v[178:181], v[194:197], v[98:101]
	v_mfma_f32_16x16x32_bf16 v[86:89], v[168:171], v[202:205], v[86:89]
	v_mfma_f32_16x16x32_bf16 v[82:85], v[178:181], v[202:205], v[82:85]
	v_mfma_f32_16x16x32_bf16 v[70:73], v[168:171], v[210:213], v[70:73]
	v_mfma_f32_16x16x32_bf16 v[66:69], v[178:181], v[210:213], v[66:69]
	v_mfma_f32_16x16x32_bf16 v[118:121], v[172:175], v[190:193], v[118:121]
	v_mfma_f32_16x16x32_bf16 v[114:117], v[182:185], v[190:193], v[114:117]
	v_mfma_f32_16x16x32_bf16 v[102:105], v[172:175], v[198:201], v[102:105]
	v_mfma_f32_16x16x32_bf16 v[98:101], v[182:185], v[198:201], v[98:101]
	v_mfma_f32_16x16x32_bf16 v[86:89], v[172:175], v[206:209], v[86:89]
	v_mfma_f32_16x16x32_bf16 v[82:85], v[182:185], v[206:209], v[82:85]
	v_mfma_f32_16x16x32_bf16 v[70:73], v[172:175], v[214:217], v[70:73]
	v_mfma_f32_16x16x32_bf16 v[66:69], v[182:185], v[214:217], v[66:69]
	s_barrier
	s_setprio 0
	s_add_u32 s30, s28, 0x80000
	s_addc_u32 s31, s29, 0
	s_add_i32 s48, s48, s0
	s_mov_b32 m0, s48
	ds_read_b128 v[186:189], v154 offset:49152
	ds_read_b128 v[190:193], v154 offset:50176
	ds_read_b128 v[194:197], v154 offset:51200
	ds_read_b128 v[198:201], v154 offset:52224
	ds_read_b128 v[202:205], v154 offset:53248
	ds_read_b128 v[206:209], v154 offset:54272
	ds_read_b128 v[210:213], v154 offset:55296
	ds_read_b128 v[214:217], v154 offset:56320
	global_load_lds_dwordx4 v132, s[30:31]
	s_add_i32 m0, s48, 0x2000
	s_add_u32 s28, s28, 0x84000
	s_addc_u32 s29, s29, 0
	global_load_lds_dwordx4 v136, s[30:31]
	s_add_i32 s30, s49, s0
	s_mov_b32 m0, s30
	s_nop 0
	global_load_lds_dwordx4 v132, s[28:29]
	s_add_i32 m0, s30, 0x2000
	s_nop 0
	global_load_lds_dwordx4 v136, s[28:29]
	s_mov_b32 m0, s39
	s_nop 0
	global_load_lds_dwordx4 v130, s[26:27]
	s_mov_b32 m0, s40
	s_nop 0
	global_load_lds_dwordx4 v134, s[26:27]
	s_waitcnt vmcnt(8)
	s_waitcnt lgkmcnt(0)
	s_setprio 1
	s_barrier
	v_mfma_f32_16x16x32_bf16 v[62:65], v[146:149], v[186:189], v[62:65]
	v_mfma_f32_16x16x32_bf16 v[58:61], v[160:163], v[186:189], v[58:61]
	v_mfma_f32_16x16x32_bf16 v[46:49], v[146:149], v[194:197], v[46:49]
	v_mfma_f32_16x16x32_bf16 v[42:45], v[160:163], v[194:197], v[42:45]
	v_mfma_f32_16x16x32_bf16 v[30:33], v[146:149], v[202:205], v[30:33]
	v_mfma_f32_16x16x32_bf16 v[26:29], v[160:163], v[202:205], v[26:29]
	v_mfma_f32_16x16x32_bf16 v[14:17], v[146:149], v[210:213], v[14:17]
	v_mfma_f32_16x16x32_bf16 v[10:13], v[160:163], v[210:213], v[10:13]
	v_mfma_f32_16x16x32_bf16 v[62:65], v[156:159], v[190:193], v[62:65]
	v_mfma_f32_16x16x32_bf16 v[58:61], v[164:167], v[190:193], v[58:61]
	v_mfma_f32_16x16x32_bf16 v[46:49], v[156:159], v[198:201], v[46:49]
	v_mfma_f32_16x16x32_bf16 v[42:45], v[164:167], v[198:201], v[42:45]
	v_mfma_f32_16x16x32_bf16 v[30:33], v[156:159], v[206:209], v[30:33]
	v_mfma_f32_16x16x32_bf16 v[26:29], v[164:167], v[206:209], v[26:29]
	v_mfma_f32_16x16x32_bf16 v[14:17], v[156:159], v[214:217], v[14:17]
	v_mfma_f32_16x16x32_bf16 v[10:13], v[164:167], v[214:217], v[10:13]
	v_mfma_f32_16x16x32_bf16 v[54:57], v[168:171], v[186:189], v[54:57]
	v_mfma_f32_16x16x32_bf16 v[50:53], v[178:181], v[186:189], v[50:53]
	v_mfma_f32_16x16x32_bf16 v[38:41], v[168:171], v[194:197], v[38:41]
	v_mfma_f32_16x16x32_bf16 v[34:37], v[178:181], v[194:197], v[34:37]
	v_mfma_f32_16x16x32_bf16 v[22:25], v[168:171], v[202:205], v[22:25]
	v_mfma_f32_16x16x32_bf16 v[18:21], v[178:181], v[202:205], v[18:21]
	v_mfma_f32_16x16x32_bf16 v[6:9], v[168:171], v[210:213], v[6:9]
	v_mfma_f32_16x16x32_bf16 v[2:5], v[178:181], v[210:213], v[2:5]
	v_mfma_f32_16x16x32_bf16 v[54:57], v[172:175], v[190:193], v[54:57]
	v_mfma_f32_16x16x32_bf16 v[50:53], v[182:185], v[190:193], v[50:53]
	v_mfma_f32_16x16x32_bf16 v[38:41], v[172:175], v[198:201], v[38:41]
	v_mfma_f32_16x16x32_bf16 v[34:37], v[182:185], v[198:201], v[34:37]
	v_mfma_f32_16x16x32_bf16 v[22:25], v[172:175], v[206:209], v[22:25]
	v_mfma_f32_16x16x32_bf16 v[18:21], v[182:185], v[206:209], v[18:21]
	v_mfma_f32_16x16x32_bf16 v[6:9], v[172:175], v[214:217], v[6:9]
	v_mfma_f32_16x16x32_bf16 v[2:5], v[182:185], v[214:217], v[2:5]
	s_barrier
	s_setprio 0
	s_add_i32 s47, s47, 2
	s_add_u32 s45, s45, 0x100000
	s_addc_u32 s46, s46, 0
	s_add_u32 s10, s10, 0x200000
	s_addc_u32 s11, s11, 0
	s_cmpk_gt_u32 s47, 0xdd
	s_cbranch_scc0 .LBB0_501
	s_and_b64 vcc, exec, s[16:17]
	s_cbranch_vccz .LBB0_504
	s_barrier

.LBB0_801:
	ds_read_b128 v[130:133], v179
	ds_read_b128 v[134:137], v179 offset:1024
	ds_read_b128 v[156:159], v179 offset:2048
	ds_read_b128 v[160:163], v179 offset:3072
	ds_read_b128 v[164:167], v180
	ds_read_b128 v[168:171], v180 offset:1024
	ds_read_b128 v[172:175], v180 offset:2048
	ds_read_b128 v[186:189], v180 offset:3072
	s_add_u32 s26, s12, 0xfc000
	s_addc_u32 s27, s13, 0
	s_cmp_eq_u32 s47, 60
	s_cselect_b32 s30, s5, s26
	s_cselect_b32 s31, s3, s27
	s_cselect_b32 s28, s21, s45
	s_cselect_b32 s29, s19, s46
	s_add_u32 s26, s30, 0x100000
	s_addc_u32 s27, s31, 0
	s_add_i32 m0, s1, 0xc000
	ds_read_b128 v[190:193], v181
	ds_read_b128 v[194:197], v181 offset:1024
	ds_read_b128 v[198:201], v181 offset:2048
	ds_read_b128 v[202:205], v181 offset:3072
	ds_read_b128 v[206:209], v181 offset:4096
	ds_read_b128 v[210:213], v181 offset:5120
	ds_read_b128 v[214:217], v181 offset:6144
	ds_read_b128 v[218:221], v181 offset:7168
	global_load_lds_dwordx4 v148, s[12:13]
	s_add_i32 m0, s1, 0xe000
	s_nop 0
	global_load_lds_dwordx4 v150, s[12:13]
	s_waitcnt vmcnt(8)
	s_waitcnt lgkmcnt(0)
	s_setprio 1
	s_barrier
	v_mfma_f32_16x16x32_bf16 v[126:129], v[130:133], v[190:193], v[126:129]
	v_mfma_f32_16x16x32_bf16 v[122:125], v[156:159], v[190:193], v[122:125]
	v_mfma_f32_16x16x32_bf16 v[110:113], v[130:133], v[198:201], v[110:113]
	v_mfma_f32_16x16x32_bf16 v[106:109], v[156:159], v[198:201], v[106:109]
	v_mfma_f32_16x16x32_bf16 v[94:97], v[130:133], v[206:209], v[94:97]
	v_mfma_f32_16x16x32_bf16 v[90:93], v[156:159], v[206:209], v[90:93]
	v_mfma_f32_16x16x32_bf16 v[78:81], v[130:133], v[214:217], v[78:81]
	v_mfma_f32_16x16x32_bf16 v[74:77], v[156:159], v[214:217], v[74:77]
	v_mfma_f32_16x16x32_bf16 v[126:129], v[134:137], v[194:197], v[126:129]
	v_mfma_f32_16x16x32_bf16 v[122:125], v[160:163], v[194:197], v[122:125]
	v_mfma_f32_16x16x32_bf16 v[110:113], v[134:137], v[202:205], v[110:113]
	v_mfma_f32_16x16x32_bf16 v[106:109], v[160:163], v[202:205], v[106:109]
	v_mfma_f32_16x16x32_bf16 v[94:97], v[134:137], v[210:213], v[94:97]
	v_mfma_f32_16x16x32_bf16 v[90:93], v[160:163], v[210:213], v[90:93]
	v_mfma_f32_16x16x32_bf16 v[78:81], v[134:137], v[218:221], v[78:81]
	v_mfma_f32_16x16x32_bf16 v[74:77], v[160:163], v[218:221], v[74:77]
	v_mfma_f32_16x16x32_bf16 v[118:121], v[164:167], v[190:193], v[118:121]
	v_mfma_f32_16x16x32_bf16 v[114:117], v[172:175], v[190:193], v[114:117]
	v_mfma_f32_16x16x32_bf16 v[102:105], v[164:167], v[198:201], v[102:105]
	v_mfma_f32_16x16x32_bf16 v[98:101], v[172:175], v[198:201], v[98:101]
	v_mfma_f32_16x16x32_bf16 v[86:89], v[164:167], v[206:209], v[86:89]
	v_mfma_f32_16x16x32_bf16 v[82:85], v[172:175], v[206:209], v[82:85]
	v_mfma_f32_16x16x32_bf16 v[70:73], v[164:167], v[214:217], v[70:73]
	v_mfma_f32_16x16x32_bf16 v[66:69], v[172:175], v[214:217], v[66:69]
	v_mfma_f32_16x16x32_bf16 v[118:121], v[168:171], v[194:197], v[118:121]
	v_mfma_f32_16x16x32_bf16 v[114:117], v[186:189], v[194:197], v[114:117]
	v_mfma_f32_16x16x32_bf16 v[102:105], v[168:171], v[202:205], v[102:105]
	v_mfma_f32_16x16x32_bf16 v[98:101], v[186:189], v[202:205], v[98:101]
	v_mfma_f32_16x16x32_bf16 v[86:89], v[168:171], v[210:213], v[86:89]
	v_mfma_f32_16x16x32_bf16 v[82:85], v[186:189], v[210:213], v[82:85]
	v_mfma_f32_16x16x32_bf16 v[70:73], v[168:171], v[218:221], v[70:73]
	v_mfma_f32_16x16x32_bf16 v[66:69], v[186:189], v[218:221], v[66:69]
	s_barrier
	s_setprio 0
	s_add_i32 s48, s42, s0
	s_mov_b32 m0, s48
	ds_read_b128 v[190:193], v181 offset:16384
	ds_read_b128 v[194:197], v181 offset:17408
	ds_read_b128 v[198:201], v181 offset:18432
	ds_read_b128 v[202:205], v181 offset:19456
	ds_read_b128 v[206:209], v181 offset:20480
	ds_read_b128 v[210:213], v181 offset:21504
	ds_read_b128 v[214:217], v181 offset:22528
	ds_read_b128 v[218:221], v181 offset:23552
	global_load_lds_dwordx4 v140, s[28:29]
	s_add_i32 m0, s48, 0x2000
	s_add_u32 s48, s28, 0x4000
	s_addc_u32 s49, s29, 0
	s_add_i32 s50, s43, s0
	global_load_lds_dwordx4 v144, s[28:29]
	s_mov_b32 m0, s50
	s_nop 0
	global_load_lds_dwordx4 v140, s[48:49]
	s_add_i32 m0, s50, 0x2000
	s_nop 0
	global_load_lds_dwordx4 v144, s[48:49]
	s_mov_b32 m0, s1
	s_nop 0
	global_load_lds_dwordx4 v138, s[30:31]
	s_mov_b32 m0, s33
	s_nop 0
	global_load_lds_dwordx4 v142, s[30:31]
	s_waitcnt vmcnt(8)
	s_waitcnt lgkmcnt(0)
	s_setprio 1
	s_barrier
	v_mfma_f32_16x16x32_bf16 v[62:65], v[130:133], v[190:193], v[62:65]
	v_mfma_f32_16x16x32_bf16 v[58:61], v[156:159], v[190:193], v[58:61]
	v_mfma_f32_16x16x32_bf16 v[46:49], v[130:133], v[198:201], v[46:49]
	v_mfma_f32_16x16x32_bf16 v[42:45], v[156:159], v[198:201], v[42:45]
	v_mfma_f32_16x16x32_bf16 v[30:33], v[130:133], v[206:209], v[30:33]
	v_mfma_f32_16x16x32_bf16 v[26:29], v[156:159], v[206:209], v[26:29]
	v_mfma_f32_16x16x32_bf16 v[14:17], v[130:133], v[214:217], v[14:17]
	v_mfma_f32_16x16x32_bf16 v[10:13], v[156:159], v[214:217], v[10:13]
	v_mfma_f32_16x16x32_bf16 v[62:65], v[134:137], v[194:197], v[62:65]
	v_mfma_f32_16x16x32_bf16 v[58:61], v[160:163], v[194:197], v[58:61]
	v_mfma_f32_16x16x32_bf16 v[46:49], v[134:137], v[202:205], v[46:49]
	v_mfma_f32_16x16x32_bf16 v[42:45], v[160:163], v[202:205], v[42:45]
	v_mfma_f32_16x16x32_bf16 v[30:33], v[134:137], v[210:213], v[30:33]
	v_mfma_f32_16x16x32_bf16 v[26:29], v[160:163], v[210:213], v[26:29]
	v_mfma_f32_16x16x32_bf16 v[14:17], v[134:137], v[218:221], v[14:17]
	v_mfma_f32_16x16x32_bf16 v[10:13], v[160:163], v[218:221], v[10:13]
	v_mfma_f32_16x16x32_bf16 v[54:57], v[164:167], v[190:193], v[54:57]
	v_mfma_f32_16x16x32_bf16 v[50:53], v[172:175], v[190:193], v[50:53]
	v_mfma_f32_16x16x32_bf16 v[38:41], v[164:167], v[198:201], v[38:41]
	v_mfma_f32_16x16x32_bf16 v[34:37], v[172:175], v[198:201], v[34:37]
	v_mfma_f32_16x16x32_bf16 v[22:25], v[164:167], v[206:209], v[22:25]
	v_mfma_f32_16x16x32_bf16 v[18:21], v[172:175], v[206:209], v[18:21]
	v_mfma_f32_16x16x32_bf16 v[6:9], v[164:167], v[214:217], v[6:9]
	v_mfma_f32_16x16x32_bf16 v[2:5], v[172:175], v[214:217], v[2:5]
	v_mfma_f32_16x16x32_bf16 v[54:57], v[168:171], v[194:197], v[54:57]
	v_mfma_f32_16x16x32_bf16 v[50:53], v[186:189], v[194:197], v[50:53]
	v_mfma_f32_16x16x32_bf16 v[38:41], v[168:171], v[202:205], v[38:41]
	v_mfma_f32_16x16x32_bf16 v[34:37], v[186:189], v[202:205], v[34:37]
	v_mfma_f32_16x16x32_bf16 v[22:25], v[168:171], v[210:213], v[22:25]
	v_mfma_f32_16x16x32_bf16 v[18:21], v[186:189], v[210:213], v[18:21]
	v_mfma_f32_16x16x32_bf16 v[6:9], v[168:171], v[218:221], v[6:9]
	v_mfma_f32_16x16x32_bf16 v[2:5], v[186:189], v[218:221], v[2:5]
	s_barrier
	s_setprio 0
	s_add_i32 s48, 0, 0x18000
	v_add_u32_e32 v146, s48, v178
	s_add_i32 s49, 0, 0x1c000
	ds_read_b128 v[130:133], v146
	ds_read_b128 v[134:137], v146 offset:1024
	ds_read_b128 v[156:159], v146 offset:2048
	ds_read_b128 v[160:163], v146 offset:3072
	v_add_u32_e32 v146, s49, v178
	ds_read_b128 v[164:167], v146
	ds_read_b128 v[168:171], v146 offset:1024
	ds_read_b128 v[172:175], v146 offset:2048
	ds_read_b128 v[186:189], v146 offset:3072
	s_add_u32 s30, s30, 0x4000
	s_addc_u32 s31, s31, 0
	s_mov_b32 m0, s34
	ds_read_b128 v[190:193], v181 offset:32768
	ds_read_b128 v[194:197], v181 offset:33792
	ds_read_b128 v[198:201], v181 offset:34816
	ds_read_b128 v[202:205], v181 offset:35840
	ds_read_b128 v[206:209], v181 offset:36864
	ds_read_b128 v[210:213], v181 offset:37888
	ds_read_b128 v[214:217], v181 offset:38912
	ds_read_b128 v[218:221], v181 offset:39936
	global_load_lds_dwordx4 v138, s[30:31]
	s_mov_b32 m0, s35
	s_nop 0
	global_load_lds_dwordx4 v142, s[30:31]
	s_waitcnt vmcnt(8)
	s_waitcnt lgkmcnt(0)
	s_setprio 1
	s_barrier
	v_mfma_f32_16x16x32_bf16 v[126:129], v[130:133], v[190:193], v[126:129]
	v_mfma_f32_16x16x32_bf16 v[122:125], v[156:159], v[190:193], v[122:125]
	v_mfma_f32_16x16x32_bf16 v[110:113], v[130:133], v[198:201], v[110:113]
	v_mfma_f32_16x16x32_bf16 v[106:109], v[156:159], v[198:201], v[106:109]
	v_mfma_f32_16x16x32_bf16 v[94:97], v[130:133], v[206:209], v[94:97]
	v_mfma_f32_16x16x32_bf16 v[90:93], v[156:159], v[206:209], v[90:93]
	v_mfma_f32_16x16x32_bf16 v[78:81], v[130:133], v[214:217], v[78:81]
	v_mfma_f32_16x16x32_bf16 v[74:77], v[156:159], v[214:217], v[74:77]
	v_mfma_f32_16x16x32_bf16 v[126:129], v[134:137], v[194:197], v[126:129]
	v_mfma_f32_16x16x32_bf16 v[122:125], v[160:163], v[194:197], v[122:125]
	v_mfma_f32_16x16x32_bf16 v[110:113], v[134:137], v[202:205], v[110:113]
	v_mfma_f32_16x16x32_bf16 v[106:109], v[160:163], v[202:205], v[106:109]
	v_mfma_f32_16x16x32_bf16 v[94:97], v[134:137], v[210:213], v[94:97]
	v_mfma_f32_16x16x32_bf16 v[90:93], v[160:163], v[210:213], v[90:93]
	v_mfma_f32_16x16x32_bf16 v[78:81], v[134:137], v[218:221], v[78:81]
	v_mfma_f32_16x16x32_bf16 v[74:77], v[160:163], v[218:221], v[74:77]
	v_mfma_f32_16x16x32_bf16 v[118:121], v[164:167], v[190:193], v[118:121]
	v_mfma_f32_16x16x32_bf16 v[114:117], v[172:175], v[190:193], v[114:117]
	v_mfma_f32_16x16x32_bf16 v[102:105], v[164:167], v[198:201], v[102:105]
	v_mfma_f32_16x16x32_bf16 v[98:101], v[172:175], v[198:201], v[98:101]
	v_mfma_f32_16x16x32_bf16 v[86:89], v[164:167], v[206:209], v[86:89]
	v_mfma_f32_16x16x32_bf16 v[82:85], v[172:175], v[206:209], v[82:85]
	v_mfma_f32_16x16x32_bf16 v[70:73], v[164:167], v[214:217], v[70:73]
	v_mfma_f32_16x16x32_bf16 v[66:69], v[172:175], v[214:217], v[66:69]
	v_mfma_f32_16x16x32_bf16 v[118:121], v[168:171], v[194:197], v[118:121]
	v_mfma_f32_16x16x32_bf16 v[114:117], v[186:189], v[194:197], v[114:117]
	v_mfma_f32_16x16x32_bf16 v[102:105], v[168:171], v[202:205], v[102:105]
	v_mfma_f32_16x16x32_bf16 v[98:101], v[186:189], v[202:205], v[98:101]
	v_mfma_f32_16x16x32_bf16 v[86:89], v[168:171], v[210:213], v[86:89]
	v_mfma_f32_16x16x32_bf16 v[82:85], v[186:189], v[210:213], v[82:85]
	v_mfma_f32_16x16x32_bf16 v[70:73], v[168:171], v[218:221], v[70:73]
	v_mfma_f32_16x16x32_bf16 v[66:69], v[186:189], v[218:221], v[66:69]
	s_barrier
	s_setprio 0
	s_add_u32 s30, s28, 0x180000
	s_addc_u32 s31, s29, 0
	s_add_i32 s48, s48, s0
	s_mov_b32 m0, s48
	ds_read_b128 v[190:193], v181 offset:49152
	ds_read_b128 v[194:197], v181 offset:50176
	ds_read_b128 v[198:201], v181 offset:51200
	ds_read_b128 v[202:205], v181 offset:52224
	ds_read_b128 v[206:209], v181 offset:53248
	ds_read_b128 v[210:213], v181 offset:54272
	ds_read_b128 v[214:217], v181 offset:55296
	ds_read_b128 v[218:221], v181 offset:56320
	global_load_lds_dwordx4 v140, s[30:31]
	s_add_i32 m0, s48, 0x2000
	s_add_u32 s28, s28, 0x184000
	s_addc_u32 s29, s29, 0
	global_load_lds_dwordx4 v144, s[30:31]
	s_add_i32 s30, s49, s0
	s_mov_b32 m0, s30
	s_nop 0
	global_load_lds_dwordx4 v140, s[28:29]
	s_add_i32 m0, s30, 0x2000
	s_nop 0
	global_load_lds_dwordx4 v144, s[28:29]
	s_mov_b32 m0, s38
	s_nop 0
	global_load_lds_dwordx4 v138, s[26:27]
	s_mov_b32 m0, s39
	s_nop 0
	global_load_lds_dwordx4 v142, s[26:27]
	s_waitcnt vmcnt(8)
	s_waitcnt lgkmcnt(0)
	s_setprio 1
	s_barrier
	v_mfma_f32_16x16x32_bf16 v[62:65], v[130:133], v[190:193], v[62:65]
	v_mfma_f32_16x16x32_bf16 v[58:61], v[156:159], v[190:193], v[58:61]
	v_mfma_f32_16x16x32_bf16 v[46:49], v[130:133], v[198:201], v[46:49]
	v_mfma_f32_16x16x32_bf16 v[42:45], v[156:159], v[198:201], v[42:45]
	v_mfma_f32_16x16x32_bf16 v[30:33], v[130:133], v[206:209], v[30:33]
	v_mfma_f32_16x16x32_bf16 v[26:29], v[156:159], v[206:209], v[26:29]
	v_mfma_f32_16x16x32_bf16 v[14:17], v[130:133], v[214:217], v[14:17]
	v_mfma_f32_16x16x32_bf16 v[10:13], v[156:159], v[214:217], v[10:13]
	v_mfma_f32_16x16x32_bf16 v[62:65], v[134:137], v[194:197], v[62:65]
	v_mfma_f32_16x16x32_bf16 v[58:61], v[160:163], v[194:197], v[58:61]
	v_mfma_f32_16x16x32_bf16 v[46:49], v[134:137], v[202:205], v[46:49]
	v_mfma_f32_16x16x32_bf16 v[42:45], v[160:163], v[202:205], v[42:45]
	v_mfma_f32_16x16x32_bf16 v[30:33], v[134:137], v[210:213], v[30:33]
	v_mfma_f32_16x16x32_bf16 v[26:29], v[160:163], v[210:213], v[26:29]
	v_mfma_f32_16x16x32_bf16 v[14:17], v[134:137], v[218:221], v[14:17]
	v_mfma_f32_16x16x32_bf16 v[10:13], v[160:163], v[218:221], v[10:13]
	v_mfma_f32_16x16x32_bf16 v[54:57], v[164:167], v[190:193], v[54:57]
	v_mfma_f32_16x16x32_bf16 v[50:53], v[172:175], v[190:193], v[50:53]
	v_mfma_f32_16x16x32_bf16 v[38:41], v[164:167], v[198:201], v[38:41]
	v_mfma_f32_16x16x32_bf16 v[34:37], v[172:175], v[198:201], v[34:37]
	v_mfma_f32_16x16x32_bf16 v[22:25], v[164:167], v[206:209], v[22:25]
	v_mfma_f32_16x16x32_bf16 v[18:21], v[172:175], v[206:209], v[18:21]
	v_mfma_f32_16x16x32_bf16 v[6:9], v[164:167], v[214:217], v[6:9]
	v_mfma_f32_16x16x32_bf16 v[2:5], v[172:175], v[214:217], v[2:5]
	v_mfma_f32_16x16x32_bf16 v[54:57], v[168:171], v[194:197], v[54:57]
	v_mfma_f32_16x16x32_bf16 v[50:53], v[186:189], v[194:197], v[50:53]
	v_mfma_f32_16x16x32_bf16 v[38:41], v[168:171], v[202:205], v[38:41]
	v_mfma_f32_16x16x32_bf16 v[34:37], v[186:189], v[202:205], v[34:37]
	v_mfma_f32_16x16x32_bf16 v[22:25], v[168:171], v[210:213], v[22:25]
	v_mfma_f32_16x16x32_bf16 v[18:21], v[186:189], v[210:213], v[18:21]
	v_mfma_f32_16x16x32_bf16 v[6:9], v[168:171], v[218:221], v[6:9]
	v_mfma_f32_16x16x32_bf16 v[2:5], v[186:189], v[218:221], v[2:5]
	s_barrier
	s_setprio 0
	s_add_i32 s47, s47, 2
	s_add_u32 s45, s45, 0x300000
	s_addc_u32 s46, s46, 0
	s_add_u32 s12, s12, 0x200000
	s_addc_u32 s13, s13, 0
	s_cmp_gt_u32 s47, 61
	s_cbranch_scc0 .LBB0_801
	s_and_b64 vcc, exec, s[8:9]
	s_cbranch_vccz .LBB0_804
	s_barrier

.LBB0_1217:
	ds_read_b128 v[146:149], v152
	ds_read_b128 v[156:159], v152 offset:1024
	ds_read_b128 v[160:163], v152 offset:2048
	ds_read_b128 v[164:167], v152 offset:3072
	ds_read_b128 v[168:171], v153
	ds_read_b128 v[172:175], v153 offset:1024
	ds_read_b128 v[176:179], v153 offset:2048
	ds_read_b128 v[180:183], v153 offset:3072
	s_add_u32 s22, s20, 0xfc000
	s_addc_u32 s23, s21, 0
	s_cmp_eq_u32 s43, 60
	s_cselect_b32 s26, s15, s22
	s_cselect_b32 s27, s5, s23
	s_cselect_b32 s24, s40, s41
	s_cselect_b32 s25, s13, s42
	s_add_u32 s22, s26, 0x100000
	s_addc_u32 s23, s27, 0
	s_add_i32 m0, s1, 0xc000
	ds_read_b128 v[184:187], v154
	ds_read_b128 v[188:191], v154 offset:1024
	ds_read_b128 v[192:195], v154 offset:2048
	ds_read_b128 v[196:199], v154 offset:3072
	ds_read_b128 v[206:209], v154 offset:4096
	ds_read_b128 v[212:215], v154 offset:5120
	ds_read_b128 v[220:223], v154 offset:6144
	ds_read_b128 v[224:227], v154 offset:7168
	global_load_lds_dwordx4 v138, s[20:21]
	s_add_i32 m0, s1, 0xe000
	s_nop 0
	global_load_lds_dwordx4 v140, s[20:21]
	s_waitcnt vmcnt(8)
	s_waitcnt lgkmcnt(0)
	s_setprio 1
	s_barrier
	v_mfma_f32_16x16x32_bf16 v[126:129], v[146:149], v[184:187], v[126:129]
	v_mfma_f32_16x16x32_bf16 v[122:125], v[160:163], v[184:187], v[122:125]
	v_mfma_f32_16x16x32_bf16 v[110:113], v[146:149], v[192:195], v[110:113]
	v_mfma_f32_16x16x32_bf16 v[106:109], v[160:163], v[192:195], v[106:109]
	v_mfma_f32_16x16x32_bf16 v[94:97], v[146:149], v[206:209], v[94:97]
	v_mfma_f32_16x16x32_bf16 v[90:93], v[160:163], v[206:209], v[90:93]
	v_mfma_f32_16x16x32_bf16 v[78:81], v[146:149], v[220:223], v[78:81]
	v_mfma_f32_16x16x32_bf16 v[74:77], v[160:163], v[220:223], v[74:77]
	v_mfma_f32_16x16x32_bf16 v[126:129], v[156:159], v[188:191], v[126:129]
	v_mfma_f32_16x16x32_bf16 v[122:125], v[164:167], v[188:191], v[122:125]
	v_mfma_f32_16x16x32_bf16 v[110:113], v[156:159], v[196:199], v[110:113]
	v_mfma_f32_16x16x32_bf16 v[106:109], v[164:167], v[196:199], v[106:109]
	v_mfma_f32_16x16x32_bf16 v[94:97], v[156:159], v[212:215], v[94:97]
	v_mfma_f32_16x16x32_bf16 v[90:93], v[164:167], v[212:215], v[90:93]
	v_mfma_f32_16x16x32_bf16 v[78:81], v[156:159], v[224:227], v[78:81]
	v_mfma_f32_16x16x32_bf16 v[74:77], v[164:167], v[224:227], v[74:77]
	v_mfma_f32_16x16x32_bf16 v[118:121], v[168:171], v[184:187], v[118:121]
	v_mfma_f32_16x16x32_bf16 v[114:117], v[176:179], v[184:187], v[114:117]
	v_mfma_f32_16x16x32_bf16 v[102:105], v[168:171], v[192:195], v[102:105]
	v_mfma_f32_16x16x32_bf16 v[98:101], v[176:179], v[192:195], v[98:101]
	v_mfma_f32_16x16x32_bf16 v[86:89], v[168:171], v[206:209], v[86:89]
	v_mfma_f32_16x16x32_bf16 v[82:85], v[176:179], v[206:209], v[82:85]
	v_mfma_f32_16x16x32_bf16 v[70:73], v[168:171], v[220:223], v[70:73]
	v_mfma_f32_16x16x32_bf16 v[66:69], v[176:179], v[220:223], v[66:69]
	v_mfma_f32_16x16x32_bf16 v[118:121], v[172:175], v[188:191], v[118:121]
	v_mfma_f32_16x16x32_bf16 v[114:117], v[180:183], v[188:191], v[114:117]
	v_mfma_f32_16x16x32_bf16 v[102:105], v[172:175], v[196:199], v[102:105]
	v_mfma_f32_16x16x32_bf16 v[98:101], v[180:183], v[196:199], v[98:101]
	v_mfma_f32_16x16x32_bf16 v[86:89], v[172:175], v[212:215], v[86:89]
	v_mfma_f32_16x16x32_bf16 v[82:85], v[180:183], v[212:215], v[82:85]
	v_mfma_f32_16x16x32_bf16 v[70:73], v[172:175], v[224:227], v[70:73]
	v_mfma_f32_16x16x32_bf16 v[66:69], v[180:183], v[224:227], v[66:69]
	s_barrier
	s_setprio 0
	s_add_i32 s44, s37, s0
	s_mov_b32 m0, s44
	ds_read_b128 v[184:187], v154 offset:16384
	ds_read_b128 v[188:191], v154 offset:17408
	ds_read_b128 v[192:195], v154 offset:18432
	ds_read_b128 v[196:199], v154 offset:19456
	ds_read_b128 v[206:209], v154 offset:20480
	ds_read_b128 v[212:215], v154 offset:21504
	ds_read_b128 v[220:223], v154 offset:22528
	ds_read_b128 v[224:227], v154 offset:23552
	global_load_lds_dwordx4 v132, s[24:25]
	s_add_i32 m0, s44, 0x2000
	s_add_u32 s44, s24, 0x4000
	s_addc_u32 s45, s25, 0
	s_add_i32 s46, s38, s0
	global_load_lds_dwordx4 v136, s[24:25]
	s_mov_b32 m0, s46
	s_nop 0
	global_load_lds_dwordx4 v132, s[44:45]
	s_add_i32 m0, s46, 0x2000
	s_nop 0
	global_load_lds_dwordx4 v136, s[44:45]
	s_mov_b32 m0, s1
	s_nop 0
	global_load_lds_dwordx4 v130, s[26:27]
	s_mov_b32 m0, s28
	s_nop 0
	global_load_lds_dwordx4 v134, s[26:27]
	s_waitcnt vmcnt(8)
	s_waitcnt lgkmcnt(0)
	s_setprio 1
	s_barrier
	v_mfma_f32_16x16x32_bf16 v[62:65], v[146:149], v[184:187], v[62:65]
	v_mfma_f32_16x16x32_bf16 v[58:61], v[160:163], v[184:187], v[58:61]
	v_mfma_f32_16x16x32_bf16 v[46:49], v[146:149], v[192:195], v[46:49]
	v_mfma_f32_16x16x32_bf16 v[42:45], v[160:163], v[192:195], v[42:45]
	v_mfma_f32_16x16x32_bf16 v[30:33], v[146:149], v[206:209], v[30:33]
	v_mfma_f32_16x16x32_bf16 v[26:29], v[160:163], v[206:209], v[26:29]
	v_mfma_f32_16x16x32_bf16 v[14:17], v[146:149], v[220:223], v[14:17]
	v_mfma_f32_16x16x32_bf16 v[10:13], v[160:163], v[220:223], v[10:13]
	v_mfma_f32_16x16x32_bf16 v[62:65], v[156:159], v[188:191], v[62:65]
	v_mfma_f32_16x16x32_bf16 v[58:61], v[164:167], v[188:191], v[58:61]
	v_mfma_f32_16x16x32_bf16 v[46:49], v[156:159], v[196:199], v[46:49]
	v_mfma_f32_16x16x32_bf16 v[42:45], v[164:167], v[196:199], v[42:45]
	v_mfma_f32_16x16x32_bf16 v[30:33], v[156:159], v[212:215], v[30:33]
	v_mfma_f32_16x16x32_bf16 v[26:29], v[164:167], v[212:215], v[26:29]
	v_mfma_f32_16x16x32_bf16 v[14:17], v[156:159], v[224:227], v[14:17]
	v_mfma_f32_16x16x32_bf16 v[10:13], v[164:167], v[224:227], v[10:13]
	v_mfma_f32_16x16x32_bf16 v[54:57], v[168:171], v[184:187], v[54:57]
	v_mfma_f32_16x16x32_bf16 v[50:53], v[176:179], v[184:187], v[50:53]
	v_mfma_f32_16x16x32_bf16 v[38:41], v[168:171], v[192:195], v[38:41]
	v_mfma_f32_16x16x32_bf16 v[34:37], v[176:179], v[192:195], v[34:37]
	v_mfma_f32_16x16x32_bf16 v[22:25], v[168:171], v[206:209], v[22:25]
	v_mfma_f32_16x16x32_bf16 v[18:21], v[176:179], v[206:209], v[18:21]
	v_mfma_f32_16x16x32_bf16 v[6:9], v[168:171], v[220:223], v[6:9]
	v_mfma_f32_16x16x32_bf16 v[2:5], v[176:179], v[220:223], v[2:5]
	v_mfma_f32_16x16x32_bf16 v[54:57], v[172:175], v[188:191], v[54:57]
	v_mfma_f32_16x16x32_bf16 v[50:53], v[180:183], v[188:191], v[50:53]
	v_mfma_f32_16x16x32_bf16 v[38:41], v[172:175], v[196:199], v[38:41]
	v_mfma_f32_16x16x32_bf16 v[34:37], v[180:183], v[196:199], v[34:37]
	v_mfma_f32_16x16x32_bf16 v[22:25], v[172:175], v[212:215], v[22:25]
	v_mfma_f32_16x16x32_bf16 v[18:21], v[180:183], v[212:215], v[18:21]
	v_mfma_f32_16x16x32_bf16 v[6:9], v[172:175], v[224:227], v[6:9]
	v_mfma_f32_16x16x32_bf16 v[2:5], v[180:183], v[224:227], v[2:5]
	s_barrier
	s_setprio 0
	s_add_i32 s44, 0, 0x18000
	v_add_u32_e32 v155, s44, v151
	s_add_i32 s45, 0, 0x1c000
	ds_read_b128 v[146:149], v155
	ds_read_b128 v[156:159], v155 offset:1024
	ds_read_b128 v[160:163], v155 offset:2048
	ds_read_b128 v[164:167], v155 offset:3072
	v_add_u32_e32 v155, s45, v151
	ds_read_b128 v[168:171], v155
	ds_read_b128 v[172:175], v155 offset:1024
	ds_read_b128 v[176:179], v155 offset:2048
	ds_read_b128 v[180:183], v155 offset:3072
	s_add_u32 s26, s26, 0x4000
	s_addc_u32 s27, s27, 0
	s_mov_b32 m0, s29
	ds_read_b128 v[184:187], v154 offset:32768
	ds_read_b128 v[188:191], v154 offset:33792
	ds_read_b128 v[192:195], v154 offset:34816
	ds_read_b128 v[196:199], v154 offset:35840
	ds_read_b128 v[206:209], v154 offset:36864
	ds_read_b128 v[212:215], v154 offset:37888
	ds_read_b128 v[220:223], v154 offset:38912
	ds_read_b128 v[224:227], v154 offset:39936
	global_load_lds_dwordx4 v130, s[26:27]
	s_mov_b32 m0, s30
	s_nop 0
	global_load_lds_dwordx4 v134, s[26:27]
	s_waitcnt vmcnt(8)
	s_waitcnt lgkmcnt(0)
	s_setprio 1
	s_barrier
	v_mfma_f32_16x16x32_bf16 v[126:129], v[146:149], v[184:187], v[126:129]
	v_mfma_f32_16x16x32_bf16 v[122:125], v[160:163], v[184:187], v[122:125]
	v_mfma_f32_16x16x32_bf16 v[110:113], v[146:149], v[192:195], v[110:113]
	v_mfma_f32_16x16x32_bf16 v[106:109], v[160:163], v[192:195], v[106:109]
	v_mfma_f32_16x16x32_bf16 v[94:97], v[146:149], v[206:209], v[94:97]
	v_mfma_f32_16x16x32_bf16 v[90:93], v[160:163], v[206:209], v[90:93]
	v_mfma_f32_16x16x32_bf16 v[78:81], v[146:149], v[220:223], v[78:81]
	v_mfma_f32_16x16x32_bf16 v[74:77], v[160:163], v[220:223], v[74:77]
	v_mfma_f32_16x16x32_bf16 v[126:129], v[156:159], v[188:191], v[126:129]
	v_mfma_f32_16x16x32_bf16 v[122:125], v[164:167], v[188:191], v[122:125]
	v_mfma_f32_16x16x32_bf16 v[110:113], v[156:159], v[196:199], v[110:113]
	v_mfma_f32_16x16x32_bf16 v[106:109], v[164:167], v[196:199], v[106:109]
	v_mfma_f32_16x16x32_bf16 v[94:97], v[156:159], v[212:215], v[94:97]
	v_mfma_f32_16x16x32_bf16 v[90:93], v[164:167], v[212:215], v[90:93]
	v_mfma_f32_16x16x32_bf16 v[78:81], v[156:159], v[224:227], v[78:81]
	v_mfma_f32_16x16x32_bf16 v[74:77], v[164:167], v[224:227], v[74:77]
	v_mfma_f32_16x16x32_bf16 v[118:121], v[168:171], v[184:187], v[118:121]
	v_mfma_f32_16x16x32_bf16 v[114:117], v[176:179], v[184:187], v[114:117]
	v_mfma_f32_16x16x32_bf16 v[102:105], v[168:171], v[192:195], v[102:105]
	v_mfma_f32_16x16x32_bf16 v[98:101], v[176:179], v[192:195], v[98:101]
	v_mfma_f32_16x16x32_bf16 v[86:89], v[168:171], v[206:209], v[86:89]
	v_mfma_f32_16x16x32_bf16 v[82:85], v[176:179], v[206:209], v[82:85]
	v_mfma_f32_16x16x32_bf16 v[70:73], v[168:171], v[220:223], v[70:73]
	v_mfma_f32_16x16x32_bf16 v[66:69], v[176:179], v[220:223], v[66:69]
	v_mfma_f32_16x16x32_bf16 v[118:121], v[172:175], v[188:191], v[118:121]
	v_mfma_f32_16x16x32_bf16 v[114:117], v[180:183], v[188:191], v[114:117]
	v_mfma_f32_16x16x32_bf16 v[102:105], v[172:175], v[196:199], v[102:105]
	v_mfma_f32_16x16x32_bf16 v[98:101], v[180:183], v[196:199], v[98:101]
	v_mfma_f32_16x16x32_bf16 v[86:89], v[172:175], v[212:215], v[86:89]
	v_mfma_f32_16x16x32_bf16 v[82:85], v[180:183], v[212:215], v[82:85]
	v_mfma_f32_16x16x32_bf16 v[70:73], v[172:175], v[224:227], v[70:73]
	v_mfma_f32_16x16x32_bf16 v[66:69], v[180:183], v[224:227], v[66:69]
	s_barrier
	s_setprio 0
	s_add_u32 s26, s24, 0x80000
	s_addc_u32 s27, s25, 0
	s_add_i32 s44, s44, s0
	s_mov_b32 m0, s44
	ds_read_b128 v[184:187], v154 offset:49152
	ds_read_b128 v[188:191], v154 offset:50176
	ds_read_b128 v[192:195], v154 offset:51200
	ds_read_b128 v[196:199], v154 offset:52224
	ds_read_b128 v[206:209], v154 offset:53248
	ds_read_b128 v[212:215], v154 offset:54272
	ds_read_b128 v[220:223], v154 offset:55296
	ds_read_b128 v[224:227], v154 offset:56320
	global_load_lds_dwordx4 v132, s[26:27]
	s_add_i32 m0, s44, 0x2000
	s_add_u32 s24, s24, 0x84000
	s_addc_u32 s25, s25, 0
	global_load_lds_dwordx4 v136, s[26:27]
	s_add_i32 s26, s45, s0
	s_mov_b32 m0, s26
	s_nop 0
	global_load_lds_dwordx4 v132, s[24:25]
	s_add_i32 m0, s26, 0x2000
	s_nop 0
	global_load_lds_dwordx4 v136, s[24:25]
	s_mov_b32 m0, s35
	s_nop 0
	global_load_lds_dwordx4 v130, s[22:23]
	s_mov_b32 m0, s36
	s_nop 0
	global_load_lds_dwordx4 v134, s[22:23]
	s_waitcnt vmcnt(8)
	s_waitcnt lgkmcnt(0)
	s_setprio 1
	s_barrier
	v_mfma_f32_16x16x32_bf16 v[62:65], v[146:149], v[184:187], v[62:65]
	v_mfma_f32_16x16x32_bf16 v[58:61], v[160:163], v[184:187], v[58:61]
	v_mfma_f32_16x16x32_bf16 v[46:49], v[146:149], v[192:195], v[46:49]
	v_mfma_f32_16x16x32_bf16 v[42:45], v[160:163], v[192:195], v[42:45]
	v_mfma_f32_16x16x32_bf16 v[30:33], v[146:149], v[206:209], v[30:33]
	v_mfma_f32_16x16x32_bf16 v[26:29], v[160:163], v[206:209], v[26:29]
	v_mfma_f32_16x16x32_bf16 v[14:17], v[146:149], v[220:223], v[14:17]
	v_mfma_f32_16x16x32_bf16 v[10:13], v[160:163], v[220:223], v[10:13]
	v_mfma_f32_16x16x32_bf16 v[62:65], v[156:159], v[188:191], v[62:65]
	v_mfma_f32_16x16x32_bf16 v[58:61], v[164:167], v[188:191], v[58:61]
	v_mfma_f32_16x16x32_bf16 v[46:49], v[156:159], v[196:199], v[46:49]
	v_mfma_f32_16x16x32_bf16 v[42:45], v[164:167], v[196:199], v[42:45]
	v_mfma_f32_16x16x32_bf16 v[30:33], v[156:159], v[212:215], v[30:33]
	v_mfma_f32_16x16x32_bf16 v[26:29], v[164:167], v[212:215], v[26:29]
	v_mfma_f32_16x16x32_bf16 v[14:17], v[156:159], v[224:227], v[14:17]
	v_mfma_f32_16x16x32_bf16 v[10:13], v[164:167], v[224:227], v[10:13]
	v_mfma_f32_16x16x32_bf16 v[54:57], v[168:171], v[184:187], v[54:57]
	v_mfma_f32_16x16x32_bf16 v[50:53], v[176:179], v[184:187], v[50:53]
	v_mfma_f32_16x16x32_bf16 v[38:41], v[168:171], v[192:195], v[38:41]
	v_mfma_f32_16x16x32_bf16 v[34:37], v[176:179], v[192:195], v[34:37]
	v_mfma_f32_16x16x32_bf16 v[22:25], v[168:171], v[206:209], v[22:25]
	v_mfma_f32_16x16x32_bf16 v[18:21], v[176:179], v[206:209], v[18:21]
	v_mfma_f32_16x16x32_bf16 v[6:9], v[168:171], v[220:223], v[6:9]
	v_mfma_f32_16x16x32_bf16 v[2:5], v[176:179], v[220:223], v[2:5]
	v_mfma_f32_16x16x32_bf16 v[54:57], v[172:175], v[188:191], v[54:57]
	v_mfma_f32_16x16x32_bf16 v[50:53], v[180:183], v[188:191], v[50:53]
	v_mfma_f32_16x16x32_bf16 v[38:41], v[172:175], v[196:199], v[38:41]
	v_mfma_f32_16x16x32_bf16 v[34:37], v[180:183], v[196:199], v[34:37]
	v_mfma_f32_16x16x32_bf16 v[22:25], v[172:175], v[212:215], v[22:25]
	v_mfma_f32_16x16x32_bf16 v[18:21], v[180:183], v[212:215], v[18:21]
	v_mfma_f32_16x16x32_bf16 v[6:9], v[172:175], v[224:227], v[6:9]
	v_mfma_f32_16x16x32_bf16 v[2:5], v[180:183], v[224:227], v[2:5]
	s_barrier
	s_setprio 0
	s_add_i32 s43, s43, 2
	s_add_u32 s41, s41, 0x100000
	s_addc_u32 s42, s42, 0
	s_add_u32 s20, s20, 0x200000
	s_addc_u32 s21, s21, 0
	s_cmp_gt_u32 s43, 61
	s_cbranch_scc0 .LBB0_1217
	s_and_b64 vcc, exec, s[8:9]
	s_cbranch_vccz .LBB0_1220
	s_barrier

.LBB0_1670:
	ds_read_b128 v[148:151], v143
	ds_read_b128 v[152:155], v143 offset:1024
	ds_read_b128 v[156:159], v143 offset:2048
	ds_read_b128 v[160:163], v143 offset:3072
	ds_read_b128 v[164:167], v144
	ds_read_b128 v[168:171], v144 offset:1024
	ds_read_b128 v[172:175], v144 offset:2048
	ds_read_b128 v[176:179], v144 offset:3072
	s_add_u32 s10, s6, 0x4000
	s_addc_u32 s11, s7, 0
	s_cmp_eq_u32 s28, 60
	s_cselect_b32 s18, s14, s10
	s_cselect_b32 s19, s15, s11
	s_cselect_b32 s16, s4, s26
	s_cselect_b32 s17, s5, s27
	s_add_u32 s10, s18, 0x8000
	s_addc_u32 s11, s19, 0
	s_mov_b32 m0, s29
	ds_read_b128 v[180:183], v145
	ds_read_b128 v[184:187], v145 offset:1024
	ds_read_b128 v[188:191], v145 offset:2048
	ds_read_b128 v[192:195], v145 offset:3072
	ds_read_b128 v[196:199], v145 offset:4096
	ds_read_b128 v[206:209], v145 offset:5120
	ds_read_b128 v[212:215], v145 offset:6144
	ds_read_b128 v[220:223], v145 offset:7168
	global_load_lds_dwordx4 v138, s[6:7]
	s_mov_b32 m0, s30
	s_nop 0
	global_load_lds_dwordx4 v140, s[6:7]
	s_waitcnt vmcnt(8)
	s_waitcnt lgkmcnt(0)
	s_setprio 1
	s_barrier
	v_mfma_f32_16x16x32_bf16 v[126:129], v[148:151], v[180:183], v[126:129]
	v_mfma_f32_16x16x32_bf16 v[122:125], v[156:159], v[180:183], v[122:125]
	v_mfma_f32_16x16x32_bf16 v[118:121], v[148:151], v[188:191], v[118:121]
	v_mfma_f32_16x16x32_bf16 v[110:113], v[156:159], v[188:191], v[110:113]
	v_mfma_f32_16x16x32_bf16 v[102:105], v[148:151], v[196:199], v[102:105]
	v_mfma_f32_16x16x32_bf16 v[94:97], v[156:159], v[196:199], v[94:97]
	v_mfma_f32_16x16x32_bf16 v[86:89], v[148:151], v[212:215], v[86:89]
	v_mfma_f32_16x16x32_bf16 v[78:81], v[156:159], v[212:215], v[78:81]
	v_mfma_f32_16x16x32_bf16 v[126:129], v[152:155], v[184:187], v[126:129]
	v_mfma_f32_16x16x32_bf16 v[122:125], v[160:163], v[184:187], v[122:125]
	v_mfma_f32_16x16x32_bf16 v[118:121], v[152:155], v[192:195], v[118:121]
	v_mfma_f32_16x16x32_bf16 v[110:113], v[160:163], v[192:195], v[110:113]
	v_mfma_f32_16x16x32_bf16 v[102:105], v[152:155], v[206:209], v[102:105]
	v_mfma_f32_16x16x32_bf16 v[94:97], v[160:163], v[206:209], v[94:97]
	v_mfma_f32_16x16x32_bf16 v[86:89], v[152:155], v[220:223], v[86:89]
	v_mfma_f32_16x16x32_bf16 v[78:81], v[160:163], v[220:223], v[78:81]
	v_mfma_f32_16x16x32_bf16 v[114:117], v[164:167], v[180:183], v[114:117]
	v_mfma_f32_16x16x32_bf16 v[106:109], v[172:175], v[180:183], v[106:109]
	v_mfma_f32_16x16x32_bf16 v[98:101], v[164:167], v[188:191], v[98:101]
	v_mfma_f32_16x16x32_bf16 v[90:93], v[172:175], v[188:191], v[90:93]
	v_mfma_f32_16x16x32_bf16 v[82:85], v[164:167], v[196:199], v[82:85]
	v_mfma_f32_16x16x32_bf16 v[74:77], v[172:175], v[196:199], v[74:77]
	v_mfma_f32_16x16x32_bf16 v[70:73], v[164:167], v[212:215], v[70:73]
	v_mfma_f32_16x16x32_bf16 v[66:69], v[172:175], v[212:215], v[66:69]
	v_mfma_f32_16x16x32_bf16 v[114:117], v[168:171], v[184:187], v[114:117]
	v_mfma_f32_16x16x32_bf16 v[106:109], v[176:179], v[184:187], v[106:109]
	v_mfma_f32_16x16x32_bf16 v[98:101], v[168:171], v[192:195], v[98:101]
	v_mfma_f32_16x16x32_bf16 v[90:93], v[176:179], v[192:195], v[90:93]
	v_mfma_f32_16x16x32_bf16 v[82:85], v[168:171], v[206:209], v[82:85]
	v_mfma_f32_16x16x32_bf16 v[74:77], v[176:179], v[206:209], v[74:77]
	v_mfma_f32_16x16x32_bf16 v[70:73], v[168:171], v[220:223], v[70:73]
	v_mfma_f32_16x16x32_bf16 v[66:69], v[176:179], v[220:223], v[66:69]
	s_barrier
	s_setprio 0
	s_mov_b32 m0, s31
	s_add_u32 s40, s16, 0x4000
	ds_read_b128 v[180:183], v145 offset:16384
	ds_read_b128 v[184:187], v145 offset:17408
	ds_read_b128 v[188:191], v145 offset:18432
	ds_read_b128 v[192:195], v145 offset:19456
	ds_read_b128 v[196:199], v145 offset:20480
	ds_read_b128 v[206:209], v145 offset:21504
	ds_read_b128 v[212:215], v145 offset:22528
	ds_read_b128 v[220:223], v145 offset:23552
	global_load_lds_dwordx4 v134, s[16:17]
	s_mov_b32 m0, s33
	s_addc_u32 s41, s17, 0
	global_load_lds_dwordx4 v130, s[16:17]
	s_mov_b32 m0, s34
	s_nop 0
	global_load_lds_dwordx4 v134, s[40:41]
	s_mov_b32 m0, s35
	s_nop 0
	global_load_lds_dwordx4 v130, s[40:41]
	s_mov_b32 m0, s1
	s_nop 0
	global_load_lds_dwordx4 v136, s[18:19]
	s_mov_b32 m0, s3
	s_nop 0
	global_load_lds_dwordx4 v132, s[18:19]
	s_waitcnt vmcnt(8)
	s_waitcnt lgkmcnt(0)
	s_setprio 1
	s_barrier
	v_mfma_f32_16x16x32_bf16 v[62:65], v[148:151], v[180:183], v[62:65]
	v_mfma_f32_16x16x32_bf16 v[58:61], v[156:159], v[180:183], v[58:61]
	v_mfma_f32_16x16x32_bf16 v[54:57], v[148:151], v[188:191], v[54:57]
	v_mfma_f32_16x16x32_bf16 v[46:49], v[156:159], v[188:191], v[46:49]
	v_mfma_f32_16x16x32_bf16 v[38:41], v[148:151], v[196:199], v[38:41]
	v_mfma_f32_16x16x32_bf16 v[30:33], v[156:159], v[196:199], v[30:33]
	v_mfma_f32_16x16x32_bf16 v[22:25], v[148:151], v[212:215], v[22:25]
	v_mfma_f32_16x16x32_bf16 v[14:17], v[156:159], v[212:215], v[14:17]
	v_mfma_f32_16x16x32_bf16 v[62:65], v[152:155], v[184:187], v[62:65]
	v_mfma_f32_16x16x32_bf16 v[58:61], v[160:163], v[184:187], v[58:61]
	v_mfma_f32_16x16x32_bf16 v[54:57], v[152:155], v[192:195], v[54:57]
	v_mfma_f32_16x16x32_bf16 v[46:49], v[160:163], v[192:195], v[46:49]
	v_mfma_f32_16x16x32_bf16 v[38:41], v[152:155], v[206:209], v[38:41]
	v_mfma_f32_16x16x32_bf16 v[30:33], v[160:163], v[206:209], v[30:33]
	v_mfma_f32_16x16x32_bf16 v[22:25], v[152:155], v[220:223], v[22:25]
	v_mfma_f32_16x16x32_bf16 v[14:17], v[160:163], v[220:223], v[14:17]
	v_mfma_f32_16x16x32_bf16 v[50:53], v[164:167], v[180:183], v[50:53]
	v_mfma_f32_16x16x32_bf16 v[42:45], v[172:175], v[180:183], v[42:45]
	v_mfma_f32_16x16x32_bf16 v[34:37], v[164:167], v[188:191], v[34:37]
	v_mfma_f32_16x16x32_bf16 v[26:29], v[172:175], v[188:191], v[26:29]
	v_mfma_f32_16x16x32_bf16 v[18:21], v[164:167], v[196:199], v[18:21]
	v_mfma_f32_16x16x32_bf16 v[10:13], v[172:175], v[196:199], v[10:13]
	v_mfma_f32_16x16x32_bf16 v[6:9], v[164:167], v[212:215], v[6:9]
	v_mfma_f32_16x16x32_bf16 v[2:5], v[172:175], v[212:215], v[2:5]
	v_mfma_f32_16x16x32_bf16 v[50:53], v[168:171], v[184:187], v[50:53]
	v_mfma_f32_16x16x32_bf16 v[42:45], v[176:179], v[184:187], v[42:45]
	v_mfma_f32_16x16x32_bf16 v[34:37], v[168:171], v[192:195], v[34:37]
	v_mfma_f32_16x16x32_bf16 v[26:29], v[176:179], v[192:195], v[26:29]
	v_mfma_f32_16x16x32_bf16 v[18:21], v[168:171], v[206:209], v[18:21]
	v_mfma_f32_16x16x32_bf16 v[10:13], v[176:179], v[206:209], v[10:13]
	v_mfma_f32_16x16x32_bf16 v[6:9], v[168:171], v[220:223], v[6:9]
	v_mfma_f32_16x16x32_bf16 v[2:5], v[176:179], v[220:223], v[2:5]
	s_barrier
	s_setprio 0
	ds_read_b128 v[148:151], v146
	ds_read_b128 v[152:155], v146 offset:1024
	ds_read_b128 v[156:159], v146 offset:2048
	ds_read_b128 v[160:163], v146 offset:3072
	ds_read_b128 v[164:167], v147
	ds_read_b128 v[168:171], v147 offset:1024
	ds_read_b128 v[172:175], v147 offset:2048
	ds_read_b128 v[176:179], v147 offset:3072
	s_add_u32 s18, s18, 0x4000
	s_addc_u32 s19, s19, 0
	s_mov_b32 m0, s20
	ds_read_b128 v[180:183], v145 offset:32768
	ds_read_b128 v[184:187], v145 offset:33792
	ds_read_b128 v[188:191], v145 offset:34816
	ds_read_b128 v[192:195], v145 offset:35840
	ds_read_b128 v[196:199], v145 offset:36864
	ds_read_b128 v[206:209], v145 offset:37888
	ds_read_b128 v[212:215], v145 offset:38912
	ds_read_b128 v[220:223], v145 offset:39936
	global_load_lds_dwordx4 v136, s[18:19]
	s_mov_b32 m0, s21
	s_nop 0
	global_load_lds_dwordx4 v132, s[18:19]
	s_waitcnt vmcnt(8)
	s_waitcnt lgkmcnt(0)
	s_setprio 1
	s_barrier
	v_mfma_f32_16x16x32_bf16 v[126:129], v[148:151], v[180:183], v[126:129]
	v_mfma_f32_16x16x32_bf16 v[122:125], v[156:159], v[180:183], v[122:125]
	v_mfma_f32_16x16x32_bf16 v[118:121], v[148:151], v[188:191], v[118:121]
	v_mfma_f32_16x16x32_bf16 v[110:113], v[156:159], v[188:191], v[110:113]
	v_mfma_f32_16x16x32_bf16 v[102:105], v[148:151], v[196:199], v[102:105]
	v_mfma_f32_16x16x32_bf16 v[94:97], v[156:159], v[196:199], v[94:97]
	v_mfma_f32_16x16x32_bf16 v[86:89], v[148:151], v[212:215], v[86:89]
	v_mfma_f32_16x16x32_bf16 v[78:81], v[156:159], v[212:215], v[78:81]
	v_mfma_f32_16x16x32_bf16 v[126:129], v[152:155], v[184:187], v[126:129]
	v_mfma_f32_16x16x32_bf16 v[122:125], v[160:163], v[184:187], v[122:125]
	v_mfma_f32_16x16x32_bf16 v[118:121], v[152:155], v[192:195], v[118:121]
	v_mfma_f32_16x16x32_bf16 v[110:113], v[160:163], v[192:195], v[110:113]
	v_mfma_f32_16x16x32_bf16 v[102:105], v[152:155], v[206:209], v[102:105]
	v_mfma_f32_16x16x32_bf16 v[94:97], v[160:163], v[206:209], v[94:97]
	v_mfma_f32_16x16x32_bf16 v[86:89], v[152:155], v[220:223], v[86:89]
	v_mfma_f32_16x16x32_bf16 v[78:81], v[160:163], v[220:223], v[78:81]
	v_mfma_f32_16x16x32_bf16 v[114:117], v[164:167], v[180:183], v[114:117]
	v_mfma_f32_16x16x32_bf16 v[106:109], v[172:175], v[180:183], v[106:109]
	v_mfma_f32_16x16x32_bf16 v[98:101], v[164:167], v[188:191], v[98:101]
	v_mfma_f32_16x16x32_bf16 v[90:93], v[172:175], v[188:191], v[90:93]
	v_mfma_f32_16x16x32_bf16 v[82:85], v[164:167], v[196:199], v[82:85]
	v_mfma_f32_16x16x32_bf16 v[74:77], v[172:175], v[196:199], v[74:77]
	v_mfma_f32_16x16x32_bf16 v[70:73], v[164:167], v[212:215], v[70:73]
	v_mfma_f32_16x16x32_bf16 v[66:69], v[172:175], v[212:215], v[66:69]
	v_mfma_f32_16x16x32_bf16 v[114:117], v[168:171], v[184:187], v[114:117]
	v_mfma_f32_16x16x32_bf16 v[106:109], v[176:179], v[184:187], v[106:109]
	v_mfma_f32_16x16x32_bf16 v[98:101], v[168:171], v[192:195], v[98:101]
	v_mfma_f32_16x16x32_bf16 v[90:93], v[176:179], v[192:195], v[90:93]
	v_mfma_f32_16x16x32_bf16 v[82:85], v[168:171], v[206:209], v[82:85]
	v_mfma_f32_16x16x32_bf16 v[74:77], v[176:179], v[206:209], v[74:77]
	v_mfma_f32_16x16x32_bf16 v[70:73], v[168:171], v[220:223], v[70:73]
	v_mfma_f32_16x16x32_bf16 v[66:69], v[176:179], v[220:223], v[66:69]
	s_barrier
	s_setprio 0
	s_add_u32 s18, s16, 0x20000
	s_addc_u32 s19, s17, 0
	s_mov_b32 m0, s36
	s_add_u32 s16, s16, 0x24000
	ds_read_b128 v[180:183], v145 offset:49152
	ds_read_b128 v[184:187], v145 offset:50176
	ds_read_b128 v[188:191], v145 offset:51200
	ds_read_b128 v[192:195], v145 offset:52224
	ds_read_b128 v[196:199], v145 offset:53248
	ds_read_b128 v[206:209], v145 offset:54272
	ds_read_b128 v[212:215], v145 offset:55296
	ds_read_b128 v[220:223], v145 offset:56320
	global_load_lds_dwordx4 v134, s[18:19]
	s_mov_b32 m0, s37
	s_addc_u32 s17, s17, 0
	global_load_lds_dwordx4 v130, s[18:19]
	s_mov_b32 m0, s38
	s_nop 0
	global_load_lds_dwordx4 v134, s[16:17]
	s_mov_b32 m0, s39
	s_nop 0
	global_load_lds_dwordx4 v130, s[16:17]
	s_mov_b32 m0, s24
	s_nop 0
	global_load_lds_dwordx4 v136, s[10:11]
	s_mov_b32 m0, s25
	s_nop 0
	global_load_lds_dwordx4 v132, s[10:11]
	s_waitcnt vmcnt(8)
	s_waitcnt lgkmcnt(0)
	s_setprio 1
	s_barrier
	v_mfma_f32_16x16x32_bf16 v[62:65], v[148:151], v[180:183], v[62:65]
	v_mfma_f32_16x16x32_bf16 v[58:61], v[156:159], v[180:183], v[58:61]
	v_mfma_f32_16x16x32_bf16 v[54:57], v[148:151], v[188:191], v[54:57]
	v_mfma_f32_16x16x32_bf16 v[46:49], v[156:159], v[188:191], v[46:49]
	v_mfma_f32_16x16x32_bf16 v[38:41], v[148:151], v[196:199], v[38:41]
	v_mfma_f32_16x16x32_bf16 v[30:33], v[156:159], v[196:199], v[30:33]
	v_mfma_f32_16x16x32_bf16 v[22:25], v[148:151], v[212:215], v[22:25]
	v_mfma_f32_16x16x32_bf16 v[14:17], v[156:159], v[212:215], v[14:17]
	v_mfma_f32_16x16x32_bf16 v[62:65], v[152:155], v[184:187], v[62:65]
	v_mfma_f32_16x16x32_bf16 v[58:61], v[160:163], v[184:187], v[58:61]
	v_mfma_f32_16x16x32_bf16 v[54:57], v[152:155], v[192:195], v[54:57]
	v_mfma_f32_16x16x32_bf16 v[46:49], v[160:163], v[192:195], v[46:49]
	v_mfma_f32_16x16x32_bf16 v[38:41], v[152:155], v[206:209], v[38:41]
	v_mfma_f32_16x16x32_bf16 v[30:33], v[160:163], v[206:209], v[30:33]
	v_mfma_f32_16x16x32_bf16 v[22:25], v[152:155], v[220:223], v[22:25]
	v_mfma_f32_16x16x32_bf16 v[14:17], v[160:163], v[220:223], v[14:17]
	v_mfma_f32_16x16x32_bf16 v[50:53], v[164:167], v[180:183], v[50:53]
	v_mfma_f32_16x16x32_bf16 v[42:45], v[172:175], v[180:183], v[42:45]
	v_mfma_f32_16x16x32_bf16 v[34:37], v[164:167], v[188:191], v[34:37]
	v_mfma_f32_16x16x32_bf16 v[26:29], v[172:175], v[188:191], v[26:29]
	v_mfma_f32_16x16x32_bf16 v[18:21], v[164:167], v[196:199], v[18:21]
	v_mfma_f32_16x16x32_bf16 v[10:13], v[172:175], v[196:199], v[10:13]
	v_mfma_f32_16x16x32_bf16 v[6:9], v[164:167], v[212:215], v[6:9]
	v_mfma_f32_16x16x32_bf16 v[2:5], v[172:175], v[212:215], v[2:5]
	v_mfma_f32_16x16x32_bf16 v[50:53], v[168:171], v[184:187], v[50:53]
	v_mfma_f32_16x16x32_bf16 v[42:45], v[176:179], v[184:187], v[42:45]
	v_mfma_f32_16x16x32_bf16 v[34:37], v[168:171], v[192:195], v[34:37]
	v_mfma_f32_16x16x32_bf16 v[26:29], v[176:179], v[192:195], v[26:29]
	v_mfma_f32_16x16x32_bf16 v[18:21], v[168:171], v[206:209], v[18:21]
	v_mfma_f32_16x16x32_bf16 v[10:13], v[176:179], v[206:209], v[10:13]
	v_mfma_f32_16x16x32_bf16 v[6:9], v[168:171], v[220:223], v[6:9]
	v_mfma_f32_16x16x32_bf16 v[2:5], v[176:179], v[220:223], v[2:5]
	s_barrier
	s_setprio 0
	s_add_i32 s28, s28, 2
	s_add_u32 s26, s26, 0x40000
	s_addc_u32 s27, s27, 0
	s_add_u32 s6, s6, 0x10000
	s_addc_u32 s7, s7, 0
	s_cmp_gt_u32 s28, 61
	s_cbranch_scc0 .LBB0_1670
	s_lshl_b32 s1, s2, 8
	v_and_or_b32 v132, v142, 15, s22
	v_lshrrev_b32_e32 v130, 1, v142
	v_and_or_b32 v130, v130, 24, s1
	v_ashrrev_i32_e32 v133, 31, v132
	v_or_b32_e32 v134, s23, v130
	v_lshlrev_b64 v[130:131], 11, v[132:133]
	v_lshl_add_u64 v[130:131], s[8:9], 0, v[130:131]
	v_lshlrev_b32_e32 v134, 1, v134
	v_mov_b32_e32 v135, 0
	v_lshl_add_u64 v[130:131], v[130:131], 0, v[134:135]
	v_cvt_pk_bf16_f32 v126, v126, v127
	v_cvt_pk_bf16_f32 v127, v128, v129
	v_cvt_pk_bf16_f32 v128, v122, v123
	v_cvt_pk_bf16_f32 v129, v124, v125
	global_store_dwordx4 v[130:131], v[126:129], off
	v_cvt_pk_bf16_f32 v114, v114, v115
	v_cvt_pk_bf16_f32 v115, v116, v117
	v_cvt_pk_bf16_f32 v116, v106, v107
	v_or_b32_e32 v106, 16, v132
	v_ashrrev_i32_e32 v107, 31, v106
	v_lshlrev_b64 v[106:107], 11, v[106:107]
	v_lshl_add_u64 v[106:107], s[8:9], 0, v[106:107]
	v_cvt_pk_bf16_f32 v117, v108, v109
	global_store_dwordx4 v[130:131], v[114:117], off offset:256
	s_mov_b32 s1, 0x40000
	s_mov_b64 s[2:3], 0x40000
	v_lshl_add_u64 v[114:115], v[106:107], 0, v[134:135]
	v_cvt_pk_bf16_f32 v106, v118, v119
	v_cvt_pk_bf16_f32 v107, v120, v121
	v_cvt_pk_bf16_f32 v108, v110, v111
	v_cvt_pk_bf16_f32 v109, v112, v113
	global_store_dwordx4 v[114:115], v[106:109], off
	v_cvt_pk_bf16_f32 v98, v98, v99
	v_cvt_pk_bf16_f32 v99, v100, v101
	v_cvt_pk_bf16_f32 v100, v90, v91
	v_or_b32_e32 v90, 32, v132
	v_ashrrev_i32_e32 v91, 31, v90
	v_lshlrev_b64 v[90:91], 11, v[90:91]
	v_lshl_add_u64 v[90:91], s[8:9], 0, v[90:91]
	v_cvt_pk_bf16_f32 v101, v92, v93
	global_store_dwordx4 v[114:115], v[98:101], off offset:256
	s_cmpk_lt_u32 s0, 0x100
	s_nop 0
	v_lshl_add_u64 v[98:99], v[90:91], 0, v[134:135]
	v_cvt_pk_bf16_f32 v90, v102, v103
	v_cvt_pk_bf16_f32 v91, v104, v105
	v_cvt_pk_bf16_f32 v92, v94, v95
	v_cvt_pk_bf16_f32 v93, v96, v97
	global_store_dwordx4 v[98:99], v[90:93], off
	v_cvt_pk_bf16_f32 v82, v82, v83
	v_cvt_pk_bf16_f32 v83, v84, v85
	v_cvt_pk_bf16_f32 v84, v74, v75
	v_or_b32_e32 v74, 48, v132
	v_ashrrev_i32_e32 v75, 31, v74
	v_lshlrev_b64 v[74:75], 11, v[74:75]
	v_lshl_add_u64 v[74:75], s[8:9], 0, v[74:75]
	v_cvt_pk_bf16_f32 v85, v76, v77
	global_store_dwordx4 v[98:99], v[82:85], off offset:256
	s_nop 1
	v_lshl_add_u64 v[82:83], v[74:75], 0, v[134:135]
	v_cvt_pk_bf16_f32 v74, v86, v87
	v_cvt_pk_bf16_f32 v75, v88, v89
	v_cvt_pk_bf16_f32 v76, v78, v79
	v_cvt_pk_bf16_f32 v77, v80, v81
	global_store_dwordx4 v[82:83], v[74:77], off
	v_cvt_pk_bf16_f32 v70, v70, v71
	v_cvt_pk_bf16_f32 v71, v72, v73
	v_cvt_pk_bf16_f32 v72, v66, v67
	v_cvt_pk_bf16_f32 v73, v68, v69
	global_store_dwordx4 v[82:83], v[70:73], off offset:256
	v_cvt_pk_bf16_f32 v62, v62, v63
	v_cvt_pk_bf16_f32 v63, v64, v65
	v_cvt_pk_bf16_f32 v64, v58, v59
	v_add_co_u32_e32 v58, vcc, s1, v130
	v_lshl_add_u64 v[66:67], v[130:131], 0, s[2:3]
	s_nop 0
	v_addc_co_u32_e32 v59, vcc, 0, v131, vcc
	s_mov_b32 s1, 0x48000
	v_cvt_pk_bf16_f32 v65, v60, v61
	global_store_dwordx4 v[58:59], v[62:65], off
	v_cvt_pk_bf16_f32 v50, v50, v51
	v_cvt_pk_bf16_f32 v51, v52, v53
	v_cvt_pk_bf16_f32 v52, v42, v43
	v_cvt_pk_bf16_f32 v53, v44, v45
	global_store_dwordx4 v[66:67], v[50:53], off offset:256
	s_mov_b64 s[2:3], 0x48000
	v_cvt_pk_bf16_f32 v42, v54, v55
	v_cvt_pk_bf16_f32 v43, v56, v57
	v_cvt_pk_bf16_f32 v44, v46, v47
	v_add_co_u32_e32 v46, vcc, s1, v130
	v_lshl_add_u64 v[50:51], v[130:131], 0, s[2:3]
	s_nop 0
	v_addc_co_u32_e32 v47, vcc, 0, v131, vcc
	s_mov_b32 s1, 0x50000
	v_cvt_pk_bf16_f32 v45, v48, v49
	global_store_dwordx4 v[46:47], v[42:45], off
	v_cvt_pk_bf16_f32 v34, v34, v35
	v_cvt_pk_bf16_f32 v35, v36, v37
	v_cvt_pk_bf16_f32 v36, v26, v27
	v_cvt_pk_bf16_f32 v37, v28, v29
	global_store_dwordx4 v[50:51], v[34:37], off offset:256
	s_mov_b64 s[2:3], 0x50000
	v_cvt_pk_bf16_f32 v26, v38, v39
	v_cvt_pk_bf16_f32 v27, v40, v41
	v_cvt_pk_bf16_f32 v28, v30, v31
	v_add_co_u32_e32 v30, vcc, s1, v130
	v_lshl_add_u64 v[34:35], v[130:131], 0, s[2:3]
	s_nop 0
	v_addc_co_u32_e32 v31, vcc, 0, v131, vcc
	s_mov_b32 s1, 0x58000
	v_cvt_pk_bf16_f32 v29, v32, v33
	global_store_dwordx4 v[30:31], v[26:29], off
	v_cvt_pk_bf16_f32 v18, v18, v19
	v_cvt_pk_bf16_f32 v19, v20, v21
	v_cvt_pk_bf16_f32 v20, v10, v11
	v_cvt_pk_bf16_f32 v21, v12, v13
	global_store_dwordx4 v[34:35], v[18:21], off offset:256
	s_mov_b64 s[2:3], 0x58000
	v_cvt_pk_bf16_f32 v10, v22, v23
	v_cvt_pk_bf16_f32 v11, v24, v25
	v_cvt_pk_bf16_f32 v12, v14, v15
	v_add_co_u32_e32 v14, vcc, s1, v130
	v_lshl_add_u64 v[18:19], v[130:131], 0, s[2:3]
	s_nop 0
	v_addc_co_u32_e32 v15, vcc, 0, v131, vcc
	v_cvt_pk_bf16_f32 v13, v16, v17
	global_store_dwordx4 v[14:15], v[10:13], off
	v_cvt_pk_bf16_f32 v6, v6, v7
	v_cvt_pk_bf16_f32 v7, v8, v9
	v_cvt_pk_bf16_f32 v8, v2, v3
	v_cvt_pk_bf16_f32 v9, v4, v5
	global_store_dwordx4 v[18:19], v[6:9], off offset:256
	s_waitcnt vmcnt(0)
	s_cbranch_scc0 .LBB0_1673
	s_barrier

.LBB0_1691:
	ds_read_b128 v[142:145], v150
	ds_read_b128 v[154:157], v150 offset:1024
	ds_read_b128 v[158:161], v150 offset:2048
	ds_read_b128 v[162:165], v150 offset:3072
	ds_read_b128 v[166:169], v151
	ds_read_b128 v[170:173], v151 offset:1024
	ds_read_b128 v[174:177], v151 offset:2048
	ds_read_b128 v[178:181], v151 offset:3072
	s_add_u32 s24, s22, 0xfc000
	s_addc_u32 s25, s23, 0
	s_cmp_eq_u32 s46, 60
	s_cselect_b32 s28, s17, s24
	s_cselect_b32 s29, s11, s25
	s_cselect_b32 s26, s43, s44
	s_cselect_b32 s27, s7, s45
	s_add_u32 s24, s28, 0x100000
	s_addc_u32 s25, s29, 0
	s_add_i32 m0, s30, 0xc000
	ds_read_b128 v[182:185], v152
	ds_read_b128 v[186:189], v152 offset:1024
	ds_read_b128 v[190:193], v152 offset:2048
	ds_read_b128 v[194:197], v152 offset:3072
	ds_read_b128 v[206:209], v152 offset:4096
	ds_read_b128 v[212:215], v152 offset:5120
	ds_read_b128 v[220:223], v152 offset:6144
	ds_read_b128 v[224:227], v152 offset:7168
	global_load_lds_dwordx4 v138, s[22:23]
	s_add_i32 m0, s30, 0xe000
	s_nop 0
	global_load_lds_dwordx4 v140, s[22:23]
	s_waitcnt vmcnt(8)
	s_waitcnt lgkmcnt(0)
	s_setprio 1
	s_barrier
	v_mfma_f32_16x16x32_bf16 v[126:129], v[142:145], v[182:185], v[126:129]
	v_mfma_f32_16x16x32_bf16 v[122:125], v[158:161], v[182:185], v[122:125]
	v_mfma_f32_16x16x32_bf16 v[110:113], v[142:145], v[190:193], v[110:113]
	v_mfma_f32_16x16x32_bf16 v[106:109], v[158:161], v[190:193], v[106:109]
	v_mfma_f32_16x16x32_bf16 v[94:97], v[142:145], v[206:209], v[94:97]
	v_mfma_f32_16x16x32_bf16 v[90:93], v[158:161], v[206:209], v[90:93]
	v_mfma_f32_16x16x32_bf16 v[78:81], v[142:145], v[220:223], v[78:81]
	v_mfma_f32_16x16x32_bf16 v[74:77], v[158:161], v[220:223], v[74:77]
	v_mfma_f32_16x16x32_bf16 v[126:129], v[154:157], v[186:189], v[126:129]
	v_mfma_f32_16x16x32_bf16 v[122:125], v[162:165], v[186:189], v[122:125]
	v_mfma_f32_16x16x32_bf16 v[110:113], v[154:157], v[194:197], v[110:113]
	v_mfma_f32_16x16x32_bf16 v[106:109], v[162:165], v[194:197], v[106:109]
	v_mfma_f32_16x16x32_bf16 v[94:97], v[154:157], v[212:215], v[94:97]
	v_mfma_f32_16x16x32_bf16 v[90:93], v[162:165], v[212:215], v[90:93]
	v_mfma_f32_16x16x32_bf16 v[78:81], v[154:157], v[224:227], v[78:81]
	v_mfma_f32_16x16x32_bf16 v[74:77], v[162:165], v[224:227], v[74:77]
	v_mfma_f32_16x16x32_bf16 v[118:121], v[166:169], v[182:185], v[118:121]
	v_mfma_f32_16x16x32_bf16 v[114:117], v[174:177], v[182:185], v[114:117]
	v_mfma_f32_16x16x32_bf16 v[102:105], v[166:169], v[190:193], v[102:105]
	v_mfma_f32_16x16x32_bf16 v[98:101], v[174:177], v[190:193], v[98:101]
	v_mfma_f32_16x16x32_bf16 v[86:89], v[166:169], v[206:209], v[86:89]
	v_mfma_f32_16x16x32_bf16 v[82:85], v[174:177], v[206:209], v[82:85]
	v_mfma_f32_16x16x32_bf16 v[70:73], v[166:169], v[220:223], v[70:73]
	v_mfma_f32_16x16x32_bf16 v[66:69], v[174:177], v[220:223], v[66:69]
	v_mfma_f32_16x16x32_bf16 v[118:121], v[170:173], v[186:189], v[118:121]
	v_mfma_f32_16x16x32_bf16 v[114:117], v[178:181], v[186:189], v[114:117]
	v_mfma_f32_16x16x32_bf16 v[102:105], v[170:173], v[194:197], v[102:105]
	v_mfma_f32_16x16x32_bf16 v[98:101], v[178:181], v[194:197], v[98:101]
	v_mfma_f32_16x16x32_bf16 v[86:89], v[170:173], v[212:215], v[86:89]
	v_mfma_f32_16x16x32_bf16 v[82:85], v[178:181], v[212:215], v[82:85]
	v_mfma_f32_16x16x32_bf16 v[70:73], v[170:173], v[224:227], v[70:73]
	v_mfma_f32_16x16x32_bf16 v[66:69], v[178:181], v[224:227], v[66:69]
	s_barrier
	s_setprio 0
	s_add_i32 s47, s40, s1
	s_mov_b32 m0, s47
	ds_read_b128 v[182:185], v152 offset:16384
	ds_read_b128 v[186:189], v152 offset:17408
	ds_read_b128 v[190:193], v152 offset:18432
	ds_read_b128 v[194:197], v152 offset:19456
	ds_read_b128 v[206:209], v152 offset:20480
	ds_read_b128 v[212:215], v152 offset:21504
	ds_read_b128 v[220:223], v152 offset:22528
	ds_read_b128 v[224:227], v152 offset:23552
	global_load_lds_dwordx4 v132, s[26:27]
	s_add_i32 m0, s47, 0x2000
	s_add_u32 s48, s26, 0x4000
	s_addc_u32 s49, s27, 0
	s_add_i32 s47, s41, s1
	global_load_lds_dwordx4 v136, s[26:27]
	s_mov_b32 m0, s47
	s_nop 0
	global_load_lds_dwordx4 v132, s[48:49]
	s_add_i32 m0, s47, 0x2000
	s_nop 0
	global_load_lds_dwordx4 v136, s[48:49]
	s_mov_b32 m0, s30
	s_nop 0
	global_load_lds_dwordx4 v130, s[28:29]
	s_mov_b32 m0, s31
	s_nop 0
	global_load_lds_dwordx4 v134, s[28:29]
	s_waitcnt vmcnt(8)
	s_waitcnt lgkmcnt(0)
	s_setprio 1
	s_barrier
	v_mfma_f32_16x16x32_bf16 v[62:65], v[142:145], v[182:185], v[62:65]
	v_mfma_f32_16x16x32_bf16 v[58:61], v[158:161], v[182:185], v[58:61]
	v_mfma_f32_16x16x32_bf16 v[46:49], v[142:145], v[190:193], v[46:49]
	v_mfma_f32_16x16x32_bf16 v[42:45], v[158:161], v[190:193], v[42:45]
	v_mfma_f32_16x16x32_bf16 v[30:33], v[142:145], v[206:209], v[30:33]
	v_mfma_f32_16x16x32_bf16 v[26:29], v[158:161], v[206:209], v[26:29]
	v_mfma_f32_16x16x32_bf16 v[14:17], v[142:145], v[220:223], v[14:17]
	v_mfma_f32_16x16x32_bf16 v[10:13], v[158:161], v[220:223], v[10:13]
	v_mfma_f32_16x16x32_bf16 v[62:65], v[154:157], v[186:189], v[62:65]
	v_mfma_f32_16x16x32_bf16 v[58:61], v[162:165], v[186:189], v[58:61]
	v_mfma_f32_16x16x32_bf16 v[46:49], v[154:157], v[194:197], v[46:49]
	v_mfma_f32_16x16x32_bf16 v[42:45], v[162:165], v[194:197], v[42:45]
	v_mfma_f32_16x16x32_bf16 v[30:33], v[154:157], v[212:215], v[30:33]
	v_mfma_f32_16x16x32_bf16 v[26:29], v[162:165], v[212:215], v[26:29]
	v_mfma_f32_16x16x32_bf16 v[14:17], v[154:157], v[224:227], v[14:17]
	v_mfma_f32_16x16x32_bf16 v[10:13], v[162:165], v[224:227], v[10:13]
	v_mfma_f32_16x16x32_bf16 v[54:57], v[166:169], v[182:185], v[54:57]
	v_mfma_f32_16x16x32_bf16 v[50:53], v[174:177], v[182:185], v[50:53]
	v_mfma_f32_16x16x32_bf16 v[38:41], v[166:169], v[190:193], v[38:41]
	v_mfma_f32_16x16x32_bf16 v[34:37], v[174:177], v[190:193], v[34:37]
	v_mfma_f32_16x16x32_bf16 v[22:25], v[166:169], v[206:209], v[22:25]
	v_mfma_f32_16x16x32_bf16 v[18:21], v[174:177], v[206:209], v[18:21]
	v_mfma_f32_16x16x32_bf16 v[6:9], v[166:169], v[220:223], v[6:9]
	v_mfma_f32_16x16x32_bf16 v[2:5], v[174:177], v[220:223], v[2:5]
	v_mfma_f32_16x16x32_bf16 v[54:57], v[170:173], v[186:189], v[54:57]
	v_mfma_f32_16x16x32_bf16 v[50:53], v[178:181], v[186:189], v[50:53]
	v_mfma_f32_16x16x32_bf16 v[38:41], v[170:173], v[194:197], v[38:41]
	v_mfma_f32_16x16x32_bf16 v[34:37], v[178:181], v[194:197], v[34:37]
	v_mfma_f32_16x16x32_bf16 v[22:25], v[170:173], v[212:215], v[22:25]
	v_mfma_f32_16x16x32_bf16 v[18:21], v[178:181], v[212:215], v[18:21]
	v_mfma_f32_16x16x32_bf16 v[6:9], v[170:173], v[224:227], v[6:9]
	v_mfma_f32_16x16x32_bf16 v[2:5], v[178:181], v[224:227], v[2:5]
	s_barrier
	s_setprio 0
	s_add_i32 s47, 0, 0x18000
	v_add_u32_e32 v146, s47, v149
	s_add_i32 s48, 0, 0x1c000
	ds_read_b128 v[142:145], v146
	ds_read_b128 v[154:157], v146 offset:1024
	ds_read_b128 v[158:161], v146 offset:2048
	ds_read_b128 v[162:165], v146 offset:3072
	v_add_u32_e32 v146, s48, v149
	ds_read_b128 v[166:169], v146
	ds_read_b128 v[170:173], v146 offset:1024
	ds_read_b128 v[174:177], v146 offset:2048
	ds_read_b128 v[178:181], v146 offset:3072
	s_add_u32 s28, s28, 0x4000
	s_addc_u32 s29, s29, 0
	s_mov_b32 m0, s33
	ds_read_b128 v[182:185], v152 offset:32768
	ds_read_b128 v[186:189], v152 offset:33792
	ds_read_b128 v[190:193], v152 offset:34816
	ds_read_b128 v[194:197], v152 offset:35840
	ds_read_b128 v[206:209], v152 offset:36864
	ds_read_b128 v[212:215], v152 offset:37888
	ds_read_b128 v[220:223], v152 offset:38912
	ds_read_b128 v[224:227], v152 offset:39936
	global_load_lds_dwordx4 v130, s[28:29]
	s_mov_b32 m0, s34
	s_nop 0
	global_load_lds_dwordx4 v134, s[28:29]
	s_waitcnt vmcnt(8)
	s_waitcnt lgkmcnt(0)
	s_setprio 1
	s_barrier
	v_mfma_f32_16x16x32_bf16 v[126:129], v[142:145], v[182:185], v[126:129]
	v_mfma_f32_16x16x32_bf16 v[122:125], v[158:161], v[182:185], v[122:125]
	v_mfma_f32_16x16x32_bf16 v[110:113], v[142:145], v[190:193], v[110:113]
	v_mfma_f32_16x16x32_bf16 v[106:109], v[158:161], v[190:193], v[106:109]
	v_mfma_f32_16x16x32_bf16 v[94:97], v[142:145], v[206:209], v[94:97]
	v_mfma_f32_16x16x32_bf16 v[90:93], v[158:161], v[206:209], v[90:93]
	v_mfma_f32_16x16x32_bf16 v[78:81], v[142:145], v[220:223], v[78:81]
	v_mfma_f32_16x16x32_bf16 v[74:77], v[158:161], v[220:223], v[74:77]
	v_mfma_f32_16x16x32_bf16 v[126:129], v[154:157], v[186:189], v[126:129]
	v_mfma_f32_16x16x32_bf16 v[122:125], v[162:165], v[186:189], v[122:125]
	v_mfma_f32_16x16x32_bf16 v[110:113], v[154:157], v[194:197], v[110:113]
	v_mfma_f32_16x16x32_bf16 v[106:109], v[162:165], v[194:197], v[106:109]
	v_mfma_f32_16x16x32_bf16 v[94:97], v[154:157], v[212:215], v[94:97]
	v_mfma_f32_16x16x32_bf16 v[90:93], v[162:165], v[212:215], v[90:93]
	v_mfma_f32_16x16x32_bf16 v[78:81], v[154:157], v[224:227], v[78:81]
	v_mfma_f32_16x16x32_bf16 v[74:77], v[162:165], v[224:227], v[74:77]
	v_mfma_f32_16x16x32_bf16 v[118:121], v[166:169], v[182:185], v[118:121]
	v_mfma_f32_16x16x32_bf16 v[114:117], v[174:177], v[182:185], v[114:117]
	v_mfma_f32_16x16x32_bf16 v[102:105], v[166:169], v[190:193], v[102:105]
	v_mfma_f32_16x16x32_bf16 v[98:101], v[174:177], v[190:193], v[98:101]
	v_mfma_f32_16x16x32_bf16 v[86:89], v[166:169], v[206:209], v[86:89]
	v_mfma_f32_16x16x32_bf16 v[82:85], v[174:177], v[206:209], v[82:85]
	v_mfma_f32_16x16x32_bf16 v[70:73], v[166:169], v[220:223], v[70:73]
	v_mfma_f32_16x16x32_bf16 v[66:69], v[174:177], v[220:223], v[66:69]
	v_mfma_f32_16x16x32_bf16 v[118:121], v[170:173], v[186:189], v[118:121]
	v_mfma_f32_16x16x32_bf16 v[114:117], v[178:181], v[186:189], v[114:117]
	v_mfma_f32_16x16x32_bf16 v[102:105], v[170:173], v[194:197], v[102:105]
	v_mfma_f32_16x16x32_bf16 v[98:101], v[178:181], v[194:197], v[98:101]
	v_mfma_f32_16x16x32_bf16 v[86:89], v[170:173], v[212:215], v[86:89]
	v_mfma_f32_16x16x32_bf16 v[82:85], v[178:181], v[212:215], v[82:85]
	v_mfma_f32_16x16x32_bf16 v[70:73], v[170:173], v[224:227], v[70:73]
	v_mfma_f32_16x16x32_bf16 v[66:69], v[178:181], v[224:227], v[66:69]
	s_barrier
	s_setprio 0
	s_add_u32 s28, s26, 0x10000
	s_addc_u32 s29, s27, 0
	s_add_i32 s47, s47, s1
	s_mov_b32 m0, s47
	ds_read_b128 v[182:185], v152 offset:49152
	ds_read_b128 v[186:189], v152 offset:50176
	ds_read_b128 v[190:193], v152 offset:51200
	ds_read_b128 v[194:197], v152 offset:52224
	ds_read_b128 v[206:209], v152 offset:53248
	ds_read_b128 v[212:215], v152 offset:54272
	ds_read_b128 v[220:223], v152 offset:55296
	ds_read_b128 v[224:227], v152 offset:56320
	global_load_lds_dwordx4 v132, s[28:29]
	s_add_i32 m0, s47, 0x2000
	s_add_u32 s26, s26, 0x14000
	s_addc_u32 s27, s27, 0
	global_load_lds_dwordx4 v136, s[28:29]
	s_add_i32 s28, s48, s1
	s_mov_b32 m0, s28
	s_nop 0
	global_load_lds_dwordx4 v132, s[26:27]
	s_add_i32 m0, s28, 0x2000
	s_nop 0
	global_load_lds_dwordx4 v136, s[26:27]
	s_mov_b32 m0, s38
	s_nop 0
	global_load_lds_dwordx4 v130, s[24:25]
	s_mov_b32 m0, s39
	s_nop 0
	global_load_lds_dwordx4 v134, s[24:25]
	s_waitcnt vmcnt(8)
	s_waitcnt lgkmcnt(0)
	s_setprio 1
	s_barrier
	v_mfma_f32_16x16x32_bf16 v[62:65], v[142:145], v[182:185], v[62:65]
	v_mfma_f32_16x16x32_bf16 v[58:61], v[158:161], v[182:185], v[58:61]
	v_mfma_f32_16x16x32_bf16 v[46:49], v[142:145], v[190:193], v[46:49]
	v_mfma_f32_16x16x32_bf16 v[42:45], v[158:161], v[190:193], v[42:45]
	v_mfma_f32_16x16x32_bf16 v[30:33], v[142:145], v[206:209], v[30:33]
	v_mfma_f32_16x16x32_bf16 v[26:29], v[158:161], v[206:209], v[26:29]
	v_mfma_f32_16x16x32_bf16 v[14:17], v[142:145], v[220:223], v[14:17]
	v_mfma_f32_16x16x32_bf16 v[10:13], v[158:161], v[220:223], v[10:13]
	v_mfma_f32_16x16x32_bf16 v[62:65], v[154:157], v[186:189], v[62:65]
	v_mfma_f32_16x16x32_bf16 v[58:61], v[162:165], v[186:189], v[58:61]
	v_mfma_f32_16x16x32_bf16 v[46:49], v[154:157], v[194:197], v[46:49]
	v_mfma_f32_16x16x32_bf16 v[42:45], v[162:165], v[194:197], v[42:45]
	v_mfma_f32_16x16x32_bf16 v[30:33], v[154:157], v[212:215], v[30:33]
	v_mfma_f32_16x16x32_bf16 v[26:29], v[162:165], v[212:215], v[26:29]
	v_mfma_f32_16x16x32_bf16 v[14:17], v[154:157], v[224:227], v[14:17]
	v_mfma_f32_16x16x32_bf16 v[10:13], v[162:165], v[224:227], v[10:13]
	v_mfma_f32_16x16x32_bf16 v[54:57], v[166:169], v[182:185], v[54:57]
	v_mfma_f32_16x16x32_bf16 v[50:53], v[174:177], v[182:185], v[50:53]
	v_mfma_f32_16x16x32_bf16 v[38:41], v[166:169], v[190:193], v[38:41]
	v_mfma_f32_16x16x32_bf16 v[34:37], v[174:177], v[190:193], v[34:37]
	v_mfma_f32_16x16x32_bf16 v[22:25], v[166:169], v[206:209], v[22:25]
	v_mfma_f32_16x16x32_bf16 v[18:21], v[174:177], v[206:209], v[18:21]
	v_mfma_f32_16x16x32_bf16 v[6:9], v[166:169], v[220:223], v[6:9]
	v_mfma_f32_16x16x32_bf16 v[2:5], v[174:177], v[220:223], v[2:5]
	v_mfma_f32_16x16x32_bf16 v[54:57], v[170:173], v[186:189], v[54:57]
	v_mfma_f32_16x16x32_bf16 v[50:53], v[178:181], v[186:189], v[50:53]
	v_mfma_f32_16x16x32_bf16 v[38:41], v[170:173], v[194:197], v[38:41]
	v_mfma_f32_16x16x32_bf16 v[34:37], v[178:181], v[194:197], v[34:37]
	v_mfma_f32_16x16x32_bf16 v[22:25], v[170:173], v[212:215], v[22:25]
	v_mfma_f32_16x16x32_bf16 v[18:21], v[178:181], v[212:215], v[18:21]
	v_mfma_f32_16x16x32_bf16 v[6:9], v[170:173], v[224:227], v[6:9]
	v_mfma_f32_16x16x32_bf16 v[2:5], v[178:181], v[224:227], v[2:5]
	s_barrier
	s_setprio 0
	s_add_i32 s46, s46, 2
	s_add_u32 s44, s44, 0x20000
	s_addc_u32 s45, s45, 0
	s_add_u32 s22, s22, 0x200000
	s_addc_u32 s23, s23, 0
	s_cmp_gt_u32 s46, 61
	s_cbranch_scc0 .LBB0_1691
	s_lshl_b32 s7, s10, 8
	v_mov_b32_e32 v144, v147
	s_add_i32 s7, s7, s36
	v_cndmask_b32_e64 v145, 0, 1, s[2:3]
	v_and_or_b32 v142, v144, 15, s7
	v_ashrrev_i32_e32 v143, 31, v142
	v_mov_b32_e32 v146, 0x3e0293ee
	v_cmp_ne_u32_e64 s[10:11], 1, v145
	s_andn2_b64 vcc, exec, s[2:3]
	v_mov_b32_e32 v148, 0x3e0293ee
	s_cbranch_vccnz .LBB0_1694
	v_readlane_b32 s22, v245, 16
	v_readlane_b32 s23, v245, 17
	s_nop 1
	v_lshl_add_u64 v[154:155], v[142:143], 2, s[22:23]
	global_load_dword v145, v[154:155], off
	s_waitcnt vmcnt(0)
	v_mul_f32_e32 v148, 0x3e0293ee, v145

.LBB0_1718:
	ds_read_b128 v[152:155], v147
	ds_read_b128 v[156:159], v147 offset:1024
	ds_read_b128 v[160:163], v147 offset:2048
	ds_read_b128 v[164:167], v147 offset:3072
	ds_read_b128 v[168:171], v148
	ds_read_b128 v[172:175], v148 offset:1024
	ds_read_b128 v[176:179], v148 offset:2048
	ds_read_b128 v[180:183], v148 offset:3072
	s_add_u32 s18, s16, 0x4000
	s_addc_u32 s19, s17, 0
	s_cmp_eq_u32 s50, 60
	s_cselect_b32 s22, s14, s18
	s_cselect_b32 s23, s15, s19
	s_cselect_b32 s20, s47, s48
	s_cselect_b32 s21, s46, s49
	s_add_u32 s18, s22, 0x8000
	s_addc_u32 s19, s23, 0
	s_mov_b32 m0, s31
	ds_read_b128 v[184:187], v149
	ds_read_b128 v[188:191], v149 offset:1024
	ds_read_b128 v[192:195], v149 offset:2048
	ds_read_b128 v[196:199], v149 offset:3072
	ds_read_b128 v[206:209], v149 offset:4096
	ds_read_b128 v[212:215], v149 offset:5120
	ds_read_b128 v[220:223], v149 offset:6144
	ds_read_b128 v[224:227], v149 offset:7168
	global_load_lds_dwordx4 v140, s[16:17]
	s_mov_b32 m0, s33
	s_nop 0
	global_load_lds_dwordx4 v142, s[16:17]
	s_waitcnt vmcnt(8)
	s_waitcnt lgkmcnt(0)
	s_setprio 1
	s_barrier
	v_mfma_f32_16x16x32_bf16 v[126:129], v[152:155], v[184:187], v[126:129]
	v_mfma_f32_16x16x32_bf16 v[122:125], v[160:163], v[184:187], v[122:125]
	v_mfma_f32_16x16x32_bf16 v[118:121], v[152:155], v[192:195], v[118:121]
	v_mfma_f32_16x16x32_bf16 v[110:113], v[160:163], v[192:195], v[110:113]
	v_mfma_f32_16x16x32_bf16 v[102:105], v[152:155], v[206:209], v[102:105]
	v_mfma_f32_16x16x32_bf16 v[94:97], v[160:163], v[206:209], v[94:97]
	v_mfma_f32_16x16x32_bf16 v[86:89], v[152:155], v[220:223], v[86:89]
	v_mfma_f32_16x16x32_bf16 v[78:81], v[160:163], v[220:223], v[78:81]
	v_mfma_f32_16x16x32_bf16 v[126:129], v[156:159], v[188:191], v[126:129]
	v_mfma_f32_16x16x32_bf16 v[122:125], v[164:167], v[188:191], v[122:125]
	v_mfma_f32_16x16x32_bf16 v[118:121], v[156:159], v[196:199], v[118:121]
	v_mfma_f32_16x16x32_bf16 v[110:113], v[164:167], v[196:199], v[110:113]
	v_mfma_f32_16x16x32_bf16 v[102:105], v[156:159], v[212:215], v[102:105]
	v_mfma_f32_16x16x32_bf16 v[94:97], v[164:167], v[212:215], v[94:97]
	v_mfma_f32_16x16x32_bf16 v[86:89], v[156:159], v[224:227], v[86:89]
	v_mfma_f32_16x16x32_bf16 v[78:81], v[164:167], v[224:227], v[78:81]
	v_mfma_f32_16x16x32_bf16 v[114:117], v[168:171], v[184:187], v[114:117]
	v_mfma_f32_16x16x32_bf16 v[106:109], v[176:179], v[184:187], v[106:109]
	v_mfma_f32_16x16x32_bf16 v[98:101], v[168:171], v[192:195], v[98:101]
	v_mfma_f32_16x16x32_bf16 v[90:93], v[176:179], v[192:195], v[90:93]
	v_mfma_f32_16x16x32_bf16 v[82:85], v[168:171], v[206:209], v[82:85]
	v_mfma_f32_16x16x32_bf16 v[74:77], v[176:179], v[206:209], v[74:77]
	v_mfma_f32_16x16x32_bf16 v[70:73], v[168:171], v[220:223], v[70:73]
	v_mfma_f32_16x16x32_bf16 v[66:69], v[176:179], v[220:223], v[66:69]
	v_mfma_f32_16x16x32_bf16 v[114:117], v[172:175], v[188:191], v[114:117]
	v_mfma_f32_16x16x32_bf16 v[106:109], v[180:183], v[188:191], v[106:109]
	v_mfma_f32_16x16x32_bf16 v[98:101], v[172:175], v[196:199], v[98:101]
	v_mfma_f32_16x16x32_bf16 v[90:93], v[180:183], v[196:199], v[90:93]
	v_mfma_f32_16x16x32_bf16 v[82:85], v[172:175], v[212:215], v[82:85]
	v_mfma_f32_16x16x32_bf16 v[74:77], v[180:183], v[212:215], v[74:77]
	v_mfma_f32_16x16x32_bf16 v[70:73], v[172:175], v[224:227], v[70:73]
	v_mfma_f32_16x16x32_bf16 v[66:69], v[180:183], v[224:227], v[66:69]
	s_barrier
	s_setprio 0
	s_mov_b32 m0, s36
	s_add_u32 s52, s20, 0x4000
	ds_read_b128 v[184:187], v149 offset:16384
	ds_read_b128 v[188:191], v149 offset:17408
	ds_read_b128 v[192:195], v149 offset:18432
	ds_read_b128 v[196:199], v149 offset:19456
	ds_read_b128 v[206:209], v149 offset:20480
	ds_read_b128 v[212:215], v149 offset:21504
	ds_read_b128 v[220:223], v149 offset:22528
	ds_read_b128 v[224:227], v149 offset:23552
	global_load_lds_dwordx4 v134, s[20:21]
	s_mov_b32 m0, s37
	s_addc_u32 s53, s21, 0
	global_load_lds_dwordx4 v130, s[20:21]
	s_mov_b32 m0, s38
	s_nop 0
	global_load_lds_dwordx4 v134, s[52:53]
	s_mov_b32 m0, s39
	s_nop 0
	global_load_lds_dwordx4 v130, s[52:53]
	s_mov_b32 m0, s1
	s_nop 0
	global_load_lds_dwordx4 v136, s[22:23]
	s_mov_b32 m0, s24
	s_nop 0
	global_load_lds_dwordx4 v132, s[22:23]
	s_waitcnt vmcnt(8)
	s_waitcnt lgkmcnt(0)
	s_setprio 1
	s_barrier
	v_mfma_f32_16x16x32_bf16 v[62:65], v[152:155], v[184:187], v[62:65]
	v_mfma_f32_16x16x32_bf16 v[58:61], v[160:163], v[184:187], v[58:61]
	v_mfma_f32_16x16x32_bf16 v[54:57], v[152:155], v[192:195], v[54:57]
	v_mfma_f32_16x16x32_bf16 v[46:49], v[160:163], v[192:195], v[46:49]
	v_mfma_f32_16x16x32_bf16 v[38:41], v[152:155], v[206:209], v[38:41]
	v_mfma_f32_16x16x32_bf16 v[30:33], v[160:163], v[206:209], v[30:33]
	v_mfma_f32_16x16x32_bf16 v[22:25], v[152:155], v[220:223], v[22:25]
	v_mfma_f32_16x16x32_bf16 v[14:17], v[160:163], v[220:223], v[14:17]
	v_mfma_f32_16x16x32_bf16 v[62:65], v[156:159], v[188:191], v[62:65]
	v_mfma_f32_16x16x32_bf16 v[58:61], v[164:167], v[188:191], v[58:61]
	v_mfma_f32_16x16x32_bf16 v[54:57], v[156:159], v[196:199], v[54:57]
	v_mfma_f32_16x16x32_bf16 v[46:49], v[164:167], v[196:199], v[46:49]
	v_mfma_f32_16x16x32_bf16 v[38:41], v[156:159], v[212:215], v[38:41]
	v_mfma_f32_16x16x32_bf16 v[30:33], v[164:167], v[212:215], v[30:33]
	v_mfma_f32_16x16x32_bf16 v[22:25], v[156:159], v[224:227], v[22:25]
	v_mfma_f32_16x16x32_bf16 v[14:17], v[164:167], v[224:227], v[14:17]
	v_mfma_f32_16x16x32_bf16 v[50:53], v[168:171], v[184:187], v[50:53]
	v_mfma_f32_16x16x32_bf16 v[42:45], v[176:179], v[184:187], v[42:45]
	v_mfma_f32_16x16x32_bf16 v[34:37], v[168:171], v[192:195], v[34:37]
	v_mfma_f32_16x16x32_bf16 v[26:29], v[176:179], v[192:195], v[26:29]
	v_mfma_f32_16x16x32_bf16 v[18:21], v[168:171], v[206:209], v[18:21]
	v_mfma_f32_16x16x32_bf16 v[10:13], v[176:179], v[206:209], v[10:13]
	v_mfma_f32_16x16x32_bf16 v[6:9], v[168:171], v[220:223], v[6:9]
	v_mfma_f32_16x16x32_bf16 v[2:5], v[176:179], v[220:223], v[2:5]
	v_mfma_f32_16x16x32_bf16 v[50:53], v[172:175], v[188:191], v[50:53]
	v_mfma_f32_16x16x32_bf16 v[42:45], v[180:183], v[188:191], v[42:45]
	v_mfma_f32_16x16x32_bf16 v[34:37], v[172:175], v[196:199], v[34:37]
	v_mfma_f32_16x16x32_bf16 v[26:29], v[180:183], v[196:199], v[26:29]
	v_mfma_f32_16x16x32_bf16 v[18:21], v[172:175], v[212:215], v[18:21]
	v_mfma_f32_16x16x32_bf16 v[10:13], v[180:183], v[212:215], v[10:13]
	v_mfma_f32_16x16x32_bf16 v[6:9], v[172:175], v[224:227], v[6:9]
	v_mfma_f32_16x16x32_bf16 v[2:5], v[180:183], v[224:227], v[2:5]
	s_barrier
	s_setprio 0
	ds_read_b128 v[152:155], v150
	ds_read_b128 v[156:159], v150 offset:1024
	ds_read_b128 v[160:163], v150 offset:2048
	ds_read_b128 v[164:167], v150 offset:3072
	ds_read_b128 v[168:171], v151
	ds_read_b128 v[172:175], v151 offset:1024
	ds_read_b128 v[176:179], v151 offset:2048
	ds_read_b128 v[180:183], v151 offset:3072
	s_add_u32 s22, s22, 0x4000
	s_addc_u32 s23, s23, 0
	s_mov_b32 m0, s25
	ds_read_b128 v[184:187], v149 offset:32768
	ds_read_b128 v[188:191], v149 offset:33792
	ds_read_b128 v[192:195], v149 offset:34816
	ds_read_b128 v[196:199], v149 offset:35840
	ds_read_b128 v[206:209], v149 offset:36864
	ds_read_b128 v[212:215], v149 offset:37888
	ds_read_b128 v[220:223], v149 offset:38912
	ds_read_b128 v[224:227], v149 offset:39936
	global_load_lds_dwordx4 v136, s[22:23]
	s_mov_b32 m0, s26
	s_nop 0
	global_load_lds_dwordx4 v132, s[22:23]
	s_waitcnt vmcnt(8)
	s_waitcnt lgkmcnt(0)
	s_setprio 1
	s_barrier
	v_mfma_f32_16x16x32_bf16 v[126:129], v[152:155], v[184:187], v[126:129]
	v_mfma_f32_16x16x32_bf16 v[122:125], v[160:163], v[184:187], v[122:125]
	v_mfma_f32_16x16x32_bf16 v[118:121], v[152:155], v[192:195], v[118:121]
	v_mfma_f32_16x16x32_bf16 v[110:113], v[160:163], v[192:195], v[110:113]
	v_mfma_f32_16x16x32_bf16 v[102:105], v[152:155], v[206:209], v[102:105]
	v_mfma_f32_16x16x32_bf16 v[94:97], v[160:163], v[206:209], v[94:97]
	v_mfma_f32_16x16x32_bf16 v[86:89], v[152:155], v[220:223], v[86:89]
	v_mfma_f32_16x16x32_bf16 v[78:81], v[160:163], v[220:223], v[78:81]
	v_mfma_f32_16x16x32_bf16 v[126:129], v[156:159], v[188:191], v[126:129]
	v_mfma_f32_16x16x32_bf16 v[122:125], v[164:167], v[188:191], v[122:125]
	v_mfma_f32_16x16x32_bf16 v[118:121], v[156:159], v[196:199], v[118:121]
	v_mfma_f32_16x16x32_bf16 v[110:113], v[164:167], v[196:199], v[110:113]
	v_mfma_f32_16x16x32_bf16 v[102:105], v[156:159], v[212:215], v[102:105]
	v_mfma_f32_16x16x32_bf16 v[94:97], v[164:167], v[212:215], v[94:97]
	v_mfma_f32_16x16x32_bf16 v[86:89], v[156:159], v[224:227], v[86:89]
	v_mfma_f32_16x16x32_bf16 v[78:81], v[164:167], v[224:227], v[78:81]
	v_mfma_f32_16x16x32_bf16 v[114:117], v[168:171], v[184:187], v[114:117]
	v_mfma_f32_16x16x32_bf16 v[106:109], v[176:179], v[184:187], v[106:109]
	v_mfma_f32_16x16x32_bf16 v[98:101], v[168:171], v[192:195], v[98:101]
	v_mfma_f32_16x16x32_bf16 v[90:93], v[176:179], v[192:195], v[90:93]
	v_mfma_f32_16x16x32_bf16 v[82:85], v[168:171], v[206:209], v[82:85]
	v_mfma_f32_16x16x32_bf16 v[74:77], v[176:179], v[206:209], v[74:77]
	v_mfma_f32_16x16x32_bf16 v[70:73], v[168:171], v[220:223], v[70:73]
	v_mfma_f32_16x16x32_bf16 v[66:69], v[176:179], v[220:223], v[66:69]
	v_mfma_f32_16x16x32_bf16 v[114:117], v[172:175], v[188:191], v[114:117]
	v_mfma_f32_16x16x32_bf16 v[106:109], v[180:183], v[188:191], v[106:109]
	v_mfma_f32_16x16x32_bf16 v[98:101], v[172:175], v[196:199], v[98:101]
	v_mfma_f32_16x16x32_bf16 v[90:93], v[180:183], v[196:199], v[90:93]
	v_mfma_f32_16x16x32_bf16 v[82:85], v[172:175], v[212:215], v[82:85]
	v_mfma_f32_16x16x32_bf16 v[74:77], v[180:183], v[212:215], v[74:77]
	v_mfma_f32_16x16x32_bf16 v[70:73], v[172:175], v[224:227], v[70:73]
	v_mfma_f32_16x16x32_bf16 v[66:69], v[180:183], v[224:227], v[66:69]
	s_barrier
	s_setprio 0
	s_add_u32 s22, s20, 0x20000
	s_addc_u32 s23, s21, 0
	s_mov_b32 m0, s40
	s_add_u32 s20, s20, 0x24000
	ds_read_b128 v[184:187], v149 offset:49152
	ds_read_b128 v[188:191], v149 offset:50176
	ds_read_b128 v[192:195], v149 offset:51200
	ds_read_b128 v[196:199], v149 offset:52224
	ds_read_b128 v[206:209], v149 offset:53248
	ds_read_b128 v[212:215], v149 offset:54272
	ds_read_b128 v[220:223], v149 offset:55296
	ds_read_b128 v[224:227], v149 offset:56320
	global_load_lds_dwordx4 v134, s[22:23]
	s_mov_b32 m0, s41
	s_addc_u32 s21, s21, 0
	global_load_lds_dwordx4 v130, s[22:23]
	s_mov_b32 m0, s42
	s_nop 0
	global_load_lds_dwordx4 v134, s[20:21]
	s_mov_b32 m0, s43
	s_nop 0
	global_load_lds_dwordx4 v130, s[20:21]
	s_mov_b32 m0, s29
	s_nop 0
	global_load_lds_dwordx4 v136, s[18:19]
	s_mov_b32 m0, s30
	s_nop 0
	global_load_lds_dwordx4 v132, s[18:19]
	s_waitcnt vmcnt(8)
	s_waitcnt lgkmcnt(0)
	s_setprio 1
	s_barrier
	v_mfma_f32_16x16x32_bf16 v[62:65], v[152:155], v[184:187], v[62:65]
	v_mfma_f32_16x16x32_bf16 v[58:61], v[160:163], v[184:187], v[58:61]
	v_mfma_f32_16x16x32_bf16 v[54:57], v[152:155], v[192:195], v[54:57]
	v_mfma_f32_16x16x32_bf16 v[46:49], v[160:163], v[192:195], v[46:49]
	v_mfma_f32_16x16x32_bf16 v[38:41], v[152:155], v[206:209], v[38:41]
	v_mfma_f32_16x16x32_bf16 v[30:33], v[160:163], v[206:209], v[30:33]
	v_mfma_f32_16x16x32_bf16 v[22:25], v[152:155], v[220:223], v[22:25]
	v_mfma_f32_16x16x32_bf16 v[14:17], v[160:163], v[220:223], v[14:17]
	v_mfma_f32_16x16x32_bf16 v[62:65], v[156:159], v[188:191], v[62:65]
	v_mfma_f32_16x16x32_bf16 v[58:61], v[164:167], v[188:191], v[58:61]
	v_mfma_f32_16x16x32_bf16 v[54:57], v[156:159], v[196:199], v[54:57]
	v_mfma_f32_16x16x32_bf16 v[46:49], v[164:167], v[196:199], v[46:49]
	v_mfma_f32_16x16x32_bf16 v[38:41], v[156:159], v[212:215], v[38:41]
	v_mfma_f32_16x16x32_bf16 v[30:33], v[164:167], v[212:215], v[30:33]
	v_mfma_f32_16x16x32_bf16 v[22:25], v[156:159], v[224:227], v[22:25]
	v_mfma_f32_16x16x32_bf16 v[14:17], v[164:167], v[224:227], v[14:17]
	v_mfma_f32_16x16x32_bf16 v[50:53], v[168:171], v[184:187], v[50:53]
	v_mfma_f32_16x16x32_bf16 v[42:45], v[176:179], v[184:187], v[42:45]
	v_mfma_f32_16x16x32_bf16 v[34:37], v[168:171], v[192:195], v[34:37]
	v_mfma_f32_16x16x32_bf16 v[26:29], v[176:179], v[192:195], v[26:29]
	v_mfma_f32_16x16x32_bf16 v[18:21], v[168:171], v[206:209], v[18:21]
	v_mfma_f32_16x16x32_bf16 v[10:13], v[176:179], v[206:209], v[10:13]
	v_mfma_f32_16x16x32_bf16 v[6:9], v[168:171], v[220:223], v[6:9]
	v_mfma_f32_16x16x32_bf16 v[2:5], v[176:179], v[220:223], v[2:5]
	v_mfma_f32_16x16x32_bf16 v[50:53], v[172:175], v[188:191], v[50:53]
	v_mfma_f32_16x16x32_bf16 v[42:45], v[180:183], v[188:191], v[42:45]
	v_mfma_f32_16x16x32_bf16 v[34:37], v[172:175], v[196:199], v[34:37]
	v_mfma_f32_16x16x32_bf16 v[26:29], v[180:183], v[196:199], v[26:29]
	v_mfma_f32_16x16x32_bf16 v[18:21], v[172:175], v[212:215], v[18:21]
	v_mfma_f32_16x16x32_bf16 v[10:13], v[180:183], v[212:215], v[10:13]
	v_mfma_f32_16x16x32_bf16 v[6:9], v[172:175], v[224:227], v[6:9]
	v_mfma_f32_16x16x32_bf16 v[2:5], v[180:183], v[224:227], v[2:5]
	s_barrier
	s_setprio 0
	s_add_i32 s50, s50, 2
	s_add_u32 s48, s48, 0x40000
	s_addc_u32 s49, s49, 0
	s_add_u32 s16, s16, 0x10000
	s_addc_u32 s17, s17, 0
	s_cmp_gt_u32 s50, 61
	s_cbranch_scc0 .LBB0_1718
	v_mov_b32_e32 v138, v146
	s_lshl_b32 s16, s45, 8
	v_and_or_b32 v152, v138, 15, s27
	v_lshrrev_b32_e32 v138, 1, v138
	v_and_or_b32 v138, v138, 24, s16
	v_ashrrev_i32_e32 v153, 31, v152
	v_or_b32_e32 v138, s28, v138
	v_lshlrev_b64 v[144:145], 11, v[152:153]
	v_lshl_add_u64 v[144:145], s[8:9], 0, v[144:145]
	v_lshlrev_b64 v[154:155], 1, v[138:139]
	v_lshl_add_u64 v[144:145], v[144:145], 0, v[154:155]
	v_cvt_pk_bf16_f32 v126, v126, v127
	v_cvt_pk_bf16_f32 v127, v128, v129
	v_cvt_pk_bf16_f32 v128, v122, v123
	v_cvt_pk_bf16_f32 v129, v124, v125
	global_store_dwordx4 v[144:145], v[126:129], off
	v_cvt_pk_bf16_f32 v114, v114, v115
	v_cvt_pk_bf16_f32 v115, v116, v117
	v_cvt_pk_bf16_f32 v116, v106, v107
	v_or_b32_e32 v106, 16, v152
	v_ashrrev_i32_e32 v107, 31, v106
	v_lshlrev_b64 v[106:107], 11, v[106:107]
	v_lshl_add_u64 v[106:107], s[8:9], 0, v[106:107]
	v_cvt_pk_bf16_f32 v117, v108, v109
	global_store_dwordx4 v[144:145], v[114:117], off offset:256
	s_mov_b64 s[16:17], 0x40000
	s_cmp_eq_u32 s44, 4
	v_lshl_add_u64 v[114:115], v[106:107], 0, v[154:155]
	v_cvt_pk_bf16_f32 v106, v118, v119
	v_cvt_pk_bf16_f32 v107, v120, v121
	v_cvt_pk_bf16_f32 v108, v110, v111
	v_cvt_pk_bf16_f32 v109, v112, v113
	global_store_dwordx4 v[114:115], v[106:109], off
	v_cvt_pk_bf16_f32 v98, v98, v99
	v_cvt_pk_bf16_f32 v99, v100, v101
	v_cvt_pk_bf16_f32 v100, v90, v91
	v_or_b32_e32 v90, 32, v152
	v_ashrrev_i32_e32 v91, 31, v90
	v_lshlrev_b64 v[90:91], 11, v[90:91]
	v_lshl_add_u64 v[90:91], s[8:9], 0, v[90:91]
	v_cvt_pk_bf16_f32 v101, v92, v93
	global_store_dwordx4 v[114:115], v[98:101], off offset:256
	s_mov_b32 s45, s44
	s_nop 0
	v_lshl_add_u64 v[98:99], v[90:91], 0, v[154:155]
	v_cvt_pk_bf16_f32 v90, v102, v103
	v_cvt_pk_bf16_f32 v91, v104, v105
	v_cvt_pk_bf16_f32 v92, v94, v95
	v_cvt_pk_bf16_f32 v93, v96, v97
	global_store_dwordx4 v[98:99], v[90:93], off
	v_cvt_pk_bf16_f32 v82, v82, v83
	v_cvt_pk_bf16_f32 v83, v84, v85
	v_cvt_pk_bf16_f32 v84, v74, v75
	v_or_b32_e32 v74, 48, v152
	v_ashrrev_i32_e32 v75, 31, v74
	v_lshlrev_b64 v[74:75], 11, v[74:75]
	v_lshl_add_u64 v[74:75], s[8:9], 0, v[74:75]
	v_cvt_pk_bf16_f32 v85, v76, v77
	global_store_dwordx4 v[98:99], v[82:85], off offset:256
	s_nop 1
	v_lshl_add_u64 v[82:83], v[74:75], 0, v[154:155]
	v_cvt_pk_bf16_f32 v74, v86, v87
	v_cvt_pk_bf16_f32 v75, v88, v89
	v_cvt_pk_bf16_f32 v76, v78, v79
	v_cvt_pk_bf16_f32 v77, v80, v81
	global_store_dwordx4 v[82:83], v[74:77], off
	v_cvt_pk_bf16_f32 v70, v70, v71
	v_cvt_pk_bf16_f32 v71, v72, v73
	v_cvt_pk_bf16_f32 v72, v66, v67
	v_lshl_add_u64 v[66:67], v[144:145], 0, s[16:17]
	s_mov_b32 s16, 0x40000
	v_cvt_pk_bf16_f32 v73, v68, v69
	global_store_dwordx4 v[82:83], v[70:73], off offset:256
	v_cvt_pk_bf16_f32 v62, v62, v63
	v_cvt_pk_bf16_f32 v63, v64, v65
	v_cvt_pk_bf16_f32 v64, v58, v59
	v_add_co_u32_e32 v58, vcc, s16, v144
	v_cvt_pk_bf16_f32 v65, v60, v61
	s_mov_b64 s[16:17], 0x48000
	s_nop 0
	v_addc_co_u32_e32 v59, vcc, 0, v145, vcc
	global_store_dwordx4 v[58:59], v[62:65], off
	v_cvt_pk_bf16_f32 v50, v50, v51
	v_cvt_pk_bf16_f32 v51, v52, v53
	v_cvt_pk_bf16_f32 v52, v42, v43
	v_cvt_pk_bf16_f32 v53, v44, v45
	global_store_dwordx4 v[66:67], v[50:53], off offset:256
	v_cvt_pk_bf16_f32 v42, v54, v55
	v_cvt_pk_bf16_f32 v43, v56, v57
	v_cvt_pk_bf16_f32 v44, v46, v47
	v_cvt_pk_bf16_f32 v45, v48, v49
	s_nop 1
	v_lshl_add_u64 v[50:51], v[144:145], 0, s[16:17]
	s_mov_b32 s16, 0x48000
	v_add_co_u32_e32 v46, vcc, s16, v144
	s_mov_b64 s[16:17], s[10:11]
	s_nop 0
	v_addc_co_u32_e32 v47, vcc, 0, v145, vcc
	global_store_dwordx4 v[46:47], v[42:45], off
	v_cvt_pk_bf16_f32 v34, v34, v35
	v_cvt_pk_bf16_f32 v35, v36, v37
	v_cvt_pk_bf16_f32 v36, v26, v27
	v_cvt_pk_bf16_f32 v37, v28, v29
	global_store_dwordx4 v[50:51], v[34:37], off offset:256
	v_cvt_pk_bf16_f32 v26, v38, v39
	v_cvt_pk_bf16_f32 v27, v40, v41
	v_cvt_pk_bf16_f32 v28, v30, v31
	v_add_co_u32_e32 v30, vcc, s34, v144
	s_nop 0
	v_lshl_add_u64 v[34:35], v[144:145], 0, s[4:5]
	v_addc_co_u32_e32 v31, vcc, 0, v145, vcc
	v_cvt_pk_bf16_f32 v29, v32, v33
	global_store_dwordx4 v[30:31], v[26:29], off
	v_cvt_pk_bf16_f32 v18, v18, v19
	v_cvt_pk_bf16_f32 v19, v20, v21
	v_cvt_pk_bf16_f32 v20, v10, v11
	v_cvt_pk_bf16_f32 v21, v12, v13
	global_store_dwordx4 v[34:35], v[18:21], off offset:256
	v_cvt_pk_bf16_f32 v10, v22, v23
	v_cvt_pk_bf16_f32 v11, v24, v25
	v_cvt_pk_bf16_f32 v12, v14, v15
	v_add_co_u32_e32 v14, vcc, s35, v144
	s_nop 0
	v_lshl_add_u64 v[18:19], v[144:145], 0, s[6:7]
	v_addc_co_u32_e32 v15, vcc, 0, v145, vcc
	v_cvt_pk_bf16_f32 v13, v16, v17
	global_store_dwordx4 v[14:15], v[10:13], off
	v_cvt_pk_bf16_f32 v6, v6, v7
	v_cvt_pk_bf16_f32 v7, v8, v9
	v_cvt_pk_bf16_f32 v8, v2, v3
	v_cvt_pk_bf16_f32 v9, v4, v5
	global_store_dwordx4 v[18:19], v[6:9], off offset:256
	s_cbranch_scc0 .LBB0_1717
	s_waitcnt vmcnt(0)
	s_cmpk_gt_u32 s0, 0xff
	s_cbranch_scc1 .LBB0_1722
	s_barrier

.LBB0_2185:
	ds_read_b128 v[146:149], v152
	ds_read_b128 v[156:159], v152 offset:1024
	ds_read_b128 v[160:163], v152 offset:2048
	ds_read_b128 v[164:167], v152 offset:3072
	ds_read_b128 v[168:171], v153
	ds_read_b128 v[172:175], v153 offset:1024
	ds_read_b128 v[176:179], v153 offset:2048
	ds_read_b128 v[180:183], v153 offset:3072
	s_add_u32 s22, s20, 0xfc000
	s_addc_u32 s23, s21, 0
	s_cmp_eq_u32 s44, 4
	s_cselect_b32 s26, s15, s22
	s_cselect_b32 s27, s5, s23
	s_cselect_b32 s24, s41, s42
	s_cselect_b32 s25, s13, s43
	s_add_u32 s22, s26, 0x100000
	s_addc_u32 s23, s27, 0
	s_add_i32 m0, s1, 0xc000
	ds_read_b128 v[184:187], v154
	ds_read_b128 v[188:191], v154 offset:1024
	ds_read_b128 v[192:195], v154 offset:2048
	ds_read_b128 v[196:199], v154 offset:3072
	ds_read_b128 v[206:209], v154 offset:4096
	ds_read_b128 v[212:215], v154 offset:5120
	ds_read_b128 v[220:223], v154 offset:6144
	ds_read_b128 v[224:227], v154 offset:7168
	global_load_lds_dwordx4 v138, s[20:21]
	s_add_i32 m0, s1, 0xe000
	s_nop 0
	global_load_lds_dwordx4 v140, s[20:21]
	s_waitcnt vmcnt(8)
	s_waitcnt lgkmcnt(0)
	s_setprio 1
	s_barrier
	v_mfma_f32_16x16x32_bf16 v[126:129], v[146:149], v[184:187], v[126:129]
	v_mfma_f32_16x16x32_bf16 v[122:125], v[160:163], v[184:187], v[122:125]
	v_mfma_f32_16x16x32_bf16 v[110:113], v[146:149], v[192:195], v[110:113]
	v_mfma_f32_16x16x32_bf16 v[106:109], v[160:163], v[192:195], v[106:109]
	v_mfma_f32_16x16x32_bf16 v[94:97], v[146:149], v[206:209], v[94:97]
	v_mfma_f32_16x16x32_bf16 v[90:93], v[160:163], v[206:209], v[90:93]
	v_mfma_f32_16x16x32_bf16 v[78:81], v[146:149], v[220:223], v[78:81]
	v_mfma_f32_16x16x32_bf16 v[74:77], v[160:163], v[220:223], v[74:77]
	v_mfma_f32_16x16x32_bf16 v[126:129], v[156:159], v[188:191], v[126:129]
	v_mfma_f32_16x16x32_bf16 v[122:125], v[164:167], v[188:191], v[122:125]
	v_mfma_f32_16x16x32_bf16 v[110:113], v[156:159], v[196:199], v[110:113]
	v_mfma_f32_16x16x32_bf16 v[106:109], v[164:167], v[196:199], v[106:109]
	v_mfma_f32_16x16x32_bf16 v[94:97], v[156:159], v[212:215], v[94:97]
	v_mfma_f32_16x16x32_bf16 v[90:93], v[164:167], v[212:215], v[90:93]
	v_mfma_f32_16x16x32_bf16 v[78:81], v[156:159], v[224:227], v[78:81]
	v_mfma_f32_16x16x32_bf16 v[74:77], v[164:167], v[224:227], v[74:77]
	v_mfma_f32_16x16x32_bf16 v[118:121], v[168:171], v[184:187], v[118:121]
	v_mfma_f32_16x16x32_bf16 v[114:117], v[176:179], v[184:187], v[114:117]
	v_mfma_f32_16x16x32_bf16 v[102:105], v[168:171], v[192:195], v[102:105]
	v_mfma_f32_16x16x32_bf16 v[98:101], v[176:179], v[192:195], v[98:101]
	v_mfma_f32_16x16x32_bf16 v[86:89], v[168:171], v[206:209], v[86:89]
	v_mfma_f32_16x16x32_bf16 v[82:85], v[176:179], v[206:209], v[82:85]
	v_mfma_f32_16x16x32_bf16 v[70:73], v[168:171], v[220:223], v[70:73]
	v_mfma_f32_16x16x32_bf16 v[66:69], v[176:179], v[220:223], v[66:69]
	v_mfma_f32_16x16x32_bf16 v[118:121], v[172:175], v[188:191], v[118:121]
	v_mfma_f32_16x16x32_bf16 v[114:117], v[180:183], v[188:191], v[114:117]
	v_mfma_f32_16x16x32_bf16 v[102:105], v[172:175], v[196:199], v[102:105]
	v_mfma_f32_16x16x32_bf16 v[98:101], v[180:183], v[196:199], v[98:101]
	v_mfma_f32_16x16x32_bf16 v[86:89], v[172:175], v[212:215], v[86:89]
	v_mfma_f32_16x16x32_bf16 v[82:85], v[180:183], v[212:215], v[82:85]
	v_mfma_f32_16x16x32_bf16 v[70:73], v[172:175], v[224:227], v[70:73]
	v_mfma_f32_16x16x32_bf16 v[66:69], v[180:183], v[224:227], v[66:69]
	s_barrier
	s_setprio 0
	s_add_i32 s45, s38, s0
	s_mov_b32 m0, s45
	ds_read_b128 v[184:187], v154 offset:16384
	ds_read_b128 v[188:191], v154 offset:17408
	ds_read_b128 v[192:195], v154 offset:18432
	ds_read_b128 v[196:199], v154 offset:19456
	ds_read_b128 v[206:209], v154 offset:20480
	ds_read_b128 v[212:215], v154 offset:21504
	ds_read_b128 v[220:223], v154 offset:22528
	ds_read_b128 v[224:227], v154 offset:23552
	global_load_lds_dwordx4 v132, s[24:25]
	s_add_i32 m0, s45, 0x2000
	s_add_u32 s46, s24, 0x4000
	s_addc_u32 s47, s25, 0
	s_add_i32 s45, s39, s0
	global_load_lds_dwordx4 v136, s[24:25]
	s_mov_b32 m0, s45
	s_nop 0
	global_load_lds_dwordx4 v132, s[46:47]
	s_add_i32 m0, s45, 0x2000
	s_nop 0
	global_load_lds_dwordx4 v136, s[46:47]
	s_mov_b32 m0, s1
	s_nop 0
	global_load_lds_dwordx4 v130, s[26:27]
	s_mov_b32 m0, s28
	s_nop 0
	global_load_lds_dwordx4 v134, s[26:27]
	s_waitcnt vmcnt(8)
	s_waitcnt lgkmcnt(0)
	s_setprio 1
	s_barrier
	v_mfma_f32_16x16x32_bf16 v[62:65], v[146:149], v[184:187], v[62:65]
	v_mfma_f32_16x16x32_bf16 v[58:61], v[160:163], v[184:187], v[58:61]
	v_mfma_f32_16x16x32_bf16 v[46:49], v[146:149], v[192:195], v[46:49]
	v_mfma_f32_16x16x32_bf16 v[42:45], v[160:163], v[192:195], v[42:45]
	v_mfma_f32_16x16x32_bf16 v[30:33], v[146:149], v[206:209], v[30:33]
	v_mfma_f32_16x16x32_bf16 v[26:29], v[160:163], v[206:209], v[26:29]
	v_mfma_f32_16x16x32_bf16 v[14:17], v[146:149], v[220:223], v[14:17]
	v_mfma_f32_16x16x32_bf16 v[10:13], v[160:163], v[220:223], v[10:13]
	v_mfma_f32_16x16x32_bf16 v[62:65], v[156:159], v[188:191], v[62:65]
	v_mfma_f32_16x16x32_bf16 v[58:61], v[164:167], v[188:191], v[58:61]
	v_mfma_f32_16x16x32_bf16 v[46:49], v[156:159], v[196:199], v[46:49]
	v_mfma_f32_16x16x32_bf16 v[42:45], v[164:167], v[196:199], v[42:45]
	v_mfma_f32_16x16x32_bf16 v[30:33], v[156:159], v[212:215], v[30:33]
	v_mfma_f32_16x16x32_bf16 v[26:29], v[164:167], v[212:215], v[26:29]
	v_mfma_f32_16x16x32_bf16 v[14:17], v[156:159], v[224:227], v[14:17]
	v_mfma_f32_16x16x32_bf16 v[10:13], v[164:167], v[224:227], v[10:13]
	v_mfma_f32_16x16x32_bf16 v[54:57], v[168:171], v[184:187], v[54:57]
	v_mfma_f32_16x16x32_bf16 v[50:53], v[176:179], v[184:187], v[50:53]
	v_mfma_f32_16x16x32_bf16 v[38:41], v[168:171], v[192:195], v[38:41]
	v_mfma_f32_16x16x32_bf16 v[34:37], v[176:179], v[192:195], v[34:37]
	v_mfma_f32_16x16x32_bf16 v[22:25], v[168:171], v[206:209], v[22:25]
	v_mfma_f32_16x16x32_bf16 v[18:21], v[176:179], v[206:209], v[18:21]
	v_mfma_f32_16x16x32_bf16 v[6:9], v[168:171], v[220:223], v[6:9]
	v_mfma_f32_16x16x32_bf16 v[2:5], v[176:179], v[220:223], v[2:5]
	v_mfma_f32_16x16x32_bf16 v[54:57], v[172:175], v[188:191], v[54:57]
	v_mfma_f32_16x16x32_bf16 v[50:53], v[180:183], v[188:191], v[50:53]
	v_mfma_f32_16x16x32_bf16 v[38:41], v[172:175], v[196:199], v[38:41]
	v_mfma_f32_16x16x32_bf16 v[34:37], v[180:183], v[196:199], v[34:37]
	v_mfma_f32_16x16x32_bf16 v[22:25], v[172:175], v[212:215], v[22:25]
	v_mfma_f32_16x16x32_bf16 v[18:21], v[180:183], v[212:215], v[18:21]
	v_mfma_f32_16x16x32_bf16 v[6:9], v[172:175], v[224:227], v[6:9]
	v_mfma_f32_16x16x32_bf16 v[2:5], v[180:183], v[224:227], v[2:5]
	s_barrier
	s_setprio 0
	s_add_i32 s45, 0, 0x18000
	v_add_u32_e32 v155, s45, v151
	s_add_i32 s46, 0, 0x1c000
	ds_read_b128 v[146:149], v155
	ds_read_b128 v[156:159], v155 offset:1024
	ds_read_b128 v[160:163], v155 offset:2048
	ds_read_b128 v[164:167], v155 offset:3072
	v_add_u32_e32 v155, s46, v151
	ds_read_b128 v[168:171], v155
	ds_read_b128 v[172:175], v155 offset:1024
	ds_read_b128 v[176:179], v155 offset:2048
	ds_read_b128 v[180:183], v155 offset:3072
	s_add_u32 s26, s26, 0x4000
	s_addc_u32 s27, s27, 0
	s_mov_b32 m0, s29
	ds_read_b128 v[184:187], v154 offset:32768
	ds_read_b128 v[188:191], v154 offset:33792
	ds_read_b128 v[192:195], v154 offset:34816
	ds_read_b128 v[196:199], v154 offset:35840
	ds_read_b128 v[206:209], v154 offset:36864
	ds_read_b128 v[212:215], v154 offset:37888
	ds_read_b128 v[220:223], v154 offset:38912
	ds_read_b128 v[224:227], v154 offset:39936
	global_load_lds_dwordx4 v130, s[26:27]
	s_mov_b32 m0, s30
	s_nop 0
	global_load_lds_dwordx4 v134, s[26:27]
	s_waitcnt vmcnt(8)
	s_waitcnt lgkmcnt(0)
	s_setprio 1
	s_barrier
	v_mfma_f32_16x16x32_bf16 v[126:129], v[146:149], v[184:187], v[126:129]
	v_mfma_f32_16x16x32_bf16 v[122:125], v[160:163], v[184:187], v[122:125]
	v_mfma_f32_16x16x32_bf16 v[110:113], v[146:149], v[192:195], v[110:113]
	v_mfma_f32_16x16x32_bf16 v[106:109], v[160:163], v[192:195], v[106:109]
	v_mfma_f32_16x16x32_bf16 v[94:97], v[146:149], v[206:209], v[94:97]
	v_mfma_f32_16x16x32_bf16 v[90:93], v[160:163], v[206:209], v[90:93]
	v_mfma_f32_16x16x32_bf16 v[78:81], v[146:149], v[220:223], v[78:81]
	v_mfma_f32_16x16x32_bf16 v[74:77], v[160:163], v[220:223], v[74:77]
	v_mfma_f32_16x16x32_bf16 v[126:129], v[156:159], v[188:191], v[126:129]
	v_mfma_f32_16x16x32_bf16 v[122:125], v[164:167], v[188:191], v[122:125]
	v_mfma_f32_16x16x32_bf16 v[110:113], v[156:159], v[196:199], v[110:113]
	v_mfma_f32_16x16x32_bf16 v[106:109], v[164:167], v[196:199], v[106:109]
	v_mfma_f32_16x16x32_bf16 v[94:97], v[156:159], v[212:215], v[94:97]
	v_mfma_f32_16x16x32_bf16 v[90:93], v[164:167], v[212:215], v[90:93]
	v_mfma_f32_16x16x32_bf16 v[78:81], v[156:159], v[224:227], v[78:81]
	v_mfma_f32_16x16x32_bf16 v[74:77], v[164:167], v[224:227], v[74:77]
	v_mfma_f32_16x16x32_bf16 v[118:121], v[168:171], v[184:187], v[118:121]
	v_mfma_f32_16x16x32_bf16 v[114:117], v[176:179], v[184:187], v[114:117]
	v_mfma_f32_16x16x32_bf16 v[102:105], v[168:171], v[192:195], v[102:105]
	v_mfma_f32_16x16x32_bf16 v[98:101], v[176:179], v[192:195], v[98:101]
	v_mfma_f32_16x16x32_bf16 v[86:89], v[168:171], v[206:209], v[86:89]
	v_mfma_f32_16x16x32_bf16 v[82:85], v[176:179], v[206:209], v[82:85]
	v_mfma_f32_16x16x32_bf16 v[70:73], v[168:171], v[220:223], v[70:73]
	v_mfma_f32_16x16x32_bf16 v[66:69], v[176:179], v[220:223], v[66:69]
	v_mfma_f32_16x16x32_bf16 v[118:121], v[172:175], v[188:191], v[118:121]
	v_mfma_f32_16x16x32_bf16 v[114:117], v[180:183], v[188:191], v[114:117]
	v_mfma_f32_16x16x32_bf16 v[102:105], v[172:175], v[196:199], v[102:105]
	v_mfma_f32_16x16x32_bf16 v[98:101], v[180:183], v[196:199], v[98:101]
	v_mfma_f32_16x16x32_bf16 v[86:89], v[172:175], v[212:215], v[86:89]
	v_mfma_f32_16x16x32_bf16 v[82:85], v[180:183], v[212:215], v[82:85]
	v_mfma_f32_16x16x32_bf16 v[70:73], v[172:175], v[224:227], v[70:73]
	v_mfma_f32_16x16x32_bf16 v[66:69], v[180:183], v[224:227], v[66:69]
	s_barrier
	s_setprio 0
	s_add_u32 s26, s24, 0x80000
	s_addc_u32 s27, s25, 0
	s_add_i32 s45, s45, s0
	s_mov_b32 m0, s45
	ds_read_b128 v[184:187], v154 offset:49152
	ds_read_b128 v[188:191], v154 offset:50176
	ds_read_b128 v[192:195], v154 offset:51200
	ds_read_b128 v[196:199], v154 offset:52224
	ds_read_b128 v[206:209], v154 offset:53248
	ds_read_b128 v[212:215], v154 offset:54272
	ds_read_b128 v[220:223], v154 offset:55296
	ds_read_b128 v[224:227], v154 offset:56320
	global_load_lds_dwordx4 v132, s[26:27]
	s_add_i32 m0, s45, 0x2000
	s_add_u32 s24, s24, 0x84000
	s_addc_u32 s25, s25, 0
	global_load_lds_dwordx4 v136, s[26:27]
	s_add_i32 s26, s46, s0
	s_mov_b32 m0, s26
	s_nop 0
	global_load_lds_dwordx4 v132, s[24:25]
	s_add_i32 m0, s26, 0x2000
	s_nop 0
	global_load_lds_dwordx4 v136, s[24:25]
	s_mov_b32 m0, s36
	s_nop 0
	global_load_lds_dwordx4 v130, s[22:23]
	s_mov_b32 m0, s37
	s_nop 0
	global_load_lds_dwordx4 v134, s[22:23]
	s_waitcnt vmcnt(8)
	s_waitcnt lgkmcnt(0)
	s_setprio 1
	s_barrier
	v_mfma_f32_16x16x32_bf16 v[62:65], v[146:149], v[184:187], v[62:65]
	v_mfma_f32_16x16x32_bf16 v[58:61], v[160:163], v[184:187], v[58:61]
	v_mfma_f32_16x16x32_bf16 v[46:49], v[146:149], v[192:195], v[46:49]
	v_mfma_f32_16x16x32_bf16 v[42:45], v[160:163], v[192:195], v[42:45]
	v_mfma_f32_16x16x32_bf16 v[30:33], v[146:149], v[206:209], v[30:33]
	v_mfma_f32_16x16x32_bf16 v[26:29], v[160:163], v[206:209], v[26:29]
	v_mfma_f32_16x16x32_bf16 v[14:17], v[146:149], v[220:223], v[14:17]
	v_mfma_f32_16x16x32_bf16 v[10:13], v[160:163], v[220:223], v[10:13]
	v_mfma_f32_16x16x32_bf16 v[62:65], v[156:159], v[188:191], v[62:65]
	v_mfma_f32_16x16x32_bf16 v[58:61], v[164:167], v[188:191], v[58:61]
	v_mfma_f32_16x16x32_bf16 v[46:49], v[156:159], v[196:199], v[46:49]
	v_mfma_f32_16x16x32_bf16 v[42:45], v[164:167], v[196:199], v[42:45]
	v_mfma_f32_16x16x32_bf16 v[30:33], v[156:159], v[212:215], v[30:33]
	v_mfma_f32_16x16x32_bf16 v[26:29], v[164:167], v[212:215], v[26:29]
	v_mfma_f32_16x16x32_bf16 v[14:17], v[156:159], v[224:227], v[14:17]
	v_mfma_f32_16x16x32_bf16 v[10:13], v[164:167], v[224:227], v[10:13]
	v_mfma_f32_16x16x32_bf16 v[54:57], v[168:171], v[184:187], v[54:57]
	v_mfma_f32_16x16x32_bf16 v[50:53], v[176:179], v[184:187], v[50:53]
	v_mfma_f32_16x16x32_bf16 v[38:41], v[168:171], v[192:195], v[38:41]
	v_mfma_f32_16x16x32_bf16 v[34:37], v[176:179], v[192:195], v[34:37]
	v_mfma_f32_16x16x32_bf16 v[22:25], v[168:171], v[206:209], v[22:25]
	v_mfma_f32_16x16x32_bf16 v[18:21], v[176:179], v[206:209], v[18:21]
	v_mfma_f32_16x16x32_bf16 v[6:9], v[168:171], v[220:223], v[6:9]
	v_mfma_f32_16x16x32_bf16 v[2:5], v[176:179], v[220:223], v[2:5]
	v_mfma_f32_16x16x32_bf16 v[54:57], v[172:175], v[188:191], v[54:57]
	v_mfma_f32_16x16x32_bf16 v[50:53], v[180:183], v[188:191], v[50:53]
	v_mfma_f32_16x16x32_bf16 v[38:41], v[172:175], v[196:199], v[38:41]
	v_mfma_f32_16x16x32_bf16 v[34:37], v[180:183], v[196:199], v[34:37]
	v_mfma_f32_16x16x32_bf16 v[22:25], v[172:175], v[212:215], v[22:25]
	v_mfma_f32_16x16x32_bf16 v[18:21], v[180:183], v[212:215], v[18:21]
	v_mfma_f32_16x16x32_bf16 v[6:9], v[172:175], v[224:227], v[6:9]
	v_mfma_f32_16x16x32_bf16 v[2:5], v[180:183], v[224:227], v[2:5]
	s_barrier
	s_setprio 0
	s_add_i32 s44, s44, 2
	s_add_u32 s42, s42, 0x100000
	s_addc_u32 s43, s43, 0
	s_add_u32 s20, s20, 0x200000
	s_addc_u32 s21, s21, 0
	s_cmp_gt_u32 s44, 5
	s_cbranch_scc0 .LBB0_2185
	s_and_b64 vcc, exec, s[8:9]
	s_cbranch_vccz .LBB0_2188
	s_barrier

.LBB0_2480:
	ds_read_b128 v[18:21], v182
	ds_read_b128 v[22:25], v182 offset:1024
	ds_read_b128 v[26:29], v182 offset:2048
	ds_read_b128 v[30:33], v182 offset:3072
	ds_read_b128 v[2:5], v183
	ds_read_b128 v[6:9], v183 offset:1024
	ds_read_b128 v[10:13], v183 offset:2048
	ds_read_b128 v[14:17], v183 offset:3072
	s_add_u32 s26, s24, 0xfc000
	s_addc_u32 s27, s25, 0
	s_cmp_eq_u32 s48, 28
	s_cselect_b32 s30, s17, s26
	s_cselect_b32 s31, s5, s27
	s_cselect_b32 s28, s23, s46
	s_cselect_b32 s29, s15, s47
	s_add_u32 s26, s30, 0x100000
	s_addc_u32 s27, s31, 0
	s_add_i32 m0, s34, 0xc000
	ds_read_b128 v[186:189], v184
	ds_read_b128 v[190:193], v184 offset:1024
	ds_read_b128 v[220:223], v184 offset:2048
	ds_read_b128 v[224:227], v184 offset:3072
	ds_read_b128 v[228:231], v184 offset:4096
	ds_read_b128 v[232:235], v184 offset:5120
	ds_read_b128 v[236:239], v184 offset:6144
	ds_read_b128 v[240:243], v184 offset:7168
	global_load_lds_dwordx4 v172, s[24:25]
	s_add_i32 m0, s34, 0xe000
	s_nop 0
	global_load_lds_dwordx4 v174, s[24:25]
	s_waitcnt vmcnt(8)
	s_waitcnt lgkmcnt(0)
	s_setprio 1
	s_barrier
	v_mfma_f32_16x16x128_f8f6f4 v[158:161], v[18:25], v[186:193], v[158:161]
	v_mfma_f32_16x16x128_f8f6f4 v[154:157], v[26:33], v[186:193], v[154:157]
	v_mfma_f32_16x16x128_f8f6f4 v[142:145], v[18:25], v[220:227], v[142:145]
	v_mfma_f32_16x16x128_f8f6f4 v[138:141], v[26:33], v[220:227], v[138:141]
	v_mfma_f32_16x16x128_f8f6f4 v[126:129], v[18:25], v[228:235], v[126:129]
	v_mfma_f32_16x16x128_f8f6f4 v[122:125], v[26:33], v[228:235], v[122:125]
	v_mfma_f32_16x16x128_f8f6f4 v[110:113], v[18:25], v[236:243], v[110:113]
	v_mfma_f32_16x16x128_f8f6f4 v[106:109], v[26:33], v[236:243], v[106:109]
	v_mfma_f32_16x16x128_f8f6f4 v[150:153], v[2:9], v[186:193], v[150:153]
	v_mfma_f32_16x16x128_f8f6f4 v[146:149], v[10:17], v[186:193], v[146:149]
	v_mfma_f32_16x16x128_f8f6f4 v[134:137], v[2:9], v[220:227], v[134:137]
	v_mfma_f32_16x16x128_f8f6f4 v[130:133], v[10:17], v[220:227], v[130:133]
	v_mfma_f32_16x16x128_f8f6f4 v[118:121], v[2:9], v[228:235], v[118:121]
	v_mfma_f32_16x16x128_f8f6f4 v[114:117], v[10:17], v[228:235], v[114:117]
	v_mfma_f32_16x16x128_f8f6f4 v[102:105], v[2:9], v[236:243], v[102:105]
	v_mfma_f32_16x16x128_f8f6f4 v[98:101], v[10:17], v[236:243], v[98:101]
	s_barrier
	s_setprio 0
	s_add_i32 s49, s42, s0
	s_mov_b32 m0, s49
	ds_read_b128 v[186:189], v184 offset:16384
	ds_read_b128 v[190:193], v184 offset:17408
	ds_read_b128 v[220:223], v184 offset:18432
	ds_read_b128 v[224:227], v184 offset:19456
	ds_read_b128 v[228:231], v184 offset:20480
	ds_read_b128 v[232:235], v184 offset:21504
	ds_read_b128 v[236:239], v184 offset:22528
	ds_read_b128 v[240:243], v184 offset:23552
	global_load_lds_dwordx4 v166, s[28:29]
	s_add_i32 m0, s49, 0x2000
	s_add_u32 s50, s28, 0x4000
	s_addc_u32 s51, s29, 0
	s_add_i32 s49, s43, s0
	global_load_lds_dwordx4 v162, s[28:29]
	s_mov_b32 m0, s49
	s_nop 0
	global_load_lds_dwordx4 v166, s[50:51]
	s_add_i32 m0, s49, 0x2000
	s_nop 0
	global_load_lds_dwordx4 v162, s[50:51]
	s_mov_b32 m0, s34
	s_nop 0
	global_load_lds_dwordx4 v168, s[30:31]
	s_mov_b32 m0, s35
	s_nop 0
	global_load_lds_dwordx4 v164, s[30:31]
	s_waitcnt vmcnt(8)
	s_waitcnt lgkmcnt(0)
	s_setprio 1
	s_barrier
	v_mfma_f32_16x16x128_f8f6f4 v[94:97], v[18:25], v[186:193], v[94:97]
	v_mfma_f32_16x16x128_f8f6f4 v[90:93], v[26:33], v[186:193], v[90:93]
	v_mfma_f32_16x16x128_f8f6f4 v[78:81], v[18:25], v[220:227], v[78:81]
	v_mfma_f32_16x16x128_f8f6f4 v[74:77], v[26:33], v[220:227], v[74:77]
	v_mfma_f32_16x16x128_f8f6f4 v[62:65], v[18:25], v[228:235], v[62:65]
	v_mfma_f32_16x16x128_f8f6f4 v[58:61], v[26:33], v[228:235], v[58:61]
	v_mfma_f32_16x16x128_f8f6f4 v[46:49], v[18:25], v[236:243], v[46:49]
	v_mfma_f32_16x16x128_f8f6f4 v[42:45], v[26:33], v[236:243], v[42:45]
	v_mfma_f32_16x16x128_f8f6f4 v[86:89], v[2:9], v[186:193], v[86:89]
	v_mfma_f32_16x16x128_f8f6f4 v[82:85], v[10:17], v[186:193], v[82:85]
	v_mfma_f32_16x16x128_f8f6f4 v[70:73], v[2:9], v[220:227], v[70:73]
	v_mfma_f32_16x16x128_f8f6f4 v[66:69], v[10:17], v[220:227], v[66:69]
	v_mfma_f32_16x16x128_f8f6f4 v[54:57], v[2:9], v[228:235], v[54:57]
	v_mfma_f32_16x16x128_f8f6f4 v[50:53], v[10:17], v[228:235], v[50:53]
	v_mfma_f32_16x16x128_f8f6f4 v[38:41], v[2:9], v[236:243], v[38:41]
	v_mfma_f32_16x16x128_f8f6f4 v[34:37], v[10:17], v[236:243], v[34:37]
	s_barrier
	s_setprio 0
	s_add_i32 s49, 0, 0x18000
	s_add_i32 s50, 0, 0x1c000
	v_add_u32_e32 v14, s49, v181
	v_add_u32_e32 v30, s50, v181
	ds_read_b128 v[2:5], v14
	ds_read_b128 v[6:9], v14 offset:1024
	ds_read_b128 v[10:13], v14 offset:2048
	ds_read_b128 v[14:17], v14 offset:3072
	ds_read_b128 v[18:21], v30
	ds_read_b128 v[22:25], v30 offset:1024
	ds_read_b128 v[26:29], v30 offset:2048
	ds_read_b128 v[30:33], v30 offset:3072
	s_add_u32 s30, s30, 0x4000
	s_addc_u32 s31, s31, 0
	s_mov_b32 m0, s36
	ds_read_b128 v[186:189], v184 offset:32768
	ds_read_b128 v[190:193], v184 offset:33792
	ds_read_b128 v[220:223], v184 offset:34816
	ds_read_b128 v[224:227], v184 offset:35840
	ds_read_b128 v[228:231], v184 offset:36864
	ds_read_b128 v[232:235], v184 offset:37888
	ds_read_b128 v[236:239], v184 offset:38912
	ds_read_b128 v[240:243], v184 offset:39936
	global_load_lds_dwordx4 v168, s[30:31]
	s_mov_b32 m0, s37
	s_nop 0
	global_load_lds_dwordx4 v164, s[30:31]
	s_waitcnt vmcnt(8)
	s_waitcnt lgkmcnt(0)
	s_setprio 1
	s_barrier
	v_mfma_f32_16x16x128_f8f6f4 v[158:161], v[2:9], v[186:193], v[158:161]
	v_mfma_f32_16x16x128_f8f6f4 v[154:157], v[10:17], v[186:193], v[154:157]
	v_mfma_f32_16x16x128_f8f6f4 v[142:145], v[2:9], v[220:227], v[142:145]
	v_mfma_f32_16x16x128_f8f6f4 v[138:141], v[10:17], v[220:227], v[138:141]
	v_mfma_f32_16x16x128_f8f6f4 v[126:129], v[2:9], v[228:235], v[126:129]
	v_mfma_f32_16x16x128_f8f6f4 v[122:125], v[10:17], v[228:235], v[122:125]
	v_mfma_f32_16x16x128_f8f6f4 v[110:113], v[2:9], v[236:243], v[110:113]
	v_mfma_f32_16x16x128_f8f6f4 v[106:109], v[10:17], v[236:243], v[106:109]
	v_mfma_f32_16x16x128_f8f6f4 v[150:153], v[18:25], v[186:193], v[150:153]
	v_mfma_f32_16x16x128_f8f6f4 v[146:149], v[26:33], v[186:193], v[146:149]
	v_mfma_f32_16x16x128_f8f6f4 v[134:137], v[18:25], v[220:227], v[134:137]
	v_mfma_f32_16x16x128_f8f6f4 v[130:133], v[26:33], v[220:227], v[130:133]
	v_mfma_f32_16x16x128_f8f6f4 v[118:121], v[18:25], v[228:235], v[118:121]
	v_mfma_f32_16x16x128_f8f6f4 v[114:117], v[26:33], v[228:235], v[114:117]
	v_mfma_f32_16x16x128_f8f6f4 v[102:105], v[18:25], v[236:243], v[102:105]
	v_mfma_f32_16x16x128_f8f6f4 v[98:101], v[26:33], v[236:243], v[98:101]
	s_barrier
	s_setprio 0
	s_add_u32 s30, s28, 0x380000
	s_addc_u32 s31, s29, 0
	s_add_i32 s49, s49, s0
	s_mov_b32 m0, s49
	ds_read_b128 v[186:189], v184 offset:49152
	ds_read_b128 v[190:193], v184 offset:50176
	ds_read_b128 v[220:223], v184 offset:51200
	ds_read_b128 v[224:227], v184 offset:52224
	ds_read_b128 v[228:231], v184 offset:53248
	ds_read_b128 v[232:235], v184 offset:54272
	ds_read_b128 v[236:239], v184 offset:55296
	ds_read_b128 v[240:243], v184 offset:56320
	global_load_lds_dwordx4 v166, s[30:31]
	s_add_i32 m0, s49, 0x2000
	s_add_u32 s28, s28, 0x384000
	s_addc_u32 s29, s29, 0
	global_load_lds_dwordx4 v162, s[30:31]
	s_add_i32 s30, s50, s0
	s_mov_b32 m0, s30
	s_nop 0
	global_load_lds_dwordx4 v166, s[28:29]
	s_add_i32 m0, s30, 0x2000
	s_nop 0
	global_load_lds_dwordx4 v162, s[28:29]
	s_mov_b32 m0, s40
	s_nop 0
	global_load_lds_dwordx4 v168, s[26:27]
	s_mov_b32 m0, s41
	s_nop 0
	global_load_lds_dwordx4 v164, s[26:27]
	s_waitcnt vmcnt(8)
	s_waitcnt lgkmcnt(0)
	s_setprio 1
	s_barrier
	v_mfma_f32_16x16x128_f8f6f4 v[94:97], v[2:9], v[186:193], v[94:97]
	v_mfma_f32_16x16x128_f8f6f4 v[90:93], v[10:17], v[186:193], v[90:93]
	v_mfma_f32_16x16x128_f8f6f4 v[78:81], v[2:9], v[220:227], v[78:81]
	v_mfma_f32_16x16x128_f8f6f4 v[74:77], v[10:17], v[220:227], v[74:77]
	v_mfma_f32_16x16x128_f8f6f4 v[62:65], v[2:9], v[228:235], v[62:65]
	v_mfma_f32_16x16x128_f8f6f4 v[58:61], v[10:17], v[228:235], v[58:61]
	v_mfma_f32_16x16x128_f8f6f4 v[46:49], v[2:9], v[236:243], v[46:49]
	v_mfma_f32_16x16x128_f8f6f4 v[42:45], v[10:17], v[236:243], v[42:45]
	v_mfma_f32_16x16x128_f8f6f4 v[86:89], v[18:25], v[186:193], v[86:89]
	v_mfma_f32_16x16x128_f8f6f4 v[82:85], v[26:33], v[186:193], v[82:85]
	v_mfma_f32_16x16x128_f8f6f4 v[70:73], v[18:25], v[220:227], v[70:73]
	v_mfma_f32_16x16x128_f8f6f4 v[66:69], v[26:33], v[220:227], v[66:69]
	v_mfma_f32_16x16x128_f8f6f4 v[54:57], v[18:25], v[228:235], v[54:57]
	v_mfma_f32_16x16x128_f8f6f4 v[50:53], v[26:33], v[228:235], v[50:53]
	v_mfma_f32_16x16x128_f8f6f4 v[38:41], v[18:25], v[236:243], v[38:41]
	v_mfma_f32_16x16x128_f8f6f4 v[34:37], v[26:33], v[236:243], v[34:37]
	s_barrier
	s_setprio 0
	s_add_i32 s48, s48, 2
	s_add_u32 s46, s46, 0x700000
	s_addc_u32 s47, s47, 0
	s_add_u32 s24, s24, 0x200000
	s_addc_u32 s25, s25, 0
	s_cmp_gt_u32 s48, 29
	s_cbranch_scc0 .LBB0_2480
	s_and_b64 vcc, exec, s[8:9]
	s_cbranch_vccz .LBB0_2483
	s_barrier

.LBB0_2714:
	ds_read_b128 v[18:21], v180
	ds_read_b128 v[22:25], v180 offset:1024
	ds_read_b128 v[26:29], v180 offset:2048
	ds_read_b128 v[30:33], v180 offset:3072
	s_waitcnt lgkmcnt(0)
	ds_read_b128 v[2:5], v181
	ds_read_b128 v[6:9], v181 offset:1024
	ds_read_b128 v[10:13], v181 offset:2048
	ds_read_b128 v[14:17], v181 offset:3072
	s_add_u32 s24, s22, 0xfc000
	s_addc_u32 s25, s23, 0
	s_cmpk_eq_i32 s44, 0x6c
	s_cselect_b32 s28, s17, s24
	s_cselect_b32 s29, s5, s25
	s_cselect_b32 s26, s41, s42
	s_cselect_b32 s27, s15, s43
	s_add_u32 s24, s28, 0x100000
	s_addc_u32 s25, s29, 0
	s_add_i32 m0, s1, 0xc000
	ds_read_b128 v[184:187], v182
	ds_read_b128 v[188:191], v182 offset:1024
	ds_read_b128 v[192:195], v182 offset:2048
	ds_read_b128 v[196:199], v182 offset:3072
	ds_read_b128 v[220:223], v182 offset:4096
	ds_read_b128 v[224:227], v182 offset:5120
	ds_read_b128 v[228:231], v182 offset:6144
	ds_read_b128 v[232:235], v182 offset:7168
	global_load_lds_dwordx4 v170, s[22:23]
	s_add_i32 m0, s1, 0xe000
	s_nop 0
	global_load_lds_dwordx4 v172, s[22:23]
	s_waitcnt vmcnt(8)
	s_waitcnt lgkmcnt(0)
	s_setprio 1
	s_barrier
	v_mfma_f32_16x16x128_f8f6f4 v[158:161], v[18:25], v[184:191], v[158:161]
	v_mfma_f32_16x16x128_f8f6f4 v[154:157], v[26:33], v[184:191], v[154:157]
	v_mfma_f32_16x16x128_f8f6f4 v[142:145], v[18:25], v[192:199], v[142:145]
	v_mfma_f32_16x16x128_f8f6f4 v[138:141], v[26:33], v[192:199], v[138:141]
	v_mfma_f32_16x16x128_f8f6f4 v[126:129], v[18:25], v[220:227], v[126:129]
	v_mfma_f32_16x16x128_f8f6f4 v[122:125], v[26:33], v[220:227], v[122:125]
	v_mfma_f32_16x16x128_f8f6f4 v[110:113], v[18:25], v[228:235], v[110:113]
	v_mfma_f32_16x16x128_f8f6f4 v[106:109], v[26:33], v[228:235], v[106:109]
	v_mfma_f32_16x16x128_f8f6f4 v[150:153], v[2:9], v[184:191], v[150:153]
	v_mfma_f32_16x16x128_f8f6f4 v[146:149], v[10:17], v[184:191], v[146:149]
	v_mfma_f32_16x16x128_f8f6f4 v[134:137], v[2:9], v[192:199], v[134:137]
	v_mfma_f32_16x16x128_f8f6f4 v[130:133], v[10:17], v[192:199], v[130:133]
	v_mfma_f32_16x16x128_f8f6f4 v[118:121], v[2:9], v[220:227], v[118:121]
	v_mfma_f32_16x16x128_f8f6f4 v[114:117], v[10:17], v[220:227], v[114:117]
	v_mfma_f32_16x16x128_f8f6f4 v[102:105], v[2:9], v[228:235], v[102:105]
	v_mfma_f32_16x16x128_f8f6f4 v[98:101], v[10:17], v[228:235], v[98:101]
	s_barrier
	s_setprio 0
	s_add_i32 s45, s38, s0
	s_mov_b32 m0, s45
	ds_read_b128 v[184:187], v182 offset:16384
	ds_read_b128 v[188:191], v182 offset:17408
	ds_read_b128 v[192:195], v182 offset:18432
	ds_read_b128 v[196:199], v182 offset:19456
	ds_read_b128 v[220:223], v182 offset:20480
	ds_read_b128 v[224:227], v182 offset:21504
	ds_read_b128 v[228:231], v182 offset:22528
	ds_read_b128 v[232:235], v182 offset:23552
	global_load_lds_dwordx4 v164, s[26:27]
	s_add_i32 m0, s45, 0x2000
	s_add_u32 s46, s26, 0x4000
	s_addc_u32 s47, s27, 0
	s_add_i32 s45, s39, s0
	global_load_lds_dwordx4 v168, s[26:27]
	s_mov_b32 m0, s45
	s_nop 0
	global_load_lds_dwordx4 v164, s[46:47]
	s_add_i32 m0, s45, 0x2000
	s_nop 0
	global_load_lds_dwordx4 v168, s[46:47]
	s_mov_b32 m0, s1
	s_nop 0
	global_load_lds_dwordx4 v162, s[28:29]
	s_mov_b32 m0, s13
	s_nop 0
	global_load_lds_dwordx4 v166, s[28:29]
	s_waitcnt vmcnt(8)
	s_waitcnt lgkmcnt(0)
	s_setprio 1
	s_barrier
	v_mfma_f32_16x16x128_f8f6f4 v[94:97], v[18:25], v[184:191], v[94:97]
	v_mfma_f32_16x16x128_f8f6f4 v[90:93], v[26:33], v[184:191], v[90:93]
	v_mfma_f32_16x16x128_f8f6f4 v[78:81], v[18:25], v[192:199], v[78:81]
	v_mfma_f32_16x16x128_f8f6f4 v[74:77], v[26:33], v[192:199], v[74:77]
	v_mfma_f32_16x16x128_f8f6f4 v[62:65], v[18:25], v[220:227], v[62:65]
	v_mfma_f32_16x16x128_f8f6f4 v[58:61], v[26:33], v[220:227], v[58:61]
	v_mfma_f32_16x16x128_f8f6f4 v[46:49], v[18:25], v[228:235], v[46:49]
	v_mfma_f32_16x16x128_f8f6f4 v[42:45], v[26:33], v[228:235], v[42:45]
	v_mfma_f32_16x16x128_f8f6f4 v[86:89], v[2:9], v[184:191], v[86:89]
	v_mfma_f32_16x16x128_f8f6f4 v[82:85], v[10:17], v[184:191], v[82:85]
	v_mfma_f32_16x16x128_f8f6f4 v[70:73], v[2:9], v[192:199], v[70:73]
	v_mfma_f32_16x16x128_f8f6f4 v[66:69], v[10:17], v[192:199], v[66:69]
	v_mfma_f32_16x16x128_f8f6f4 v[54:57], v[2:9], v[220:227], v[54:57]
	v_mfma_f32_16x16x128_f8f6f4 v[50:53], v[10:17], v[220:227], v[50:53]
	v_mfma_f32_16x16x128_f8f6f4 v[38:41], v[2:9], v[228:235], v[38:41]
	v_mfma_f32_16x16x128_f8f6f4 v[34:37], v[10:17], v[228:235], v[34:37]
	s_barrier
	s_setprio 0
	s_add_i32 s45, 0, 0x18000
	s_add_i32 s46, 0, 0x1c000
	v_add_u32_e32 v14, s45, v179
	v_add_u32_e32 v30, s46, v179
	ds_read_b128 v[2:5], v14
	ds_read_b128 v[6:9], v14 offset:1024
	ds_read_b128 v[10:13], v14 offset:2048
	ds_read_b128 v[14:17], v14 offset:3072
	ds_read_b128 v[18:21], v30
	ds_read_b128 v[22:25], v30 offset:1024
	ds_read_b128 v[26:29], v30 offset:2048
	ds_read_b128 v[30:33], v30 offset:3072
	s_add_u32 s28, s28, 0x4000
	s_addc_u32 s29, s29, 0
	s_mov_b32 m0, s30
	ds_read_b128 v[184:187], v182 offset:32768
	ds_read_b128 v[188:191], v182 offset:33792
	ds_read_b128 v[192:195], v182 offset:34816
	ds_read_b128 v[196:199], v182 offset:35840
	ds_read_b128 v[220:223], v182 offset:36864
	ds_read_b128 v[224:227], v182 offset:37888
	ds_read_b128 v[228:231], v182 offset:38912
	ds_read_b128 v[232:235], v182 offset:39936
	global_load_lds_dwordx4 v162, s[28:29]
	s_mov_b32 m0, s31
	s_nop 0
	global_load_lds_dwordx4 v166, s[28:29]
	s_waitcnt vmcnt(8)
	s_waitcnt lgkmcnt(0)
	s_setprio 1
	s_barrier
	v_mfma_f32_16x16x128_f8f6f4 v[158:161], v[2:9], v[184:191], v[158:161]
	v_mfma_f32_16x16x128_f8f6f4 v[154:157], v[10:17], v[184:191], v[154:157]
	v_mfma_f32_16x16x128_f8f6f4 v[142:145], v[2:9], v[192:199], v[142:145]
	v_mfma_f32_16x16x128_f8f6f4 v[138:141], v[10:17], v[192:199], v[138:141]
	v_mfma_f32_16x16x128_f8f6f4 v[126:129], v[2:9], v[220:227], v[126:129]
	v_mfma_f32_16x16x128_f8f6f4 v[122:125], v[10:17], v[220:227], v[122:125]
	v_mfma_f32_16x16x128_f8f6f4 v[110:113], v[2:9], v[228:235], v[110:113]
	v_mfma_f32_16x16x128_f8f6f4 v[106:109], v[10:17], v[228:235], v[106:109]
	v_mfma_f32_16x16x128_f8f6f4 v[150:153], v[18:25], v[184:191], v[150:153]
	v_mfma_f32_16x16x128_f8f6f4 v[146:149], v[26:33], v[184:191], v[146:149]
	v_mfma_f32_16x16x128_f8f6f4 v[134:137], v[18:25], v[192:199], v[134:137]
	v_mfma_f32_16x16x128_f8f6f4 v[130:133], v[26:33], v[192:199], v[130:133]
	v_mfma_f32_16x16x128_f8f6f4 v[118:121], v[18:25], v[220:227], v[118:121]
	v_mfma_f32_16x16x128_f8f6f4 v[114:117], v[26:33], v[220:227], v[114:117]
	v_mfma_f32_16x16x128_f8f6f4 v[102:105], v[18:25], v[228:235], v[102:105]
	v_mfma_f32_16x16x128_f8f6f4 v[98:101], v[26:33], v[228:235], v[98:101]
	s_barrier
	s_setprio 0
	s_add_u32 s28, s26, 0x80000
	s_addc_u32 s29, s27, 0
	s_add_i32 s45, s45, s0
	s_mov_b32 m0, s45
	ds_read_b128 v[184:187], v182 offset:49152
	ds_read_b128 v[188:191], v182 offset:50176
	ds_read_b128 v[192:195], v182 offset:51200
	ds_read_b128 v[196:199], v182 offset:52224
	ds_read_b128 v[220:223], v182 offset:53248
	ds_read_b128 v[224:227], v182 offset:54272
	ds_read_b128 v[228:231], v182 offset:55296
	ds_read_b128 v[232:235], v182 offset:56320
	global_load_lds_dwordx4 v164, s[28:29]
	s_add_i32 m0, s45, 0x2000
	s_add_u32 s26, s26, 0x84000
	s_addc_u32 s27, s27, 0
	global_load_lds_dwordx4 v168, s[28:29]
	s_add_i32 s28, s46, s0
	s_mov_b32 m0, s28
	s_nop 0
	global_load_lds_dwordx4 v164, s[26:27]
	s_add_i32 m0, s28, 0x2000
	s_nop 0
	global_load_lds_dwordx4 v168, s[26:27]
	s_mov_b32 m0, s36
	s_nop 0
	global_load_lds_dwordx4 v162, s[24:25]
	s_mov_b32 m0, s37
	s_nop 0
	global_load_lds_dwordx4 v166, s[24:25]
	s_waitcnt vmcnt(8)
	s_waitcnt lgkmcnt(0)
	s_setprio 1
	s_barrier
	v_mfma_f32_16x16x128_f8f6f4 v[94:97], v[2:9], v[184:191], v[94:97]
	v_mfma_f32_16x16x128_f8f6f4 v[90:93], v[10:17], v[184:191], v[90:93]
	v_mfma_f32_16x16x128_f8f6f4 v[78:81], v[2:9], v[192:199], v[78:81]
	v_mfma_f32_16x16x128_f8f6f4 v[74:77], v[10:17], v[192:199], v[74:77]
	v_mfma_f32_16x16x128_f8f6f4 v[62:65], v[2:9], v[220:227], v[62:65]
	v_mfma_f32_16x16x128_f8f6f4 v[58:61], v[10:17], v[220:227], v[58:61]
	v_mfma_f32_16x16x128_f8f6f4 v[46:49], v[2:9], v[228:235], v[46:49]
	v_mfma_f32_16x16x128_f8f6f4 v[42:45], v[10:17], v[228:235], v[42:45]
	v_mfma_f32_16x16x128_f8f6f4 v[86:89], v[18:25], v[184:191], v[86:89]
	v_mfma_f32_16x16x128_f8f6f4 v[82:85], v[26:33], v[184:191], v[82:85]
	v_mfma_f32_16x16x128_f8f6f4 v[70:73], v[18:25], v[192:199], v[70:73]
	v_mfma_f32_16x16x128_f8f6f4 v[66:69], v[26:33], v[192:199], v[66:69]
	v_mfma_f32_16x16x128_f8f6f4 v[54:57], v[18:25], v[220:227], v[54:57]
	v_mfma_f32_16x16x128_f8f6f4 v[50:53], v[26:33], v[220:227], v[50:53]
	v_mfma_f32_16x16x128_f8f6f4 v[38:41], v[18:25], v[228:235], v[38:41]
	v_mfma_f32_16x16x128_f8f6f4 v[34:37], v[26:33], v[228:235], v[34:37]
	s_barrier
	s_setprio 0
	s_add_i32 s44, s44, 2
	s_add_u32 s42, s42, 0x100000
	s_addc_u32 s43, s43, 0
	s_add_u32 s22, s22, 0x200000
	s_addc_u32 s23, s23, 0
	s_cmpk_gt_u32 s44, 0x6d
	s_cbranch_scc0 .LBB0_2714
	s_and_b64 vcc, exec, s[10:11]
	s_cbranch_vccz .LBB0_2717
	s_barrier
